# v20 + GEMM loops: load prep moved behind the phase barrier; in-proj pointer increments at the loop head (setprio placement unchanged)
# speedup vs baseline: 1.0008x; 1.0008x over previous
; #define PG8_STAGE(bufoff, gbase, voff) do { _Pragma("unroll") for (int _i = 0; _i < 2; ++_i) \
;         __builtin_amdgcn_global_load_lds((const unsigned*)((const char*)(gbase) + (voff)[_i]), (PG8_LAS unsigned*)(lds + (bufoff) + ldsw + _i * 8192), 16, 0, 0); } while (0)
; #define PG8_LDA(dst, b, h) do { _Pragma("unroll") for (int m = 0; m < 4; ++m) _Pragma("unroll") for (int k = 0; k < 2; ++k) dst[m][k] = *(const PG8_LAS bf16x8*)(lds + PG8_SA(b, h) + aoff + m * 2048 + k * 1024); } while (0)
; #define PG8_LDB(dst, b, h) do { _Pragma("unroll") for (int n = 0; n < 2; ++n) _Pragma("unroll") for (int k = 0; k < 2; ++k) dst[n][k] = *(const PG8_LAS bf16x8*)(lds + PG8_SB(b, h) + boff + n * 2048 + k * 1024); } while (0)
; #define PG8_MMA(ai, bj, At, Bt) do { __builtin_amdgcn_s_setprio(1); _Pragma("unroll") for (int m = 0; m < 4; ++m) _Pragma("unroll") for (int n = 0; n < 2; ++n) _Pragma("unroll") for (int k = 0; k < 2; ++k) \
;         acc[ai][bj][m][n] = __builtin_amdgcn_mfma_f32_16x16x32_bf16(Bt[n][k], At[m][k], acc[ai][bj][m][n], 0, 0, 0); __builtin_amdgcn_s_setprio(0); } while (0)
; #define PG8_WAIT_L(n) asm volatile("s_waitcnt lgkmcnt(" #n ")" ::: "memory")
; #define PG8_BAR __builtin_amdgcn_s_barrier()
; #define PG8_SCHED __builtin_amdgcn_sched_barrier(0)
; template <class Epi, class Sched>
; __device__ __forceinline__ void gemm_phase(PG8_LAS unsigned char* lds, const Gemm g, const Sched& S, const Epi& E) {
;     ...
;             PG8_LDB(B0, 0, 0); PG8_SCHED; PG8_LDA(At, 0, 0); PG8_STAGE(PG8_SA(1, 1), a1 + hstep, voffA);
;             PG8_WAIT_L(8); PG8_BAR; PG8_WAIT_L(0); PG8_MMA(0, 0, At, B0); PG8_BAR; PG8_SCHED;
;             PG8_LDB(B1, 0, 1); PG8_STAGE(PG8_SB(0, 0), b2, voffB);
;             PG8_BAR; PG8_WAIT_L(0); PG8_MMA(0, 1, At, B1); PG8_BAR;
;             PG8_LDA(At, 0, 1); PG8_STAGE(PG8_SA(0, 0), a2, voffA);
;             PG8_BAR; PG8_WAIT_L(0); PG8_MMA(1, 0, At, B0); PG8_BAR; PG8_SCHED;
.LBB0_75:
	s_add_u32 s10, vcc_lo, 0xfffc0080
	s_addc_u32 s11, vcc_hi, -1
	s_add_i32 s89, 0, 0x10000
	v_add_u32_e32 v156, s89, v141
	ds_read_b128 v[144:147], v156
	ds_read_b128 v[148:151], v156 offset:1024
	ds_read_b128 v[152:155], v156 offset:2048
	ds_read_b128 v[156:159], v156 offset:3072
	s_cmp_eq_u32 s88, 12
	s_cselect_b32 s41, s39, s11
	s_cselect_b32 s40, s84, s10
	s_cselect_b32 s11, s37, s87
	s_cselect_b32 s10, s85, s86
	v_lshl_add_u64 v[202:203], vcc, 0, v[136:137]
	s_add_i32 m0, s21, 0xc000
	ds_read_b128 v[160:163], v143
	ds_read_b128 v[174:177], v143 offset:1024
	ds_read_b128 v[178:181], v143 offset:2048
	ds_read_b128 v[182:185], v143 offset:3072
	ds_read_b128 v[186:189], v143 offset:4096
	ds_read_b128 v[190:193], v143 offset:5120
	ds_read_b128 v[194:197], v143 offset:6144
	ds_read_b128 v[198:201], v143 offset:7168
	global_load_lds_dwordx4 v[202:203], off
	v_lshl_add_u64 v[202:203], vcc, 0, v[138:139]
	s_add_i32 m0, s21, 0xe000
	s_nop 0
	global_load_lds_dwordx4 v[202:203], off
	s_waitcnt lgkmcnt(8)
	s_barrier
	s_waitcnt lgkmcnt(0)
	s_setprio 1
	v_mfma_f32_16x16x32_bf16 v[126:129], v[144:147], v[160:163], v[126:129]
	v_mfma_f32_16x16x32_bf16 v[122:125], v[152:155], v[160:163], v[122:125]
	v_mfma_f32_16x16x32_bf16 v[118:121], v[144:147], v[178:181], v[118:121]
	v_mfma_f32_16x16x32_bf16 v[114:117], v[152:155], v[178:181], v[114:117]
	v_mfma_f32_16x16x32_bf16 v[102:105], v[144:147], v[186:189], v[102:105]
	v_mfma_f32_16x16x32_bf16 v[98:101], v[152:155], v[186:189], v[98:101]
	v_mfma_f32_16x16x32_bf16 v[86:89], v[144:147], v[194:197], v[86:89]
	v_mfma_f32_16x16x32_bf16 v[82:85], v[152:155], v[194:197], v[82:85]
	v_mfma_f32_16x16x32_bf16 v[126:129], v[148:151], v[174:177], v[126:129]
	v_mfma_f32_16x16x32_bf16 v[122:125], v[156:159], v[174:177], v[122:125]
	v_mfma_f32_16x16x32_bf16 v[118:121], v[148:151], v[182:185], v[118:121]
	v_mfma_f32_16x16x32_bf16 v[114:117], v[156:159], v[182:185], v[114:117]
	v_mfma_f32_16x16x32_bf16 v[102:105], v[148:151], v[190:193], v[102:105]
	v_mfma_f32_16x16x32_bf16 v[98:101], v[156:159], v[190:193], v[98:101]
	v_mfma_f32_16x16x32_bf16 v[86:89], v[148:151], v[198:201], v[86:89]
	v_mfma_f32_16x16x32_bf16 v[82:85], v[156:159], v[198:201], v[82:85]
	s_setprio 0
	s_barrier
	s_add_i32 s92, 0, 0x14000
	s_add_i32 s89, s89, s76
	v_add_u32_e32 v173, s92, v141
	v_lshl_add_u64 v[202:203], s[10:11], 0, v[0:1]
	s_mov_b32 m0, s89
	ds_read_b128 v[216:219], v173
	ds_read_b128 v[220:223], v173 offset:1024
	ds_read_b128 v[224:227], v173 offset:2048
	ds_read_b128 v[228:231], v173 offset:3072
	global_load_lds_dwordx4 v[202:203], off
	v_lshl_add_u64 v[232:233], s[10:11], 0, v[134:135]
	s_add_i32 m0, s89, 0x2000
	s_nop 0
	global_load_lds_dwordx4 v[232:233], off
	s_barrier
	s_waitcnt lgkmcnt(0)
	s_setprio 1
	v_mfma_f32_16x16x32_bf16 v[110:113], v[216:219], v[160:163], v[110:113]
	v_mfma_f32_16x16x32_bf16 v[106:109], v[224:227], v[160:163], v[106:109]
	v_mfma_f32_16x16x32_bf16 v[94:97], v[216:219], v[178:181], v[94:97]
	v_mfma_f32_16x16x32_bf16 v[90:93], v[224:227], v[178:181], v[90:93]
	v_mfma_f32_16x16x32_bf16 v[78:81], v[216:219], v[186:189], v[78:81]
	v_mfma_f32_16x16x32_bf16 v[74:77], v[224:227], v[186:189], v[74:77]
	v_mfma_f32_16x16x32_bf16 v[70:73], v[216:219], v[194:197], v[70:73]
	v_mfma_f32_16x16x32_bf16 v[66:69], v[224:227], v[194:197], v[66:69]
	v_mfma_f32_16x16x32_bf16 v[110:113], v[220:223], v[174:177], v[110:113]
	v_mfma_f32_16x16x32_bf16 v[106:109], v[228:231], v[174:177], v[106:109]
	v_mfma_f32_16x16x32_bf16 v[94:97], v[220:223], v[182:185], v[94:97]
	v_mfma_f32_16x16x32_bf16 v[90:93], v[228:231], v[182:185], v[90:93]
	v_mfma_f32_16x16x32_bf16 v[78:81], v[220:223], v[190:193], v[78:81]
	v_mfma_f32_16x16x32_bf16 v[74:77], v[228:231], v[190:193], v[74:77]
	v_mfma_f32_16x16x32_bf16 v[70:73], v[220:223], v[198:201], v[70:73]
	v_mfma_f32_16x16x32_bf16 v[66:69], v[228:231], v[198:201], v[66:69]
	s_setprio 0
	s_barrier
	s_mov_b32 m0, s21
	v_lshl_add_u64 v[234:235], s[40:41], 0, v[130:131]
	ds_read_b128 v[160:163], v143 offset:16384
	ds_read_b128 v[174:177], v143 offset:17408
	ds_read_b128 v[178:181], v143 offset:18432
	ds_read_b128 v[182:185], v143 offset:19456
	ds_read_b128 v[186:189], v143 offset:20480
	ds_read_b128 v[190:193], v143 offset:21504
	ds_read_b128 v[194:197], v143 offset:22528
	ds_read_b128 v[198:201], v143 offset:23552
	global_load_lds_dwordx4 v[234:235], off
	v_lshl_add_u64 v[236:237], s[40:41], 0, v[132:133]
	s_mov_b32 m0, s77
	s_nop 0
	global_load_lds_dwordx4 v[236:237], off
	s_barrier
	s_waitcnt lgkmcnt(0)
	s_setprio 1
	v_mfma_f32_16x16x32_bf16 v[62:65], v[144:147], v[160:163], v[62:65]
	v_mfma_f32_16x16x32_bf16 v[58:61], v[152:155], v[160:163], v[58:61]
	v_mfma_f32_16x16x32_bf16 v[54:57], v[144:147], v[178:181], v[54:57]
	v_mfma_f32_16x16x32_bf16 v[50:53], v[152:155], v[178:181], v[50:53]
	v_mfma_f32_16x16x32_bf16 v[38:41], v[144:147], v[186:189], v[38:41]
	v_mfma_f32_16x16x32_bf16 v[34:37], v[152:155], v[186:189], v[34:37]
	v_mfma_f32_16x16x32_bf16 v[22:25], v[144:147], v[194:197], v[22:25]
	v_mfma_f32_16x16x32_bf16 v[18:21], v[152:155], v[194:197], v[18:21]
	v_mfma_f32_16x16x32_bf16 v[62:65], v[148:151], v[174:177], v[62:65]
	v_mfma_f32_16x16x32_bf16 v[58:61], v[156:159], v[174:177], v[58:61]
	v_mfma_f32_16x16x32_bf16 v[54:57], v[148:151], v[182:185], v[54:57]
	v_mfma_f32_16x16x32_bf16 v[50:53], v[156:159], v[182:185], v[50:53]
	v_mfma_f32_16x16x32_bf16 v[38:41], v[148:151], v[190:193], v[38:41]
	v_mfma_f32_16x16x32_bf16 v[34:37], v[156:159], v[190:193], v[34:37]
	v_mfma_f32_16x16x32_bf16 v[22:25], v[148:151], v[198:201], v[22:25]
	v_mfma_f32_16x16x32_bf16 v[18:21], v[156:159], v[198:201], v[18:21]
	s_setprio 0
	s_barrier
; #define PG8_STAGE(bufoff, gbase, voff) do { _Pragma("unroll") for (int _i = 0; _i < 2; ++_i) \
;         __builtin_amdgcn_global_load_lds((const unsigned*)((const char*)(gbase) + (voff)[_i]), (PG8_LAS unsigned*)(lds + (bufoff) + ldsw + _i * 8192), 16, 0, 0); } while (0)
; #define PG8_LDA(dst, b, h) do { _Pragma("unroll") for (int m = 0; m < 4; ++m) _Pragma("unroll") for (int k = 0; k < 2; ++k) dst[m][k] = *(const PG8_LAS bf16x8*)(lds + PG8_SA(b, h) + aoff + m * 2048 + k * 1024); } while (0)
; #define PG8_LDB(dst, b, h) do { _Pragma("unroll") for (int n = 0; n < 2; ++n) _Pragma("unroll") for (int k = 0; k < 2; ++k) dst[n][k] = *(const PG8_LAS bf16x8*)(lds + PG8_SB(b, h) + boff + n * 2048 + k * 1024); } while (0)
; #define PG8_MMA(ai, bj, At, Bt) do { __builtin_amdgcn_s_setprio(1); _Pragma("unroll") for (int m = 0; m < 4; ++m) _Pragma("unroll") for (int n = 0; n < 2; ++n) _Pragma("unroll") for (int k = 0; k < 2; ++k) \
;         acc[ai][bj][m][n] = __builtin_amdgcn_mfma_f32_16x16x32_bf16(Bt[n][k], At[m][k], acc[ai][bj][m][n], 0, 0, 0); __builtin_amdgcn_s_setprio(0); } while (0)
; #define PG8_WAIT_V(n) asm volatile("s_waitcnt vmcnt(" #n ")" ::: "memory")
; #define PG8_WAIT_L(n) asm volatile("s_waitcnt lgkmcnt(" #n ")" ::: "memory")
; #define PG8_BAR __builtin_amdgcn_s_barrier()
; #define PG8_SCHED __builtin_amdgcn_sched_barrier(0)
; template <class Epi, class Sched>
; __device__ __forceinline__ void gemm_phase(PG8_LAS unsigned char* lds, const Gemm g, const Sched& S, const Epi& E) {
;     ...
;             PG8_STAGE(PG8_SB(0, 1), b2 + hstep, voffB);
;             PG8_WAIT_V(6); PG8_BAR; PG8_MMA(1, 1, At, B1); PG8_BAR;
;             PG8_LDB(B0, 1, 0); PG8_SCHED; PG8_LDA(At, 1, 0); PG8_STAGE(PG8_SA(0, 1), a2 + hstep, voffA);
;             PG8_WAIT_L(8); PG8_BAR; PG8_WAIT_L(0); PG8_MMA(0, 0, At, B0); PG8_BAR; PG8_SCHED;
;             PG8_LDB(B1, 1, 1); PG8_STAGE(PG8_SB(1, 0), b3, voffB);
;             PG8_BAR; PG8_WAIT_L(0); PG8_MMA(0, 1, At, B1); PG8_BAR;
;             PG8_LDA(At, 1, 1); PG8_STAGE(PG8_SA(1, 0), a3, voffA);
	s_add_u32 s90, s10, 0x40000
	s_addc_u32 s91, s11, 0
	s_add_i32 s89, s92, s76
	v_lshl_add_u64 v[144:145], s[90:91], 0, v[0:1]
	s_mov_b32 m0, s89
	s_nop 0
	global_load_lds_dwordx4 v[144:145], off
	v_lshl_add_u64 v[144:145], s[90:91], 0, v[134:135]
	s_add_i32 m0, s89, 0x2000
	s_nop 0
	global_load_lds_dwordx4 v[144:145], off
	s_waitcnt vmcnt(6)
	s_barrier
	s_setprio 1
	v_mfma_f32_16x16x32_bf16 v[46:49], v[216:219], v[160:163], v[46:49]
	v_mfma_f32_16x16x32_bf16 v[42:45], v[224:227], v[160:163], v[42:45]
	v_mfma_f32_16x16x32_bf16 v[30:33], v[216:219], v[178:181], v[30:33]
	v_mfma_f32_16x16x32_bf16 v[26:29], v[224:227], v[178:181], v[26:29]
	v_mfma_f32_16x16x32_bf16 v[14:17], v[216:219], v[186:189], v[14:17]
	v_mfma_f32_16x16x32_bf16 v[10:13], v[224:227], v[186:189], v[10:13]
	v_mfma_f32_16x16x32_bf16 v[6:9], v[216:219], v[194:197], v[6:9]
	v_mfma_f32_16x16x32_bf16 v[2:5], v[224:227], v[194:197], v[2:5]
	v_mfma_f32_16x16x32_bf16 v[46:49], v[220:223], v[174:177], v[46:49]
	v_mfma_f32_16x16x32_bf16 v[42:45], v[228:231], v[174:177], v[42:45]
	v_mfma_f32_16x16x32_bf16 v[30:33], v[220:223], v[182:185], v[30:33]
	v_mfma_f32_16x16x32_bf16 v[26:29], v[228:231], v[182:185], v[26:29]
	v_mfma_f32_16x16x32_bf16 v[14:17], v[220:223], v[190:193], v[14:17]
	v_mfma_f32_16x16x32_bf16 v[10:13], v[228:231], v[190:193], v[10:13]
	v_mfma_f32_16x16x32_bf16 v[6:9], v[220:223], v[198:201], v[6:9]
	v_mfma_f32_16x16x32_bf16 v[2:5], v[228:231], v[198:201], v[2:5]
	s_setprio 0
	s_barrier
	s_add_i32 s89, 0, 0x18000
	v_add_u32_e32 v156, s89, v141
	ds_read_b128 v[144:147], v156
	ds_read_b128 v[148:151], v156 offset:1024
	ds_read_b128 v[152:155], v156 offset:2048
	ds_read_b128 v[156:159], v156 offset:3072
	s_add_u32 s40, s40, 0x40000
	s_addc_u32 s41, s41, 0
	s_mov_b32 m0, s78
	v_lshl_add_u64 v[216:217], s[40:41], 0, v[130:131]
	ds_read_b128 v[160:163], v143 offset:32768
	ds_read_b128 v[174:177], v143 offset:33792
	ds_read_b128 v[178:181], v143 offset:34816
	ds_read_b128 v[182:185], v143 offset:35840
	ds_read_b128 v[186:189], v143 offset:36864
	ds_read_b128 v[190:193], v143 offset:37888
	ds_read_b128 v[194:197], v143 offset:38912
	ds_read_b128 v[198:201], v143 offset:39936
	global_load_lds_dwordx4 v[216:217], off
	v_lshl_add_u64 v[216:217], s[40:41], 0, v[132:133]
	s_mov_b32 m0, s79
	s_nop 0
	global_load_lds_dwordx4 v[216:217], off
	s_waitcnt lgkmcnt(8)
	s_barrier
	s_waitcnt lgkmcnt(0)
	s_setprio 1
	v_mfma_f32_16x16x32_bf16 v[126:129], v[144:147], v[160:163], v[126:129]
	v_mfma_f32_16x16x32_bf16 v[122:125], v[152:155], v[160:163], v[122:125]
	v_mfma_f32_16x16x32_bf16 v[118:121], v[144:147], v[178:181], v[118:121]
	v_mfma_f32_16x16x32_bf16 v[114:117], v[152:155], v[178:181], v[114:117]
	v_mfma_f32_16x16x32_bf16 v[102:105], v[144:147], v[186:189], v[102:105]
	v_mfma_f32_16x16x32_bf16 v[98:101], v[152:155], v[186:189], v[98:101]
	v_mfma_f32_16x16x32_bf16 v[86:89], v[144:147], v[194:197], v[86:89]
	v_mfma_f32_16x16x32_bf16 v[82:85], v[152:155], v[194:197], v[82:85]
	v_mfma_f32_16x16x32_bf16 v[126:129], v[148:151], v[174:177], v[126:129]
	v_mfma_f32_16x16x32_bf16 v[122:125], v[156:159], v[174:177], v[122:125]
	v_mfma_f32_16x16x32_bf16 v[118:121], v[148:151], v[182:185], v[118:121]
	v_mfma_f32_16x16x32_bf16 v[114:117], v[156:159], v[182:185], v[114:117]
	v_mfma_f32_16x16x32_bf16 v[102:105], v[148:151], v[190:193], v[102:105]
	v_mfma_f32_16x16x32_bf16 v[98:101], v[156:159], v[190:193], v[98:101]
	v_mfma_f32_16x16x32_bf16 v[86:89], v[148:151], v[198:201], v[86:89]
	v_mfma_f32_16x16x32_bf16 v[82:85], v[156:159], v[198:201], v[82:85]
	s_setprio 0
	s_barrier
	s_add_i32 s40, 0, 0x1c000
	s_add_i32 s41, s89, s76
	v_add_u32_e32 v173, s40, v141
	v_lshl_add_u64 v[202:203], v[202:203], 0, s[8:9]
	s_mov_b32 m0, s41
	ds_read_b128 v[216:219], v173
	ds_read_b128 v[220:223], v173 offset:1024
	ds_read_b128 v[224:227], v173 offset:2048
	ds_read_b128 v[228:231], v173 offset:3072
	global_load_lds_dwordx4 v[202:203], off
	v_lshl_add_u64 v[202:203], v[232:233], 0, s[8:9]
	s_add_i32 m0, s41, 0x2000
	s_nop 0
	global_load_lds_dwordx4 v[202:203], off
	s_barrier
	s_waitcnt lgkmcnt(0)
	s_setprio 1
	v_mfma_f32_16x16x32_bf16 v[110:113], v[216:219], v[160:163], v[110:113]
	v_mfma_f32_16x16x32_bf16 v[106:109], v[224:227], v[160:163], v[106:109]
	v_mfma_f32_16x16x32_bf16 v[94:97], v[216:219], v[178:181], v[94:97]
	v_mfma_f32_16x16x32_bf16 v[90:93], v[224:227], v[178:181], v[90:93]
	v_mfma_f32_16x16x32_bf16 v[78:81], v[216:219], v[186:189], v[78:81]
	v_mfma_f32_16x16x32_bf16 v[74:77], v[224:227], v[186:189], v[74:77]
	v_mfma_f32_16x16x32_bf16 v[70:73], v[216:219], v[194:197], v[70:73]
	v_mfma_f32_16x16x32_bf16 v[66:69], v[224:227], v[194:197], v[66:69]
	v_mfma_f32_16x16x32_bf16 v[110:113], v[220:223], v[174:177], v[110:113]
	v_mfma_f32_16x16x32_bf16 v[106:109], v[228:231], v[174:177], v[106:109]
	v_mfma_f32_16x16x32_bf16 v[94:97], v[220:223], v[182:185], v[94:97]
	v_mfma_f32_16x16x32_bf16 v[90:93], v[228:231], v[182:185], v[90:93]
	v_mfma_f32_16x16x32_bf16 v[78:81], v[220:223], v[190:193], v[78:81]
	v_mfma_f32_16x16x32_bf16 v[74:77], v[228:231], v[190:193], v[74:77]
	v_mfma_f32_16x16x32_bf16 v[70:73], v[220:223], v[198:201], v[70:73]
	v_mfma_f32_16x16x32_bf16 v[66:69], v[228:231], v[198:201], v[66:69]
	s_setprio 0
	s_barrier
	s_mov_b32 m0, s80
	v_lshl_add_u64 v[202:203], v[234:235], 0, s[8:9]
	ds_read_b128 v[160:163], v143 offset:49152
	ds_read_b128 v[174:177], v143 offset:50176
	ds_read_b128 v[178:181], v143 offset:51200
	ds_read_b128 v[182:185], v143 offset:52224
	ds_read_b128 v[186:189], v143 offset:53248
	ds_read_b128 v[190:193], v143 offset:54272
	ds_read_b128 v[194:197], v143 offset:55296
	ds_read_b128 v[198:201], v143 offset:56320
	global_load_lds_dwordx4 v[202:203], off
	v_lshl_add_u64 v[202:203], v[236:237], 0, s[8:9]
	s_mov_b32 m0, s81
	s_nop 0
	global_load_lds_dwordx4 v[202:203], off
	s_barrier
; #define PG8_STAGE(bufoff, gbase, voff) do { _Pragma("unroll") for (int _i = 0; _i < 2; ++_i) \
;         __builtin_amdgcn_global_load_lds((const unsigned*)((const char*)(gbase) + (voff)[_i]), (PG8_LAS unsigned*)(lds + (bufoff) + ldsw + _i * 8192), 16, 0, 0); } while (0)
; #define PG8_MMA(ai, bj, At, Bt) do { __builtin_amdgcn_s_setprio(1); _Pragma("unroll") for (int m = 0; m < 4; ++m) _Pragma("unroll") for (int n = 0; n < 2; ++n) _Pragma("unroll") for (int k = 0; k < 2; ++k) \
;         acc[ai][bj][m][n] = __builtin_amdgcn_mfma_f32_16x16x32_bf16(Bt[n][k], At[m][k], acc[ai][bj][m][n], 0, 0, 0); __builtin_amdgcn_s_setprio(0); } while (0)
; #define PG8_WAIT_V(n) asm volatile("s_waitcnt vmcnt(" #n ")" ::: "memory")
; #define PG8_WAIT_L(n) asm volatile("s_waitcnt lgkmcnt(" #n ")" ::: "memory")
; #define PG8_BAR __builtin_amdgcn_s_barrier()
; #define PG8_SCHED __builtin_amdgcn_sched_barrier(0)
; template <class Epi, class Sched>
; __device__ __forceinline__ void gemm_phase(PG8_LAS unsigned char* lds, const Gemm g, const Sched& S, const Epi& E) {
;     ...
;             PG8_BAR; PG8_WAIT_L(0); PG8_MMA(1, 0, At, B0); PG8_BAR; PG8_SCHED;
;             PG8_STAGE(PG8_SB(1, 1), b3 + hstep, voffB);
;             PG8_WAIT_V(6); PG8_BAR; PG8_MMA(1, 1, At, B1); PG8_BAR;
	s_waitcnt lgkmcnt(0)
	s_setprio 1
	v_mfma_f32_16x16x32_bf16 v[62:65], v[144:147], v[160:163], v[62:65]
	v_mfma_f32_16x16x32_bf16 v[58:61], v[152:155], v[160:163], v[58:61]
	v_mfma_f32_16x16x32_bf16 v[54:57], v[144:147], v[178:181], v[54:57]
	v_mfma_f32_16x16x32_bf16 v[50:53], v[152:155], v[178:181], v[50:53]
	v_mfma_f32_16x16x32_bf16 v[38:41], v[144:147], v[186:189], v[38:41]
	v_mfma_f32_16x16x32_bf16 v[34:37], v[152:155], v[186:189], v[34:37]
	v_mfma_f32_16x16x32_bf16 v[22:25], v[144:147], v[194:197], v[22:25]
	v_mfma_f32_16x16x32_bf16 v[18:21], v[152:155], v[194:197], v[18:21]
	v_mfma_f32_16x16x32_bf16 v[62:65], v[148:151], v[174:177], v[62:65]
	v_mfma_f32_16x16x32_bf16 v[58:61], v[156:159], v[174:177], v[58:61]
	v_mfma_f32_16x16x32_bf16 v[54:57], v[148:151], v[182:185], v[54:57]
	v_mfma_f32_16x16x32_bf16 v[50:53], v[156:159], v[182:185], v[50:53]
	v_mfma_f32_16x16x32_bf16 v[38:41], v[148:151], v[190:193], v[38:41]
	v_mfma_f32_16x16x32_bf16 v[34:37], v[156:159], v[190:193], v[34:37]
	v_mfma_f32_16x16x32_bf16 v[22:25], v[148:151], v[198:201], v[22:25]
	v_mfma_f32_16x16x32_bf16 v[18:21], v[156:159], v[198:201], v[18:21]
	s_setprio 0
	s_barrier
	s_add_u32 s10, s10, 0x40080
	s_addc_u32 s11, s11, 0
	s_add_i32 s40, s40, s76
	v_lshl_add_u64 v[144:145], s[10:11], 0, v[0:1]
	s_mov_b32 m0, s40
	s_nop 0
	global_load_lds_dwordx4 v[144:145], off
	v_lshl_add_u64 v[144:145], s[10:11], 0, v[134:135]
	s_add_i32 m0, s40, 0x2000
	s_nop 0
	global_load_lds_dwordx4 v[144:145], off
	s_waitcnt vmcnt(6)
	s_barrier
	s_setprio 1
	v_mfma_f32_16x16x32_bf16 v[46:49], v[216:219], v[160:163], v[46:49]
	v_mfma_f32_16x16x32_bf16 v[42:45], v[224:227], v[160:163], v[42:45]
	v_mfma_f32_16x16x32_bf16 v[30:33], v[216:219], v[178:181], v[30:33]
	v_mfma_f32_16x16x32_bf16 v[26:29], v[224:227], v[178:181], v[26:29]
	v_mfma_f32_16x16x32_bf16 v[14:17], v[216:219], v[186:189], v[14:17]
	v_mfma_f32_16x16x32_bf16 v[10:13], v[224:227], v[186:189], v[10:13]
	v_mfma_f32_16x16x32_bf16 v[6:9], v[216:219], v[194:197], v[6:9]
	v_mfma_f32_16x16x32_bf16 v[2:5], v[224:227], v[194:197], v[2:5]
	v_mfma_f32_16x16x32_bf16 v[46:49], v[220:223], v[174:177], v[46:49]
	v_mfma_f32_16x16x32_bf16 v[42:45], v[228:231], v[174:177], v[42:45]
	v_mfma_f32_16x16x32_bf16 v[30:33], v[220:223], v[182:185], v[30:33]
	v_mfma_f32_16x16x32_bf16 v[26:29], v[228:231], v[182:185], v[26:29]
	v_mfma_f32_16x16x32_bf16 v[14:17], v[220:223], v[190:193], v[14:17]
	v_mfma_f32_16x16x32_bf16 v[10:13], v[228:231], v[190:193], v[10:13]
	v_mfma_f32_16x16x32_bf16 v[6:9], v[220:223], v[198:201], v[6:9]
	v_mfma_f32_16x16x32_bf16 v[2:5], v[228:231], v[198:201], v[2:5]
	s_setprio 0
	s_add_i32 s88, s88, 2
	s_add_u32 vcc_lo, vcc_lo, 0x100
	s_addc_u32 vcc_hi, vcc_hi, 0
	s_add_u32 s86, s86, 0x100
	s_addc_u32 s87, s87, 0
	s_cmp_gt_u32 s88, 13
	s_barrier
	s_cbranch_scc0 .LBB0_75
; #define PG8_WAIT_V(n) asm volatile("s_waitcnt vmcnt(" #n ")" ::: "memory")
; #define PG8_BAR __builtin_amdgcn_s_barrier()
; __device__ __forceinline__ unsigned pk2(float lo, float hi) { v2f v = {lo, hi}; return __builtin_bit_cast(unsigned, __builtin_convertvector(v, v2bf)); }
; template <class Epi, class Sched>
; __device__ __forceinline__ void gemm_phase(PG8_LAS unsigned char* lds, const Gemm g, const Sched& S, const Epi& E) {
;     ...
;     PG8_WAIT_V(0);
;     if (wr == 0) PG8_BAR;
;     PG8_BAR;
;     __device__ __forceinline__ void operator()(const f32x4 (&acc)[2][2][4][2], const Unit& u, int wr, int wc, int fr, int fq) const {
;         const int row0 = u.pm * 256 + wr * 64 + fr; int col0 = u.pn * 256 + wc * 32 + 8 * fq; int ld = ldz; bf16* base = Z;
;         if (SEG) { int c0, w; seg_of(u.pn * 256, c0, w); base = Z + (size_t)T * c0; ld = w; col0 -= c0; }
; #pragma unroll
;         for (int ai = 0; ai < 2; ++ai)
; #pragma unroll
;             for (int m = 0; m < 4; ++m) { bf16* rowp = base + (size_t)(row0 + ai * 128 + m * 16) * ld + col0;
; #pragma unroll
;                 for (int bj = 0; bj < 2; ++bj) { const f32x4 v0 = acc[ai][bj][m][0], v1 = acc[ai][bj][m][1];
;                     v4u w; w.x = pk2(v0[0], v0[1]); w.y = pk2(v0[2], v0[3]); w.z = pk2(v1[0], v1[1]); w.w = pk2(v1[2], v1[3]);
;                     *(v4u*)(rowp + bj * 128) = w; } }
;     }
	v_lshl_add_u32 v144, s20, 8, v140
	v_lshl_or_b32 v146, s83, 8, v142
	v_ashrrev_i32_e32 v147, 31, v146
	v_ashrrev_i32_e32 v145, 31, v144
	v_lshl_add_u64 v[146:147], v[146:147], 1, s[6:7]
	v_lshlrev_b64 v[148:149], 11, v[144:145]
	v_lshl_add_u64 v[148:149], v[146:147], 0, v[148:149]
	s_mov_b64 s[10:11], 0x40000
	v_cvt_pk_bf16_f32 v70, v70, v71
	v_cvt_pk_bf16_f32 v71, v72, v73
	v_cvt_pk_bf16_f32 v72, v66, v67
	v_lshl_add_u64 v[66:67], v[148:149], 0, s[10:11]
	v_cvt_pk_bf16_f32 v62, v62, v63
	v_cvt_pk_bf16_f32 v63, v64, v65
	v_cvt_pk_bf16_f32 v64, v58, v59
	v_add_co_u32_e32 v58, vcc, s67, v148
	v_cvt_pk_bf16_f32 v46, v46, v47
	v_cvt_pk_bf16_f32 v47, v48, v49
	v_cvt_pk_bf16_f32 v48, v42, v43
	v_cvt_pk_bf16_f32 v49, v44, v45
	s_mov_b64 s[10:11], 0x48000
	v_addc_co_u32_e32 v59, vcc, 0, v149, vcc
	global_store_dwordx4 v[66:67], v[46:49], off offset:256
	v_cvt_pk_bf16_f32 v30, v30, v31
	v_cvt_pk_bf16_f32 v31, v32, v33
	v_lshl_add_u64 v[46:47], v[148:149], 0, s[10:11]
	s_mov_b32 s10, 0x48000
	v_add_co_u32_e32 v48, vcc, s10, v148
	v_cvt_pk_bf16_f32 v32, v26, v27
	v_cvt_pk_bf16_f32 v33, v28, v29
	s_mov_b64 s[10:11], 0x50000
	v_cvt_pk_bf16_f32 v110, v110, v111
	v_cvt_pk_bf16_f32 v111, v112, v113
	v_cvt_pk_bf16_f32 v112, v106, v107
	v_or_b32_e32 v106, 16, v144
	v_addc_co_u32_e32 v49, vcc, 0, v149, vcc
	global_store_dwordx4 v[46:47], v[30:33], off offset:256
	v_ashrrev_i32_e32 v107, 31, v106
	v_cvt_pk_bf16_f32 v94, v94, v95
	v_lshl_add_u64 v[30:31], v[148:149], 0, s[10:11]
	s_mov_b32 s10, 0x50000
	v_cvt_pk_bf16_f32 v95, v96, v97
	v_cvt_pk_bf16_f32 v96, v90, v91
	v_or_b32_e32 v90, 32, v144
	v_add_co_u32_e32 v32, vcc, s10, v148
	v_cvt_pk_bf16_f32 v14, v14, v15
	v_cvt_pk_bf16_f32 v15, v16, v17
	v_cvt_pk_bf16_f32 v16, v10, v11
	v_cvt_pk_bf16_f32 v17, v12, v13
	s_mov_b64 s[10:11], 0x58000
	v_cvt_pk_bf16_f32 v113, v108, v109
	v_lshlrev_b64 v[106:107], 11, v[106:107]
	v_ashrrev_i32_e32 v91, 31, v90
	v_cvt_pk_bf16_f32 v78, v78, v79
	v_cvt_pk_bf16_f32 v79, v80, v81
	v_cvt_pk_bf16_f32 v80, v74, v75
	v_or_b32_e32 v74, 48, v144
	v_addc_co_u32_e32 v33, vcc, 0, v149, vcc
	global_store_dwordx4 v[30:31], v[14:17], off offset:256
	global_store_dwordx4 v[148:149], v[110:113], off offset:256
	v_cvt_pk_bf16_f32 v97, v92, v93
	v_lshl_add_u64 v[14:15], v[148:149], 0, s[10:11]
	s_mov_b32 s10, 0x58000
	v_lshl_add_u64 v[110:111], v[146:147], 0, v[106:107]
	v_lshlrev_b64 v[90:91], 11, v[90:91]
	v_ashrrev_i32_e32 v75, 31, v74
	v_add_co_u32_e32 v16, vcc, s10, v148
	global_store_dwordx4 v[110:111], v[94:97], off offset:256
	v_cvt_pk_bf16_f32 v81, v76, v77
	v_lshlrev_b64 v[74:75], 11, v[74:75]
	v_lshl_add_u64 v[94:95], v[146:147], 0, v[90:91]
	v_addc_co_u32_e32 v17, vcc, 0, v149, vcc
	v_cvt_pk_bf16_f32 v126, v126, v127
	v_cvt_pk_bf16_f32 v127, v128, v129
	v_cvt_pk_bf16_f32 v128, v122, v123
	v_cvt_pk_bf16_f32 v129, v124, v125
	v_cvt_pk_bf16_f32 v106, v118, v119
	v_cvt_pk_bf16_f32 v107, v120, v121
	v_cvt_pk_bf16_f32 v108, v114, v115
	v_cvt_pk_bf16_f32 v109, v116, v117
	v_cvt_pk_bf16_f32 v90, v102, v103
	v_cvt_pk_bf16_f32 v91, v104, v105
	v_cvt_pk_bf16_f32 v92, v98, v99
	v_cvt_pk_bf16_f32 v93, v100, v101
	global_store_dwordx4 v[94:95], v[78:81], off offset:256
	v_cvt_pk_bf16_f32 v76, v82, v83
	v_cvt_pk_bf16_f32 v77, v84, v85
	v_lshl_add_u64 v[78:79], v[146:147], 0, v[74:75]
	v_cvt_pk_bf16_f32 v74, v86, v87
	v_cvt_pk_bf16_f32 v75, v88, v89
	v_cvt_pk_bf16_f32 v73, v68, v69
	v_cvt_pk_bf16_f32 v65, v60, v61
	v_cvt_pk_bf16_f32 v42, v54, v55
	v_cvt_pk_bf16_f32 v43, v56, v57
	v_cvt_pk_bf16_f32 v44, v50, v51
	v_cvt_pk_bf16_f32 v45, v52, v53
	v_cvt_pk_bf16_f32 v26, v38, v39
	v_cvt_pk_bf16_f32 v27, v40, v41
	v_cvt_pk_bf16_f32 v28, v34, v35
	v_cvt_pk_bf16_f32 v29, v36, v37
	v_cvt_pk_bf16_f32 v10, v22, v23
	v_cvt_pk_bf16_f32 v11, v24, v25
	v_cvt_pk_bf16_f32 v12, v18, v19
	v_cvt_pk_bf16_f32 v13, v20, v21
	v_cvt_pk_bf16_f32 v6, v6, v7
	v_cvt_pk_bf16_f32 v7, v8, v9
	v_cvt_pk_bf16_f32 v8, v2, v3
	v_cvt_pk_bf16_f32 v9, v4, v5
	s_and_b64 vcc, exec, s[18:19]
	s_mov_b32 s83, s36
	s_mov_b32 s20, s38
	s_mov_b64 s[10:11], s[50:51]
	s_mov_b64 s[40:41], s[52:53]
	global_store_dwordx4 v[148:149], v[126:129], off
	global_store_dwordx4 v[110:111], v[106:109], off
	global_store_dwordx4 v[94:95], v[90:93], off
	global_store_dwordx4 v[78:79], v[74:77], off
	global_store_dwordx4 v[78:79], v[70:73], off offset:256
	global_store_dwordx4 v[58:59], v[62:65], off
	global_store_dwordx4 v[48:49], v[42:45], off
	global_store_dwordx4 v[32:33], v[26:29], off
	global_store_dwordx4 v[16:17], v[10:13], off
	global_store_dwordx4 v[14:15], v[6:9], off offset:256
	s_cbranch_vccz .LBB0_68
	s_waitcnt vmcnt(0)
	s_cmpk_gt_u32 s70, 0xff
	s_cbranch_scc1 .LBB0_58
	s_barrier
	s_branch .LBB0_58

; #define PG8_STAGE(bufoff, gbase, voff) do { _Pragma("unroll") for (int _i = 0; _i < 2; ++_i) \
;         __builtin_amdgcn_global_load_lds((const unsigned*)((const char*)(gbase) + (voff)[_i]), (PG8_LAS unsigned*)(lds + (bufoff) + ldsw + _i * 8192), 16, 0, 0); } while (0)
; #define PG8_LDA(dst, b, h) do { _Pragma("unroll") for (int m = 0; m < 4; ++m) _Pragma("unroll") for (int k = 0; k < 2; ++k) dst[m][k] = *(const PG8_LAS bf16x8*)(lds + PG8_SA(b, h) + aoff + m * 2048 + k * 1024); } while (0)
; #define PG8_LDB(dst, b, h) do { _Pragma("unroll") for (int n = 0; n < 2; ++n) _Pragma("unroll") for (int k = 0; k < 2; ++k) dst[n][k] = *(const PG8_LAS bf16x8*)(lds + PG8_SB(b, h) + boff + n * 2048 + k * 1024); } while (0)
; #define PG8_WAIT_L(n) asm volatile("s_waitcnt lgkmcnt(" #n ")" ::: "memory")
; #define PG8_BAR __builtin_amdgcn_s_barrier()
; #define PG8_SCHED __builtin_amdgcn_sched_barrier(0)
;     __device__ __forceinline__ bool next(int i, Unit& u) const { if (!S.next(i >> 2, u)) return false; u.seg = i & 3; return true; }
; template <class Epi, class Sched>
; __device__ __forceinline__ void gemm_phase(PG8_LAS unsigned char* lds, const Gemm g, const Sched& S, const Epi& E) {
;     ...
;         const bool has_next = S.next(ui + 1, nxt);
;         const char* nA = has_next ? (const char*)g.A + (size_t)nxt.pm * tstep + (size_t)nxt.seg * SEGB : cA; const char* nB = has_next ? (const char*)g.Bt + (size_t)nxt.pn * tstep + (size_t)nxt.seg * SEGB : cB;
;         for (int t = 0; t < nt; t += 2) {
;             const bool last = (t == nt - 2);
;             const char* a1 = cA + (size_t)(t + 1) * kstep;
;             const char* a2 = last ? nA : cA + (size_t)(t + 2) * kstep; const char* b2 = last ? nB : cB + (size_t)(t + 2) * kstep;
;             const char* a3 = a2 + kstep; const char* b3 = b2 + kstep;
;             if (last && has_next) S.a_ready(nxt);
;             PG8_LDB(B0, 0, 0); PG8_SCHED; PG8_LDA(At, 0, 0); PG8_STAGE(PG8_SA(1, 1), a1 + hstep, voffA);
;             PG8_WAIT_L(8); PG8_BAR; PG8_WAIT_L(0); PG8_MMA(0, 0, At, B0); PG8_BAR; PG8_SCHED;
;             PG8_LDB(B1, 0, 1); PG8_STAGE(PG8_SB(0, 0), b2, voffB);
;             PG8_BAR; PG8_WAIT_L(0); PG8_MMA(0, 1, At, B1); PG8_BAR;
;             PG8_LDA(At, 0, 1); PG8_STAGE(PG8_SA(0, 0), a2, voffA);
;             PG8_BAR; PG8_WAIT_L(0); PG8_MMA(1, 0, At, B0); PG8_BAR; PG8_SCHED;
.LBB0_87:
	s_ashr_i32 s19, s18, 31
	v_cmp_lt_i64_e32 vcc, s[20:21], v[166:167]
	s_lshl_b64 s[20:21], s[18:19], 19
	s_add_u32 s20, s56, s20
	s_addc_u32 s21, s57, s21
	s_and_b64 s[38:39], vcc, exec
	s_cselect_b32 s19, s21, s41
	s_cselect_b32 s79, s20, s40
	s_ashr_i32 s7, s6, 31
	s_lshl_b64 s[38:39], s[6:7], 19
	s_add_u32 s38, s52, s38
	s_addc_u32 s39, s53, s39
	s_and_b64 s[50:51], vcc, exec
	s_cselect_b32 s7, s39, s11
	s_cselect_b32 s80, s38, s10
	s_add_u32 s40, s40, 0x40080
	s_addc_u32 s41, s41, 0
	s_add_u32 s81, s10, 0x100
	s_addc_u32 s82, s11, 0
	s_mov_b32 s83, -2
	s_add_u32 s10, s40, 0xfffc0080
	s_addc_u32 s11, s41, -1
	s_add_i32 s84, 0, 0x10000
	v_add_u32_e32 v156, s84, v141
	ds_read_b128 v[144:147], v156
	ds_read_b128 v[148:151], v156 offset:1024
	ds_read_b128 v[152:155], v156 offset:2048
	ds_read_b128 v[156:159], v156 offset:3072
	s_cmp_eq_u32 s83, 12
	s_cselect_b32 s51, s19, s11
	s_cselect_b32 s50, s79, s10
	s_cselect_b32 s11, s7, s82
	s_cselect_b32 s10, s80, s81
	v_lshl_add_u64 v[202:203], s[40:41], 0, v[136:137]
	s_add_i32 m0, s71, 0xc000
	ds_read_b128 v[160:163], v143
	ds_read_b128 v[174:177], v143 offset:1024
	ds_read_b128 v[178:181], v143 offset:2048
	ds_read_b128 v[182:185], v143 offset:3072
	ds_read_b128 v[186:189], v143 offset:4096
	ds_read_b128 v[190:193], v143 offset:5120
	ds_read_b128 v[194:197], v143 offset:6144
	ds_read_b128 v[198:201], v143 offset:7168
	global_load_lds_dwordx4 v[202:203], off
	v_lshl_add_u64 v[202:203], s[40:41], 0, v[138:139]
	s_add_i32 m0, s71, 0xe000
	s_nop 0
	global_load_lds_dwordx4 v[202:203], off
	s_waitcnt lgkmcnt(8)
	s_barrier
	s_waitcnt lgkmcnt(0)
	s_setprio 1
	v_mfma_f32_16x16x32_bf16 v[126:129], v[144:147], v[160:163], 0
	v_mfma_f32_16x16x32_bf16 v[122:125], v[152:155], v[160:163], 0
	v_mfma_f32_16x16x32_bf16 v[118:121], v[144:147], v[178:181], 0
	v_mfma_f32_16x16x32_bf16 v[114:117], v[152:155], v[178:181], 0
	v_mfma_f32_16x16x32_bf16 v[102:105], v[144:147], v[186:189], 0
	v_mfma_f32_16x16x32_bf16 v[98:101], v[152:155], v[186:189], 0
	v_mfma_f32_16x16x32_bf16 v[86:89], v[144:147], v[194:197], 0
	v_mfma_f32_16x16x32_bf16 v[82:85], v[152:155], v[194:197], 0
	v_mfma_f32_16x16x32_bf16 v[126:129], v[148:151], v[174:177], v[126:129]
	v_mfma_f32_16x16x32_bf16 v[122:125], v[156:159], v[174:177], v[122:125]
	v_mfma_f32_16x16x32_bf16 v[118:121], v[148:151], v[182:185], v[118:121]
	v_mfma_f32_16x16x32_bf16 v[114:117], v[156:159], v[182:185], v[114:117]
	v_mfma_f32_16x16x32_bf16 v[102:105], v[148:151], v[190:193], v[102:105]
	v_mfma_f32_16x16x32_bf16 v[98:101], v[156:159], v[190:193], v[98:101]
	v_mfma_f32_16x16x32_bf16 v[86:89], v[148:151], v[198:201], v[86:89]
	v_mfma_f32_16x16x32_bf16 v[82:85], v[156:159], v[198:201], v[82:85]
	s_setprio 0
	s_barrier
	s_add_i32 s86, 0, 0x14000
	s_add_i32 s84, s84, s70
	v_add_u32_e32 v173, s86, v141
	v_lshl_add_u64 v[202:203], s[10:11], 0, v[0:1]
	s_mov_b32 m0, s84
	ds_read_b128 v[216:219], v173
	ds_read_b128 v[220:223], v173 offset:1024
	ds_read_b128 v[224:227], v173 offset:2048
	ds_read_b128 v[228:231], v173 offset:3072
	global_load_lds_dwordx4 v[202:203], off
	v_lshl_add_u64 v[232:233], s[10:11], 0, v[130:131]
	s_add_i32 m0, s84, 0x2000
	s_nop 0
	global_load_lds_dwordx4 v[232:233], off
	s_barrier
	s_waitcnt lgkmcnt(0)
	s_setprio 1
	v_mfma_f32_16x16x32_bf16 v[110:113], v[216:219], v[160:163], 0
	v_mfma_f32_16x16x32_bf16 v[106:109], v[224:227], v[160:163], 0
	v_mfma_f32_16x16x32_bf16 v[94:97], v[216:219], v[178:181], 0
	v_mfma_f32_16x16x32_bf16 v[90:93], v[224:227], v[178:181], 0
	v_mfma_f32_16x16x32_bf16 v[78:81], v[216:219], v[186:189], 0
	v_mfma_f32_16x16x32_bf16 v[74:77], v[224:227], v[186:189], 0
	v_mfma_f32_16x16x32_bf16 v[70:73], v[216:219], v[194:197], 0
	v_mfma_f32_16x16x32_bf16 v[66:69], v[224:227], v[194:197], 0
	v_mfma_f32_16x16x32_bf16 v[110:113], v[220:223], v[174:177], v[110:113]
	v_mfma_f32_16x16x32_bf16 v[106:109], v[228:231], v[174:177], v[106:109]
	v_mfma_f32_16x16x32_bf16 v[94:97], v[220:223], v[182:185], v[94:97]
	v_mfma_f32_16x16x32_bf16 v[90:93], v[228:231], v[182:185], v[90:93]
	v_mfma_f32_16x16x32_bf16 v[78:81], v[220:223], v[190:193], v[78:81]
	v_mfma_f32_16x16x32_bf16 v[74:77], v[228:231], v[190:193], v[74:77]
	v_mfma_f32_16x16x32_bf16 v[70:73], v[220:223], v[198:201], v[70:73]
	v_mfma_f32_16x16x32_bf16 v[66:69], v[228:231], v[198:201], v[66:69]
	s_setprio 0
	s_barrier
	s_mov_b32 m0, s71
	v_lshl_add_u64 v[234:235], s[50:51], 0, v[134:135]
	ds_read_b128 v[160:163], v143 offset:16384
	ds_read_b128 v[174:177], v143 offset:17408
	ds_read_b128 v[178:181], v143 offset:18432
	ds_read_b128 v[182:185], v143 offset:19456
	ds_read_b128 v[186:189], v143 offset:20480
	ds_read_b128 v[190:193], v143 offset:21504
	ds_read_b128 v[194:197], v143 offset:22528
	ds_read_b128 v[198:201], v143 offset:23552
	global_load_lds_dwordx4 v[234:235], off
	v_lshl_add_u64 v[236:237], s[50:51], 0, v[132:133]
	s_mov_b32 m0, s72
	s_nop 0
	global_load_lds_dwordx4 v[236:237], off
	s_barrier
	s_waitcnt lgkmcnt(0)
	s_setprio 1
	v_mfma_f32_16x16x32_bf16 v[62:65], v[144:147], v[160:163], 0
	v_mfma_f32_16x16x32_bf16 v[58:61], v[152:155], v[160:163], 0
	v_mfma_f32_16x16x32_bf16 v[54:57], v[144:147], v[178:181], 0
	v_mfma_f32_16x16x32_bf16 v[50:53], v[152:155], v[178:181], 0
	v_mfma_f32_16x16x32_bf16 v[38:41], v[144:147], v[186:189], 0
	v_mfma_f32_16x16x32_bf16 v[34:37], v[152:155], v[186:189], 0
	v_mfma_f32_16x16x32_bf16 v[22:25], v[144:147], v[194:197], 0
	v_mfma_f32_16x16x32_bf16 v[18:21], v[152:155], v[194:197], 0
	v_mfma_f32_16x16x32_bf16 v[62:65], v[148:151], v[174:177], v[62:65]
	v_mfma_f32_16x16x32_bf16 v[58:61], v[156:159], v[174:177], v[58:61]
	v_mfma_f32_16x16x32_bf16 v[54:57], v[148:151], v[182:185], v[54:57]
	v_mfma_f32_16x16x32_bf16 v[50:53], v[156:159], v[182:185], v[50:53]
	v_mfma_f32_16x16x32_bf16 v[38:41], v[148:151], v[190:193], v[38:41]
	v_mfma_f32_16x16x32_bf16 v[34:37], v[156:159], v[190:193], v[34:37]
	v_mfma_f32_16x16x32_bf16 v[22:25], v[148:151], v[198:201], v[22:25]
	v_mfma_f32_16x16x32_bf16 v[18:21], v[156:159], v[198:201], v[18:21]
	s_setprio 0
	s_barrier
; #define PG8_STAGE(bufoff, gbase, voff) do { _Pragma("unroll") for (int _i = 0; _i < 2; ++_i) \
;         __builtin_amdgcn_global_load_lds((const unsigned*)((const char*)(gbase) + (voff)[_i]), (PG8_LAS unsigned*)(lds + (bufoff) + ldsw + _i * 8192), 16, 0, 0); } while (0)
; #define PG8_LDA(dst, b, h) do { _Pragma("unroll") for (int m = 0; m < 4; ++m) _Pragma("unroll") for (int k = 0; k < 2; ++k) dst[m][k] = *(const PG8_LAS bf16x8*)(lds + PG8_SA(b, h) + aoff + m * 2048 + k * 1024); } while (0)
; #define PG8_LDB(dst, b, h) do { _Pragma("unroll") for (int n = 0; n < 2; ++n) _Pragma("unroll") for (int k = 0; k < 2; ++k) dst[n][k] = *(const PG8_LAS bf16x8*)(lds + PG8_SB(b, h) + boff + n * 2048 + k * 1024); } while (0)
; #define PG8_MMA(ai, bj, At, Bt) do { __builtin_amdgcn_s_setprio(1); _Pragma("unroll") for (int m = 0; m < 4; ++m) _Pragma("unroll") for (int n = 0; n < 2; ++n) _Pragma("unroll") for (int k = 0; k < 2; ++k) \
;         acc[ai][bj][m][n] = __builtin_amdgcn_mfma_f32_16x16x32_bf16(Bt[n][k], At[m][k], acc[ai][bj][m][n], 0, 0, 0); __builtin_amdgcn_s_setprio(0); } while (0)
; #define PG8_WAIT_V(n) asm volatile("s_waitcnt vmcnt(" #n ")" ::: "memory")
; #define PG8_WAIT_L(n) asm volatile("s_waitcnt lgkmcnt(" #n ")" ::: "memory")
; #define PG8_BAR __builtin_amdgcn_s_barrier()
; #define PG8_SCHED __builtin_amdgcn_sched_barrier(0)
; template <class Epi, class Sched>
; __device__ __forceinline__ void gemm_phase(PG8_LAS unsigned char* lds, const Gemm g, const Sched& S, const Epi& E) {
;     ...
;             PG8_STAGE(PG8_SB(0, 1), b2 + hstep, voffB);
;             PG8_WAIT_V(6); PG8_BAR; PG8_MMA(1, 1, At, B1); PG8_BAR;
;             PG8_LDB(B0, 1, 0); PG8_SCHED; PG8_LDA(At, 1, 0); PG8_STAGE(PG8_SA(0, 1), a2 + hstep, voffA);
;             PG8_WAIT_L(8); PG8_BAR; PG8_WAIT_L(0); PG8_MMA(0, 0, At, B0); PG8_BAR; PG8_SCHED;
;             PG8_LDB(B1, 1, 1); PG8_STAGE(PG8_SB(1, 0), b3, voffB);
;             PG8_BAR; PG8_WAIT_L(0); PG8_MMA(0, 1, At, B1); PG8_BAR;
;             PG8_LDA(At, 1, 1); PG8_STAGE(PG8_SA(1, 0), a3, voffA);
;             PG8_BAR; PG8_WAIT_L(0); PG8_MMA(1, 0, At, B0); PG8_BAR; PG8_SCHED;
	s_add_u32 s84, s10, 0x40000
	s_addc_u32 s85, s11, 0
	s_add_i32 s86, s86, s70
	v_lshl_add_u64 v[144:145], s[84:85], 0, v[0:1]
	s_mov_b32 m0, s86
	s_nop 0
	global_load_lds_dwordx4 v[144:145], off
	v_lshl_add_u64 v[144:145], s[84:85], 0, v[130:131]
	s_add_i32 m0, s86, 0x2000
	s_nop 0
	global_load_lds_dwordx4 v[144:145], off
	s_waitcnt vmcnt(6)
	s_barrier
	s_setprio 1
	v_mfma_f32_16x16x32_bf16 v[46:49], v[216:219], v[160:163], 0
	v_mfma_f32_16x16x32_bf16 v[42:45], v[224:227], v[160:163], 0
	v_mfma_f32_16x16x32_bf16 v[30:33], v[216:219], v[178:181], 0
	v_mfma_f32_16x16x32_bf16 v[26:29], v[224:227], v[178:181], 0
	v_mfma_f32_16x16x32_bf16 v[14:17], v[216:219], v[186:189], 0
	v_mfma_f32_16x16x32_bf16 v[10:13], v[224:227], v[186:189], 0
	v_mfma_f32_16x16x32_bf16 v[6:9], v[216:219], v[194:197], 0
	v_mfma_f32_16x16x32_bf16 v[2:5], v[224:227], v[194:197], 0
	v_mfma_f32_16x16x32_bf16 v[46:49], v[220:223], v[174:177], v[46:49]
	v_mfma_f32_16x16x32_bf16 v[42:45], v[228:231], v[174:177], v[42:45]
	v_mfma_f32_16x16x32_bf16 v[30:33], v[220:223], v[182:185], v[30:33]
	v_mfma_f32_16x16x32_bf16 v[26:29], v[228:231], v[182:185], v[26:29]
	v_mfma_f32_16x16x32_bf16 v[14:17], v[220:223], v[190:193], v[14:17]
	v_mfma_f32_16x16x32_bf16 v[10:13], v[228:231], v[190:193], v[10:13]
	v_mfma_f32_16x16x32_bf16 v[6:9], v[220:223], v[198:201], v[6:9]
	v_mfma_f32_16x16x32_bf16 v[2:5], v[228:231], v[198:201], v[2:5]
	s_setprio 0
	s_barrier
	s_add_i32 s84, 0, 0x18000
	v_add_u32_e32 v156, s84, v141
	ds_read_b128 v[144:147], v156
	ds_read_b128 v[148:151], v156 offset:1024
	ds_read_b128 v[152:155], v156 offset:2048
	ds_read_b128 v[156:159], v156 offset:3072
	s_add_u32 s50, s50, 0x40000
	s_addc_u32 s51, s51, 0
	s_mov_b32 m0, s73
	v_lshl_add_u64 v[216:217], s[50:51], 0, v[134:135]
	ds_read_b128 v[160:163], v143 offset:32768
	ds_read_b128 v[174:177], v143 offset:33792
	ds_read_b128 v[178:181], v143 offset:34816
	ds_read_b128 v[182:185], v143 offset:35840
	ds_read_b128 v[186:189], v143 offset:36864
	ds_read_b128 v[190:193], v143 offset:37888
	ds_read_b128 v[194:197], v143 offset:38912
	ds_read_b128 v[198:201], v143 offset:39936
	global_load_lds_dwordx4 v[216:217], off
	v_lshl_add_u64 v[216:217], s[50:51], 0, v[132:133]
	s_mov_b32 m0, s74
	s_nop 0
	global_load_lds_dwordx4 v[216:217], off
	s_waitcnt lgkmcnt(8)
	s_barrier
	s_waitcnt lgkmcnt(0)
	s_setprio 1
	v_mfma_f32_16x16x32_bf16 v[126:129], v[144:147], v[160:163], v[126:129]
	v_mfma_f32_16x16x32_bf16 v[122:125], v[152:155], v[160:163], v[122:125]
	v_mfma_f32_16x16x32_bf16 v[118:121], v[144:147], v[178:181], v[118:121]
	v_mfma_f32_16x16x32_bf16 v[114:117], v[152:155], v[178:181], v[114:117]
	v_mfma_f32_16x16x32_bf16 v[102:105], v[144:147], v[186:189], v[102:105]
	v_mfma_f32_16x16x32_bf16 v[98:101], v[152:155], v[186:189], v[98:101]
	v_mfma_f32_16x16x32_bf16 v[86:89], v[144:147], v[194:197], v[86:89]
	v_mfma_f32_16x16x32_bf16 v[82:85], v[152:155], v[194:197], v[82:85]
	v_mfma_f32_16x16x32_bf16 v[126:129], v[148:151], v[174:177], v[126:129]
	v_mfma_f32_16x16x32_bf16 v[122:125], v[156:159], v[174:177], v[122:125]
	v_mfma_f32_16x16x32_bf16 v[118:121], v[148:151], v[182:185], v[118:121]
	v_mfma_f32_16x16x32_bf16 v[114:117], v[156:159], v[182:185], v[114:117]
	v_mfma_f32_16x16x32_bf16 v[102:105], v[148:151], v[190:193], v[102:105]
	v_mfma_f32_16x16x32_bf16 v[98:101], v[156:159], v[190:193], v[98:101]
	v_mfma_f32_16x16x32_bf16 v[86:89], v[148:151], v[198:201], v[86:89]
	v_mfma_f32_16x16x32_bf16 v[82:85], v[156:159], v[198:201], v[82:85]
	s_setprio 0
	s_barrier
	s_add_i32 s50, 0, 0x1c000
	s_add_i32 s51, s84, s70
	v_add_u32_e32 v173, s50, v141
	v_lshl_add_u64 v[202:203], v[202:203], 0, s[8:9]
	s_mov_b32 m0, s51
	ds_read_b128 v[216:219], v173
	ds_read_b128 v[220:223], v173 offset:1024
	ds_read_b128 v[224:227], v173 offset:2048
	ds_read_b128 v[228:231], v173 offset:3072
	global_load_lds_dwordx4 v[202:203], off
	v_lshl_add_u64 v[202:203], v[232:233], 0, s[8:9]
	s_add_i32 m0, s51, 0x2000
	s_nop 0
	global_load_lds_dwordx4 v[202:203], off
	s_barrier
	s_waitcnt lgkmcnt(0)
	s_setprio 1
	v_mfma_f32_16x16x32_bf16 v[110:113], v[216:219], v[160:163], v[110:113]
	v_mfma_f32_16x16x32_bf16 v[106:109], v[224:227], v[160:163], v[106:109]
	v_mfma_f32_16x16x32_bf16 v[94:97], v[216:219], v[178:181], v[94:97]
	v_mfma_f32_16x16x32_bf16 v[90:93], v[224:227], v[178:181], v[90:93]
	v_mfma_f32_16x16x32_bf16 v[78:81], v[216:219], v[186:189], v[78:81]
	v_mfma_f32_16x16x32_bf16 v[74:77], v[224:227], v[186:189], v[74:77]
	v_mfma_f32_16x16x32_bf16 v[70:73], v[216:219], v[194:197], v[70:73]
	v_mfma_f32_16x16x32_bf16 v[66:69], v[224:227], v[194:197], v[66:69]
	v_mfma_f32_16x16x32_bf16 v[110:113], v[220:223], v[174:177], v[110:113]
	v_mfma_f32_16x16x32_bf16 v[106:109], v[228:231], v[174:177], v[106:109]
	v_mfma_f32_16x16x32_bf16 v[94:97], v[220:223], v[182:185], v[94:97]
	v_mfma_f32_16x16x32_bf16 v[90:93], v[228:231], v[182:185], v[90:93]
	v_mfma_f32_16x16x32_bf16 v[78:81], v[220:223], v[190:193], v[78:81]
	v_mfma_f32_16x16x32_bf16 v[74:77], v[228:231], v[190:193], v[74:77]
	v_mfma_f32_16x16x32_bf16 v[70:73], v[220:223], v[198:201], v[70:73]
	v_mfma_f32_16x16x32_bf16 v[66:69], v[228:231], v[198:201], v[66:69]
	s_setprio 0
	s_barrier
	s_mov_b32 m0, s75
	v_lshl_add_u64 v[202:203], v[234:235], 0, s[8:9]
	ds_read_b128 v[160:163], v143 offset:49152
	ds_read_b128 v[174:177], v143 offset:50176
	ds_read_b128 v[178:181], v143 offset:51200
	ds_read_b128 v[182:185], v143 offset:52224
	ds_read_b128 v[186:189], v143 offset:53248
	ds_read_b128 v[190:193], v143 offset:54272
	ds_read_b128 v[194:197], v143 offset:55296
	ds_read_b128 v[198:201], v143 offset:56320
	global_load_lds_dwordx4 v[202:203], off
	v_lshl_add_u64 v[202:203], v[236:237], 0, s[8:9]
	s_mov_b32 m0, s76
	s_nop 0
	global_load_lds_dwordx4 v[202:203], off
	s_barrier
; #define PG8_STAGE(bufoff, gbase, voff) do { _Pragma("unroll") for (int _i = 0; _i < 2; ++_i) \
;         __builtin_amdgcn_global_load_lds((const unsigned*)((const char*)(gbase) + (voff)[_i]), (PG8_LAS unsigned*)(lds + (bufoff) + ldsw + _i * 8192), 16, 0, 0); } while (0)
; #define PG8_LDA(dst, b, h) do { _Pragma("unroll") for (int m = 0; m < 4; ++m) _Pragma("unroll") for (int k = 0; k < 2; ++k) dst[m][k] = *(const PG8_LAS bf16x8*)(lds + PG8_SA(b, h) + aoff + m * 2048 + k * 1024); } while (0)
; #define PG8_LDB(dst, b, h) do { _Pragma("unroll") for (int n = 0; n < 2; ++n) _Pragma("unroll") for (int k = 0; k < 2; ++k) dst[n][k] = *(const PG8_LAS bf16x8*)(lds + PG8_SB(b, h) + boff + n * 2048 + k * 1024); } while (0)
; #define PG8_MMA(ai, bj, At, Bt) do { __builtin_amdgcn_s_setprio(1); _Pragma("unroll") for (int m = 0; m < 4; ++m) _Pragma("unroll") for (int n = 0; n < 2; ++n) _Pragma("unroll") for (int k = 0; k < 2; ++k) \
;         acc[ai][bj][m][n] = __builtin_amdgcn_mfma_f32_16x16x32_bf16(Bt[n][k], At[m][k], acc[ai][bj][m][n], 0, 0, 0); __builtin_amdgcn_s_setprio(0); } while (0)
; #define PG8_WAIT_V(n) asm volatile("s_waitcnt vmcnt(" #n ")" ::: "memory")
; #define PG8_WAIT_L(n) asm volatile("s_waitcnt lgkmcnt(" #n ")" ::: "memory")
; #define PG8_BAR __builtin_amdgcn_s_barrier()
; #define PG8_SCHED __builtin_amdgcn_sched_barrier(0)
; template <class Epi, class Sched>
; __device__ __forceinline__ void gemm_phase(PG8_LAS unsigned char* lds, const Gemm g, const Sched& S, const Epi& E) {
;     ...
;             PG8_LDB(B0, 0, 0); PG8_SCHED; PG8_LDA(At, 0, 0); PG8_STAGE(PG8_SA(1, 1), a1 + hstep, voffA);
;             PG8_WAIT_L(8); PG8_BAR; PG8_WAIT_L(0); PG8_MMA(0, 0, At, B0); PG8_BAR; PG8_SCHED;
;             PG8_LDB(B1, 0, 1); PG8_STAGE(PG8_SB(0, 0), b2, voffB);
;             PG8_BAR; PG8_WAIT_L(0); PG8_MMA(0, 1, At, B1); PG8_BAR;
;     ...
;             PG8_BAR; PG8_WAIT_L(0); PG8_MMA(1, 0, At, B0); PG8_BAR; PG8_SCHED;
;             PG8_STAGE(PG8_SB(1, 1), b3 + hstep, voffB);
;             PG8_WAIT_V(6); PG8_BAR; PG8_MMA(1, 1, At, B1); PG8_BAR;
	s_waitcnt lgkmcnt(0)
	s_setprio 1
	v_mfma_f32_16x16x32_bf16 v[62:65], v[144:147], v[160:163], v[62:65]
	v_mfma_f32_16x16x32_bf16 v[58:61], v[152:155], v[160:163], v[58:61]
	v_mfma_f32_16x16x32_bf16 v[54:57], v[144:147], v[178:181], v[54:57]
	v_mfma_f32_16x16x32_bf16 v[50:53], v[152:155], v[178:181], v[50:53]
	v_mfma_f32_16x16x32_bf16 v[38:41], v[144:147], v[186:189], v[38:41]
	v_mfma_f32_16x16x32_bf16 v[34:37], v[152:155], v[186:189], v[34:37]
	v_mfma_f32_16x16x32_bf16 v[22:25], v[144:147], v[194:197], v[22:25]
	v_mfma_f32_16x16x32_bf16 v[18:21], v[152:155], v[194:197], v[18:21]
	v_mfma_f32_16x16x32_bf16 v[62:65], v[148:151], v[174:177], v[62:65]
	v_mfma_f32_16x16x32_bf16 v[58:61], v[156:159], v[174:177], v[58:61]
	v_mfma_f32_16x16x32_bf16 v[54:57], v[148:151], v[182:185], v[54:57]
	v_mfma_f32_16x16x32_bf16 v[50:53], v[156:159], v[182:185], v[50:53]
	v_mfma_f32_16x16x32_bf16 v[38:41], v[148:151], v[190:193], v[38:41]
	v_mfma_f32_16x16x32_bf16 v[34:37], v[156:159], v[190:193], v[34:37]
	v_mfma_f32_16x16x32_bf16 v[22:25], v[148:151], v[198:201], v[22:25]
	v_mfma_f32_16x16x32_bf16 v[18:21], v[156:159], v[198:201], v[18:21]
	s_setprio 0
	s_barrier
	s_add_u32 s10, s10, 0x40080
	s_addc_u32 s11, s11, 0
	s_add_i32 s50, s50, s70
	v_lshl_add_u64 v[144:145], s[10:11], 0, v[0:1]
	s_mov_b32 m0, s50
	s_nop 0
	global_load_lds_dwordx4 v[144:145], off
	v_lshl_add_u64 v[144:145], s[10:11], 0, v[130:131]
	s_add_i32 m0, s50, 0x2000
	s_nop 0
	global_load_lds_dwordx4 v[144:145], off
	s_waitcnt vmcnt(6)
	s_barrier
	s_setprio 1
	v_mfma_f32_16x16x32_bf16 v[46:49], v[216:219], v[160:163], v[46:49]
	v_mfma_f32_16x16x32_bf16 v[42:45], v[224:227], v[160:163], v[42:45]
	v_mfma_f32_16x16x32_bf16 v[30:33], v[216:219], v[178:181], v[30:33]
	v_mfma_f32_16x16x32_bf16 v[26:29], v[224:227], v[178:181], v[26:29]
	v_mfma_f32_16x16x32_bf16 v[14:17], v[216:219], v[186:189], v[14:17]
	v_mfma_f32_16x16x32_bf16 v[10:13], v[224:227], v[186:189], v[10:13]
	v_mfma_f32_16x16x32_bf16 v[6:9], v[216:219], v[194:197], v[6:9]
	v_mfma_f32_16x16x32_bf16 v[2:5], v[224:227], v[194:197], v[2:5]
	v_mfma_f32_16x16x32_bf16 v[46:49], v[220:223], v[174:177], v[46:49]
	v_mfma_f32_16x16x32_bf16 v[42:45], v[228:231], v[174:177], v[42:45]
	v_mfma_f32_16x16x32_bf16 v[30:33], v[220:223], v[182:185], v[30:33]
	v_mfma_f32_16x16x32_bf16 v[26:29], v[228:231], v[182:185], v[26:29]
	v_mfma_f32_16x16x32_bf16 v[14:17], v[220:223], v[190:193], v[14:17]
	v_mfma_f32_16x16x32_bf16 v[10:13], v[228:231], v[190:193], v[10:13]
	v_mfma_f32_16x16x32_bf16 v[6:9], v[220:223], v[198:201], v[6:9]
	v_mfma_f32_16x16x32_bf16 v[2:5], v[228:231], v[198:201], v[2:5]
	s_setprio 0
	s_add_i32 s83, s83, 2
	s_cmp_gt_u32 s83, 13
	s_barrier
.LBB0_88:
	s_add_u32 s40, s40, 0x100
	s_addc_u32 s41, s41, 0
	s_add_u32 s81, s81, 0x100
	s_addc_u32 s82, s82, 0
	s_add_u32 s10, s40, 0xfffc0080
	s_addc_u32 s11, s41, -1
	s_add_i32 s84, 0, 0x10000
	v_add_u32_e32 v156, s84, v141
	ds_read_b128 v[144:147], v156
	ds_read_b128 v[148:151], v156 offset:1024
	ds_read_b128 v[152:155], v156 offset:2048
	ds_read_b128 v[156:159], v156 offset:3072
	s_cmp_eq_u32 s83, 12
	s_cselect_b32 s51, s19, s11
	s_cselect_b32 s50, s79, s10
	s_cselect_b32 s11, s7, s82
	s_cselect_b32 s10, s80, s81
	v_lshl_add_u64 v[202:203], s[40:41], 0, v[136:137]
	s_add_i32 m0, s71, 0xc000
	ds_read_b128 v[160:163], v143
	ds_read_b128 v[174:177], v143 offset:1024
	ds_read_b128 v[178:181], v143 offset:2048
	ds_read_b128 v[182:185], v143 offset:3072
	ds_read_b128 v[186:189], v143 offset:4096
	ds_read_b128 v[190:193], v143 offset:5120
	ds_read_b128 v[194:197], v143 offset:6144
	ds_read_b128 v[198:201], v143 offset:7168
	global_load_lds_dwordx4 v[202:203], off
	v_lshl_add_u64 v[202:203], s[40:41], 0, v[138:139]
	s_add_i32 m0, s71, 0xe000
	s_nop 0
	global_load_lds_dwordx4 v[202:203], off
	s_waitcnt lgkmcnt(8)
	s_barrier
	s_waitcnt lgkmcnt(0)
	s_setprio 1
	v_mfma_f32_16x16x32_bf16 v[126:129], v[144:147], v[160:163], v[126:129]
	v_mfma_f32_16x16x32_bf16 v[122:125], v[152:155], v[160:163], v[122:125]
	v_mfma_f32_16x16x32_bf16 v[118:121], v[144:147], v[178:181], v[118:121]
	v_mfma_f32_16x16x32_bf16 v[114:117], v[152:155], v[178:181], v[114:117]
	v_mfma_f32_16x16x32_bf16 v[102:105], v[144:147], v[186:189], v[102:105]
	v_mfma_f32_16x16x32_bf16 v[98:101], v[152:155], v[186:189], v[98:101]
	v_mfma_f32_16x16x32_bf16 v[86:89], v[144:147], v[194:197], v[86:89]
	v_mfma_f32_16x16x32_bf16 v[82:85], v[152:155], v[194:197], v[82:85]
	v_mfma_f32_16x16x32_bf16 v[126:129], v[148:151], v[174:177], v[126:129]
	v_mfma_f32_16x16x32_bf16 v[122:125], v[156:159], v[174:177], v[122:125]
	v_mfma_f32_16x16x32_bf16 v[118:121], v[148:151], v[182:185], v[118:121]
	v_mfma_f32_16x16x32_bf16 v[114:117], v[156:159], v[182:185], v[114:117]
	v_mfma_f32_16x16x32_bf16 v[102:105], v[148:151], v[190:193], v[102:105]
	v_mfma_f32_16x16x32_bf16 v[98:101], v[156:159], v[190:193], v[98:101]
	v_mfma_f32_16x16x32_bf16 v[86:89], v[148:151], v[198:201], v[86:89]
	v_mfma_f32_16x16x32_bf16 v[82:85], v[156:159], v[198:201], v[82:85]
	s_setprio 0
	s_barrier
	s_add_i32 s86, 0, 0x14000
	s_add_i32 s84, s84, s70
	v_add_u32_e32 v173, s86, v141
	v_lshl_add_u64 v[202:203], s[10:11], 0, v[0:1]
	s_mov_b32 m0, s84
	ds_read_b128 v[216:219], v173
	ds_read_b128 v[220:223], v173 offset:1024
	ds_read_b128 v[224:227], v173 offset:2048
	ds_read_b128 v[228:231], v173 offset:3072
	global_load_lds_dwordx4 v[202:203], off
	v_lshl_add_u64 v[232:233], s[10:11], 0, v[130:131]
	s_add_i32 m0, s84, 0x2000
	s_nop 0
	global_load_lds_dwordx4 v[232:233], off
	s_barrier
; #define PG8_STAGE(bufoff, gbase, voff) do { _Pragma("unroll") for (int _i = 0; _i < 2; ++_i) \
;         __builtin_amdgcn_global_load_lds((const unsigned*)((const char*)(gbase) + (voff)[_i]), (PG8_LAS unsigned*)(lds + (bufoff) + ldsw + _i * 8192), 16, 0, 0); } while (0)
; #define PG8_LDA(dst, b, h) do { _Pragma("unroll") for (int m = 0; m < 4; ++m) _Pragma("unroll") for (int k = 0; k < 2; ++k) dst[m][k] = *(const PG8_LAS bf16x8*)(lds + PG8_SA(b, h) + aoff + m * 2048 + k * 1024); } while (0)
; #define PG8_LDB(dst, b, h) do { _Pragma("unroll") for (int n = 0; n < 2; ++n) _Pragma("unroll") for (int k = 0; k < 2; ++k) dst[n][k] = *(const PG8_LAS bf16x8*)(lds + PG8_SB(b, h) + boff + n * 2048 + k * 1024); } while (0)
; #define PG8_MMA(ai, bj, At, Bt) do { __builtin_amdgcn_s_setprio(1); _Pragma("unroll") for (int m = 0; m < 4; ++m) _Pragma("unroll") for (int n = 0; n < 2; ++n) _Pragma("unroll") for (int k = 0; k < 2; ++k) \
;         acc[ai][bj][m][n] = __builtin_amdgcn_mfma_f32_16x16x32_bf16(Bt[n][k], At[m][k], acc[ai][bj][m][n], 0, 0, 0); __builtin_amdgcn_s_setprio(0); } while (0)
; #define PG8_WAIT_V(n) asm volatile("s_waitcnt vmcnt(" #n ")" ::: "memory")
; #define PG8_WAIT_L(n) asm volatile("s_waitcnt lgkmcnt(" #n ")" ::: "memory")
; #define PG8_BAR __builtin_amdgcn_s_barrier()
; #define PG8_SCHED __builtin_amdgcn_sched_barrier(0)
; template <class Epi, class Sched>
; __device__ __forceinline__ void gemm_phase(PG8_LAS unsigned char* lds, const Gemm g, const Sched& S, const Epi& E) {
;     ...
;             PG8_BAR; PG8_WAIT_L(0); PG8_MMA(0, 1, At, B1); PG8_BAR;
;             PG8_LDA(At, 0, 1); PG8_STAGE(PG8_SA(0, 0), a2, voffA);
;             PG8_BAR; PG8_WAIT_L(0); PG8_MMA(1, 0, At, B0); PG8_BAR; PG8_SCHED;
;             PG8_STAGE(PG8_SB(0, 1), b2 + hstep, voffB);
;             PG8_WAIT_V(6); PG8_BAR; PG8_MMA(1, 1, At, B1); PG8_BAR;
;             PG8_LDB(B0, 1, 0); PG8_SCHED; PG8_LDA(At, 1, 0); PG8_STAGE(PG8_SA(0, 1), a2 + hstep, voffA);
;             PG8_WAIT_L(8); PG8_BAR; PG8_WAIT_L(0); PG8_MMA(0, 0, At, B0); PG8_BAR; PG8_SCHED;
	s_waitcnt lgkmcnt(0)
	s_setprio 1
	v_mfma_f32_16x16x32_bf16 v[110:113], v[216:219], v[160:163], v[110:113]
	v_mfma_f32_16x16x32_bf16 v[106:109], v[224:227], v[160:163], v[106:109]
	v_mfma_f32_16x16x32_bf16 v[94:97], v[216:219], v[178:181], v[94:97]
	v_mfma_f32_16x16x32_bf16 v[90:93], v[224:227], v[178:181], v[90:93]
	v_mfma_f32_16x16x32_bf16 v[78:81], v[216:219], v[186:189], v[78:81]
	v_mfma_f32_16x16x32_bf16 v[74:77], v[224:227], v[186:189], v[74:77]
	v_mfma_f32_16x16x32_bf16 v[70:73], v[216:219], v[194:197], v[70:73]
	v_mfma_f32_16x16x32_bf16 v[66:69], v[224:227], v[194:197], v[66:69]
	v_mfma_f32_16x16x32_bf16 v[110:113], v[220:223], v[174:177], v[110:113]
	v_mfma_f32_16x16x32_bf16 v[106:109], v[228:231], v[174:177], v[106:109]
	v_mfma_f32_16x16x32_bf16 v[94:97], v[220:223], v[182:185], v[94:97]
	v_mfma_f32_16x16x32_bf16 v[90:93], v[228:231], v[182:185], v[90:93]
	v_mfma_f32_16x16x32_bf16 v[78:81], v[220:223], v[190:193], v[78:81]
	v_mfma_f32_16x16x32_bf16 v[74:77], v[228:231], v[190:193], v[74:77]
	v_mfma_f32_16x16x32_bf16 v[70:73], v[220:223], v[198:201], v[70:73]
	v_mfma_f32_16x16x32_bf16 v[66:69], v[228:231], v[198:201], v[66:69]
	s_setprio 0
	s_barrier
	s_mov_b32 m0, s71
	v_lshl_add_u64 v[234:235], s[50:51], 0, v[134:135]
	ds_read_b128 v[160:163], v143 offset:16384
	ds_read_b128 v[174:177], v143 offset:17408
	ds_read_b128 v[178:181], v143 offset:18432
	ds_read_b128 v[182:185], v143 offset:19456
	ds_read_b128 v[186:189], v143 offset:20480
	ds_read_b128 v[190:193], v143 offset:21504
	ds_read_b128 v[194:197], v143 offset:22528
	ds_read_b128 v[198:201], v143 offset:23552
	global_load_lds_dwordx4 v[234:235], off
	v_lshl_add_u64 v[236:237], s[50:51], 0, v[132:133]
	s_mov_b32 m0, s72
	s_nop 0
	global_load_lds_dwordx4 v[236:237], off
	s_barrier
	s_waitcnt lgkmcnt(0)
	s_setprio 1
	v_mfma_f32_16x16x32_bf16 v[62:65], v[144:147], v[160:163], v[62:65]
	v_mfma_f32_16x16x32_bf16 v[58:61], v[152:155], v[160:163], v[58:61]
	v_mfma_f32_16x16x32_bf16 v[54:57], v[144:147], v[178:181], v[54:57]
	v_mfma_f32_16x16x32_bf16 v[50:53], v[152:155], v[178:181], v[50:53]
	v_mfma_f32_16x16x32_bf16 v[38:41], v[144:147], v[186:189], v[38:41]
	v_mfma_f32_16x16x32_bf16 v[34:37], v[152:155], v[186:189], v[34:37]
	v_mfma_f32_16x16x32_bf16 v[22:25], v[144:147], v[194:197], v[22:25]
	v_mfma_f32_16x16x32_bf16 v[18:21], v[152:155], v[194:197], v[18:21]
	v_mfma_f32_16x16x32_bf16 v[62:65], v[148:151], v[174:177], v[62:65]
	v_mfma_f32_16x16x32_bf16 v[58:61], v[156:159], v[174:177], v[58:61]
	v_mfma_f32_16x16x32_bf16 v[54:57], v[148:151], v[182:185], v[54:57]
	v_mfma_f32_16x16x32_bf16 v[50:53], v[156:159], v[182:185], v[50:53]
	v_mfma_f32_16x16x32_bf16 v[38:41], v[148:151], v[190:193], v[38:41]
	v_mfma_f32_16x16x32_bf16 v[34:37], v[156:159], v[190:193], v[34:37]
	v_mfma_f32_16x16x32_bf16 v[22:25], v[148:151], v[198:201], v[22:25]
	v_mfma_f32_16x16x32_bf16 v[18:21], v[156:159], v[198:201], v[18:21]
	s_setprio 0
	s_barrier
	s_add_u32 s84, s10, 0x40000
	s_addc_u32 s85, s11, 0
	s_add_i32 s86, s86, s70
	v_lshl_add_u64 v[144:145], s[84:85], 0, v[0:1]
	s_mov_b32 m0, s86
	s_nop 0
	global_load_lds_dwordx4 v[144:145], off
	v_lshl_add_u64 v[144:145], s[84:85], 0, v[130:131]
	s_add_i32 m0, s86, 0x2000
	s_nop 0
	global_load_lds_dwordx4 v[144:145], off
	s_waitcnt vmcnt(6)
	s_barrier
	s_setprio 1
	v_mfma_f32_16x16x32_bf16 v[46:49], v[216:219], v[160:163], v[46:49]
	v_mfma_f32_16x16x32_bf16 v[42:45], v[224:227], v[160:163], v[42:45]
	v_mfma_f32_16x16x32_bf16 v[30:33], v[216:219], v[178:181], v[30:33]
	v_mfma_f32_16x16x32_bf16 v[26:29], v[224:227], v[178:181], v[26:29]
	v_mfma_f32_16x16x32_bf16 v[14:17], v[216:219], v[186:189], v[14:17]
	v_mfma_f32_16x16x32_bf16 v[10:13], v[224:227], v[186:189], v[10:13]
	v_mfma_f32_16x16x32_bf16 v[6:9], v[216:219], v[194:197], v[6:9]
	v_mfma_f32_16x16x32_bf16 v[2:5], v[224:227], v[194:197], v[2:5]
	v_mfma_f32_16x16x32_bf16 v[46:49], v[220:223], v[174:177], v[46:49]
	v_mfma_f32_16x16x32_bf16 v[42:45], v[228:231], v[174:177], v[42:45]
	v_mfma_f32_16x16x32_bf16 v[30:33], v[220:223], v[182:185], v[30:33]
	v_mfma_f32_16x16x32_bf16 v[26:29], v[228:231], v[182:185], v[26:29]
	v_mfma_f32_16x16x32_bf16 v[14:17], v[220:223], v[190:193], v[14:17]
	v_mfma_f32_16x16x32_bf16 v[10:13], v[228:231], v[190:193], v[10:13]
	v_mfma_f32_16x16x32_bf16 v[6:9], v[220:223], v[198:201], v[6:9]
	v_mfma_f32_16x16x32_bf16 v[2:5], v[228:231], v[198:201], v[2:5]
	s_setprio 0
	s_barrier
	s_add_i32 s84, 0, 0x18000
	v_add_u32_e32 v156, s84, v141
	ds_read_b128 v[144:147], v156
	ds_read_b128 v[148:151], v156 offset:1024
	ds_read_b128 v[152:155], v156 offset:2048
	ds_read_b128 v[156:159], v156 offset:3072
	s_add_u32 s50, s50, 0x40000
	s_addc_u32 s51, s51, 0
	s_mov_b32 m0, s73
	v_lshl_add_u64 v[216:217], s[50:51], 0, v[134:135]
	ds_read_b128 v[160:163], v143 offset:32768
	ds_read_b128 v[174:177], v143 offset:33792
	ds_read_b128 v[178:181], v143 offset:34816
	ds_read_b128 v[182:185], v143 offset:35840
	ds_read_b128 v[186:189], v143 offset:36864
	ds_read_b128 v[190:193], v143 offset:37888
	ds_read_b128 v[194:197], v143 offset:38912
	ds_read_b128 v[198:201], v143 offset:39936
	global_load_lds_dwordx4 v[216:217], off
	v_lshl_add_u64 v[216:217], s[50:51], 0, v[132:133]
	s_mov_b32 m0, s74
	s_nop 0
	global_load_lds_dwordx4 v[216:217], off
	s_waitcnt lgkmcnt(8)
	s_barrier
; #define PG8_STAGE(bufoff, gbase, voff) do { _Pragma("unroll") for (int _i = 0; _i < 2; ++_i) \
;         __builtin_amdgcn_global_load_lds((const unsigned*)((const char*)(gbase) + (voff)[_i]), (PG8_LAS unsigned*)(lds + (bufoff) + ldsw + _i * 8192), 16, 0, 0); } while (0)
; #define PG8_LDA(dst, b, h) do { _Pragma("unroll") for (int m = 0; m < 4; ++m) _Pragma("unroll") for (int k = 0; k < 2; ++k) dst[m][k] = *(const PG8_LAS bf16x8*)(lds + PG8_SA(b, h) + aoff + m * 2048 + k * 1024); } while (0)
; #define PG8_LDB(dst, b, h) do { _Pragma("unroll") for (int n = 0; n < 2; ++n) _Pragma("unroll") for (int k = 0; k < 2; ++k) dst[n][k] = *(const PG8_LAS bf16x8*)(lds + PG8_SB(b, h) + boff + n * 2048 + k * 1024); } while (0)
; #define PG8_WAIT_V(n) asm volatile("s_waitcnt vmcnt(" #n ")" ::: "memory")
; #define PG8_WAIT_L(n) asm volatile("s_waitcnt lgkmcnt(" #n ")" ::: "memory")
; #define PG8_BAR __builtin_amdgcn_s_barrier()
; #define PG8_SCHED __builtin_amdgcn_sched_barrier(0)
; template <class Epi, class Sched>
; __device__ __forceinline__ void gemm_phase(PG8_LAS unsigned char* lds, const Gemm g, const Sched& S, const Epi& E) {
;     ...
;             PG8_WAIT_L(8); PG8_BAR; PG8_WAIT_L(0); PG8_MMA(0, 0, At, B0); PG8_BAR; PG8_SCHED;
;             PG8_LDB(B1, 1, 1); PG8_STAGE(PG8_SB(1, 0), b3, voffB);
;             PG8_BAR; PG8_WAIT_L(0); PG8_MMA(0, 1, At, B1); PG8_BAR;
;             PG8_LDA(At, 1, 1); PG8_STAGE(PG8_SA(1, 0), a3, voffA);
;             PG8_BAR; PG8_WAIT_L(0); PG8_MMA(1, 0, At, B0); PG8_BAR; PG8_SCHED;
;             PG8_STAGE(PG8_SB(1, 1), b3 + hstep, voffB);
;             PG8_WAIT_V(6); PG8_BAR; PG8_MMA(1, 1, At, B1); PG8_BAR;
; __device__ __forceinline__ void seg_of(int ct, int& c0, int& w) {
;     if (ct < OFF_LQ) { c0 = ct & ~1023; w = 1024; }
;     else if (ct < OFF_LG) { const int k = (ct - OFF_LQ) / 1536; c0 = OFF_LQ + k * 1536; w = 1536; }
;     else if (ct < OFF_GATE) { c0 = OFF_LG + ((ct - OFF_LG) & ~511); w = 512; }
;     else { c0 = OFF_GATE; w = 3072; }
; }
;     __device__ __forceinline__ void operator()(const f32x4 (&acc)[2][2][4][2], const Unit& u, int wr, int wc, int fr, int fq) const {
;         const int row0 = u.pm * 256 + wr * 64 + fr; int col0 = u.pn * 256 + wc * 32 + 8 * fq; int ld = ldz; bf16* base = Z;
;         if (SEG) { int c0, w; seg_of(u.pn * 256, c0, w); base = Z + (size_t)T * c0; ld = w; col0 -= c0; }
	s_waitcnt lgkmcnt(0)
	s_setprio 1
	v_mfma_f32_16x16x32_bf16 v[126:129], v[144:147], v[160:163], v[126:129]
	v_mfma_f32_16x16x32_bf16 v[122:125], v[152:155], v[160:163], v[122:125]
	v_mfma_f32_16x16x32_bf16 v[118:121], v[144:147], v[178:181], v[118:121]
	v_mfma_f32_16x16x32_bf16 v[114:117], v[152:155], v[178:181], v[114:117]
	v_mfma_f32_16x16x32_bf16 v[102:105], v[144:147], v[186:189], v[102:105]
	v_mfma_f32_16x16x32_bf16 v[98:101], v[152:155], v[186:189], v[98:101]
	v_mfma_f32_16x16x32_bf16 v[86:89], v[144:147], v[194:197], v[86:89]
	v_mfma_f32_16x16x32_bf16 v[82:85], v[152:155], v[194:197], v[82:85]
	v_mfma_f32_16x16x32_bf16 v[126:129], v[148:151], v[174:177], v[126:129]
	v_mfma_f32_16x16x32_bf16 v[122:125], v[156:159], v[174:177], v[122:125]
	v_mfma_f32_16x16x32_bf16 v[118:121], v[148:151], v[182:185], v[118:121]
	v_mfma_f32_16x16x32_bf16 v[114:117], v[156:159], v[182:185], v[114:117]
	v_mfma_f32_16x16x32_bf16 v[102:105], v[148:151], v[190:193], v[102:105]
	v_mfma_f32_16x16x32_bf16 v[98:101], v[156:159], v[190:193], v[98:101]
	v_mfma_f32_16x16x32_bf16 v[86:89], v[148:151], v[198:201], v[86:89]
	v_mfma_f32_16x16x32_bf16 v[82:85], v[156:159], v[198:201], v[82:85]
	s_setprio 0
	s_barrier
	s_add_i32 s50, 0, 0x1c000
	s_add_i32 s51, s84, s70
	v_add_u32_e32 v173, s50, v141
	v_lshl_add_u64 v[202:203], v[202:203], 0, s[8:9]
	s_mov_b32 m0, s51
	ds_read_b128 v[216:219], v173
	ds_read_b128 v[220:223], v173 offset:1024
	ds_read_b128 v[224:227], v173 offset:2048
	ds_read_b128 v[228:231], v173 offset:3072
	global_load_lds_dwordx4 v[202:203], off
	v_lshl_add_u64 v[202:203], v[232:233], 0, s[8:9]
	s_add_i32 m0, s51, 0x2000
	s_nop 0
	global_load_lds_dwordx4 v[202:203], off
	s_barrier
	s_waitcnt lgkmcnt(0)
	s_setprio 1
	v_mfma_f32_16x16x32_bf16 v[110:113], v[216:219], v[160:163], v[110:113]
	v_mfma_f32_16x16x32_bf16 v[106:109], v[224:227], v[160:163], v[106:109]
	v_mfma_f32_16x16x32_bf16 v[94:97], v[216:219], v[178:181], v[94:97]
	v_mfma_f32_16x16x32_bf16 v[90:93], v[224:227], v[178:181], v[90:93]
	v_mfma_f32_16x16x32_bf16 v[78:81], v[216:219], v[186:189], v[78:81]
	v_mfma_f32_16x16x32_bf16 v[74:77], v[224:227], v[186:189], v[74:77]
	v_mfma_f32_16x16x32_bf16 v[70:73], v[216:219], v[194:197], v[70:73]
	v_mfma_f32_16x16x32_bf16 v[66:69], v[224:227], v[194:197], v[66:69]
	v_mfma_f32_16x16x32_bf16 v[110:113], v[220:223], v[174:177], v[110:113]
	v_mfma_f32_16x16x32_bf16 v[106:109], v[228:231], v[174:177], v[106:109]
	v_mfma_f32_16x16x32_bf16 v[94:97], v[220:223], v[182:185], v[94:97]
	v_mfma_f32_16x16x32_bf16 v[90:93], v[228:231], v[182:185], v[90:93]
	v_mfma_f32_16x16x32_bf16 v[78:81], v[220:223], v[190:193], v[78:81]
	v_mfma_f32_16x16x32_bf16 v[74:77], v[228:231], v[190:193], v[74:77]
	v_mfma_f32_16x16x32_bf16 v[70:73], v[220:223], v[198:201], v[70:73]
	v_mfma_f32_16x16x32_bf16 v[66:69], v[228:231], v[198:201], v[66:69]
	s_setprio 0
	s_barrier
	s_mov_b32 m0, s75
	v_lshl_add_u64 v[202:203], v[234:235], 0, s[8:9]
	ds_read_b128 v[160:163], v143 offset:49152
	ds_read_b128 v[174:177], v143 offset:50176
	ds_read_b128 v[178:181], v143 offset:51200
	ds_read_b128 v[182:185], v143 offset:52224
	ds_read_b128 v[186:189], v143 offset:53248
	ds_read_b128 v[190:193], v143 offset:54272
	ds_read_b128 v[194:197], v143 offset:55296
	ds_read_b128 v[198:201], v143 offset:56320
	global_load_lds_dwordx4 v[202:203], off
	v_lshl_add_u64 v[202:203], v[236:237], 0, s[8:9]
	s_mov_b32 m0, s76
	s_nop 0
	global_load_lds_dwordx4 v[202:203], off
	s_barrier
	s_waitcnt lgkmcnt(0)
	s_setprio 1
	v_mfma_f32_16x16x32_bf16 v[62:65], v[144:147], v[160:163], v[62:65]
	v_mfma_f32_16x16x32_bf16 v[58:61], v[152:155], v[160:163], v[58:61]
	v_mfma_f32_16x16x32_bf16 v[54:57], v[144:147], v[178:181], v[54:57]
	v_mfma_f32_16x16x32_bf16 v[50:53], v[152:155], v[178:181], v[50:53]
	v_mfma_f32_16x16x32_bf16 v[38:41], v[144:147], v[186:189], v[38:41]
	v_mfma_f32_16x16x32_bf16 v[34:37], v[152:155], v[186:189], v[34:37]
	v_mfma_f32_16x16x32_bf16 v[22:25], v[144:147], v[194:197], v[22:25]
	v_mfma_f32_16x16x32_bf16 v[18:21], v[152:155], v[194:197], v[18:21]
	v_mfma_f32_16x16x32_bf16 v[62:65], v[148:151], v[174:177], v[62:65]
	v_mfma_f32_16x16x32_bf16 v[58:61], v[156:159], v[174:177], v[58:61]
	v_mfma_f32_16x16x32_bf16 v[54:57], v[148:151], v[182:185], v[54:57]
	v_mfma_f32_16x16x32_bf16 v[50:53], v[156:159], v[182:185], v[50:53]
	v_mfma_f32_16x16x32_bf16 v[38:41], v[148:151], v[190:193], v[38:41]
	v_mfma_f32_16x16x32_bf16 v[34:37], v[156:159], v[190:193], v[34:37]
	v_mfma_f32_16x16x32_bf16 v[22:25], v[148:151], v[198:201], v[22:25]
	v_mfma_f32_16x16x32_bf16 v[18:21], v[156:159], v[198:201], v[18:21]
	s_setprio 0
	s_barrier
	s_add_u32 s10, s10, 0x40080
	s_addc_u32 s11, s11, 0
	s_add_i32 s50, s50, s70
	v_lshl_add_u64 v[144:145], s[10:11], 0, v[0:1]
	s_mov_b32 m0, s50
	s_nop 0
	global_load_lds_dwordx4 v[144:145], off
	v_lshl_add_u64 v[144:145], s[10:11], 0, v[130:131]
	s_add_i32 m0, s50, 0x2000
	s_nop 0
	global_load_lds_dwordx4 v[144:145], off
	s_waitcnt vmcnt(6)
	s_barrier
	s_setprio 1
	v_mfma_f32_16x16x32_bf16 v[46:49], v[216:219], v[160:163], v[46:49]
	v_mfma_f32_16x16x32_bf16 v[42:45], v[224:227], v[160:163], v[42:45]
	v_mfma_f32_16x16x32_bf16 v[30:33], v[216:219], v[178:181], v[30:33]
	v_mfma_f32_16x16x32_bf16 v[26:29], v[224:227], v[178:181], v[26:29]
	v_mfma_f32_16x16x32_bf16 v[14:17], v[216:219], v[186:189], v[14:17]
	v_mfma_f32_16x16x32_bf16 v[10:13], v[224:227], v[186:189], v[10:13]
	v_mfma_f32_16x16x32_bf16 v[6:9], v[216:219], v[194:197], v[6:9]
	v_mfma_f32_16x16x32_bf16 v[2:5], v[224:227], v[194:197], v[2:5]
	v_mfma_f32_16x16x32_bf16 v[46:49], v[220:223], v[174:177], v[46:49]
	v_mfma_f32_16x16x32_bf16 v[42:45], v[228:231], v[174:177], v[42:45]
	v_mfma_f32_16x16x32_bf16 v[30:33], v[220:223], v[182:185], v[30:33]
	v_mfma_f32_16x16x32_bf16 v[26:29], v[228:231], v[182:185], v[26:29]
	v_mfma_f32_16x16x32_bf16 v[14:17], v[220:223], v[190:193], v[14:17]
	v_mfma_f32_16x16x32_bf16 v[10:13], v[228:231], v[190:193], v[10:13]
	v_mfma_f32_16x16x32_bf16 v[6:9], v[220:223], v[198:201], v[6:9]
	v_mfma_f32_16x16x32_bf16 v[2:5], v[228:231], v[198:201], v[2:5]
	s_setprio 0
	s_add_i32 s83, s83, 2
	s_cmp_gt_u32 s83, 13
	s_barrier
	s_cbranch_scc0 .LBB0_88
	s_lshl_b32 s7, s28, 8
	s_cmp_gt_i32 s28, 15
	s_mov_b64 s[50:51], -1
	s_cbranch_scc0 .LBB0_95
	s_cmpk_gt_u32 s7, 0x21ff
	s_cbranch_scc0 .LBB0_92
	s_min_u32 s10, s7, 0x2800
	s_and_b32 s40, s10, 0x3e00
	s_cmpk_lt_u32 s7, 0x2800
	s_movk_i32 s10, 0x200
	s_cselect_b32 s28, s10, 0xc00
	s_mov_b64 s[50:51], 0
	s_mov_b64 s[10:11], s[28:29]

; #define PG8_STAGE(bufoff, gbase, voff) do { _Pragma("unroll") for (int _i = 0; _i < 2; ++_i) \
;         __builtin_amdgcn_global_load_lds((const unsigned*)((const char*)(gbase) + (voff)[_i]), (PG8_LAS unsigned*)(lds + (bufoff) + ldsw + _i * 8192), 16, 0, 0); } while (0)
; #define PG8_LDA(dst, b, h) do { _Pragma("unroll") for (int m = 0; m < 4; ++m) _Pragma("unroll") for (int k = 0; k < 2; ++k) dst[m][k] = *(const PG8_LAS bf16x8*)(lds + PG8_SA(b, h) + aoff + m * 2048 + k * 1024); } while (0)
; #define PG8_LDB(dst, b, h) do { _Pragma("unroll") for (int n = 0; n < 2; ++n) _Pragma("unroll") for (int k = 0; k < 2; ++k) dst[n][k] = *(const PG8_LAS bf16x8*)(lds + PG8_SB(b, h) + boff + n * 2048 + k * 1024); } while (0)
; #define PG8_MMA(ai, bj, At, Bt) do { __builtin_amdgcn_s_setprio(1); _Pragma("unroll") for (int m = 0; m < 4; ++m) _Pragma("unroll") for (int n = 0; n < 2; ++n) _Pragma("unroll") for (int k = 0; k < 2; ++k) \
;         acc[ai][bj][m][n] = __builtin_amdgcn_mfma_f32_16x16x32_bf16(Bt[n][k], At[m][k], acc[ai][bj][m][n], 0, 0, 0); __builtin_amdgcn_s_setprio(0); } while (0)
; #define PG8_WAIT_L(n) asm volatile("s_waitcnt lgkmcnt(" #n ")" ::: "memory")
; #define PG8_BAR __builtin_amdgcn_s_barrier()
; #define PG8_SCHED __builtin_amdgcn_sched_barrier(0)
; template <class Epi, class Sched>
; __device__ __forceinline__ void gemm_phase(PG8_LAS unsigned char* lds, const Gemm g, const Sched& S, const Epi& E) {
;     ...
;             PG8_LDB(B0, 0, 0); PG8_SCHED; PG8_LDA(At, 0, 0); PG8_STAGE(PG8_SA(1, 1), a1 + hstep, voffA);
;             PG8_WAIT_L(8); PG8_BAR; PG8_WAIT_L(0); PG8_MMA(0, 0, At, B0); PG8_BAR; PG8_SCHED;
;             PG8_LDB(B1, 0, 1); PG8_STAGE(PG8_SB(0, 0), b2, voffB);
;             PG8_BAR; PG8_WAIT_L(0); PG8_MMA(0, 1, At, B1); PG8_BAR;
;             PG8_LDA(At, 0, 1); PG8_STAGE(PG8_SA(0, 0), a2, voffA);
;             PG8_BAR; PG8_WAIT_L(0); PG8_MMA(1, 0, At, B0); PG8_BAR; PG8_SCHED;
.LBB0_472:
	s_add_u32 s6, s50, 0xfff80080
	s_addc_u32 s7, s51, -1
	s_add_i32 s85, 0, 0x10000
	v_add_u32_e32 v0, s85, v222
	ds_read_b128 v[132:135], v0
	ds_read_b128 v[136:139], v0 offset:1024
	ds_read_b128 v[140:143], v0 offset:2048
	ds_read_b128 v[144:147], v0 offset:3072
	s_cmp_eq_u32 s84, 4
	s_cselect_b32 s53, s19, s7
	s_cselect_b32 s52, s41, s6
	s_cselect_b32 s7, s39, s83
	s_cselect_b32 s6, s81, s82
	v_lshl_add_u64 v[2:3], s[50:51], 0, v[182:183]
	s_add_i32 m0, s71, 0xc000
	ds_read_b128 v[148:151], v224
	ds_read_b128 v[152:155], v224 offset:1024
	ds_read_b128 v[156:159], v224 offset:2048
	ds_read_b128 v[160:163], v224 offset:3072
	ds_read_b128 v[186:189], v224 offset:4096
	ds_read_b128 v[190:193], v224 offset:5120
	ds_read_b128 v[194:197], v224 offset:6144
	ds_read_b128 v[198:201], v224 offset:7168
	global_load_lds_dwordx4 v[2:3], off
	v_lshl_add_u64 v[2:3], s[50:51], 0, v[184:185]
	s_add_i32 m0, s71, 0xe000
	s_nop 0
	global_load_lds_dwordx4 v[2:3], off
	s_waitcnt lgkmcnt(8)
	s_barrier
	s_waitcnt lgkmcnt(0)
	s_setprio 1
	v_mfma_f32_16x16x32_bf16 v[2:5], v[132:135], v[148:151], v[4:7]
	v_mfma_f32_16x16x32_bf16 v[6:9], v[140:143], v[148:151], v[8:11]
	v_mfma_f32_16x16x32_bf16 v[12:15], v[132:135], v[156:159], v[12:15]
	v_mfma_f32_16x16x32_bf16 v[16:19], v[140:143], v[156:159], v[16:19]
	v_mfma_f32_16x16x32_bf16 v[20:23], v[132:135], v[186:189], v[20:23]
	v_mfma_f32_16x16x32_bf16 v[24:27], v[140:143], v[186:189], v[24:27]
	v_mfma_f32_16x16x32_bf16 v[28:31], v[132:135], v[194:197], v[28:31]
	v_mfma_f32_16x16x32_bf16 v[32:35], v[140:143], v[194:197], v[32:35]
	v_mfma_f32_16x16x32_bf16 v[2:5], v[136:139], v[152:155], v[2:5]
	v_mfma_f32_16x16x32_bf16 v[8:11], v[144:147], v[152:155], v[6:9]
	v_mfma_f32_16x16x32_bf16 v[12:15], v[136:139], v[160:163], v[12:15]
	v_mfma_f32_16x16x32_bf16 v[16:19], v[144:147], v[160:163], v[16:19]
	v_mfma_f32_16x16x32_bf16 v[20:23], v[136:139], v[190:193], v[20:23]
	v_mfma_f32_16x16x32_bf16 v[24:27], v[144:147], v[190:193], v[24:27]
	v_mfma_f32_16x16x32_bf16 v[28:31], v[136:139], v[198:201], v[28:31]
	v_mfma_f32_16x16x32_bf16 v[32:35], v[144:147], v[198:201], v[32:35]
	s_setprio 0
	s_barrier
	s_add_i32 s88, 0, 0x14000
	s_add_i32 s85, s85, s70
	v_add_u32_e32 v0, s88, v222
	v_lshl_add_u64 v[202:203], s[6:7], 0, v[178:179]
	s_mov_b32 m0, s85
	ds_read_b128 v[226:229], v0
	ds_read_b128 v[230:233], v0 offset:1024
	ds_read_b128 v[234:237], v0 offset:2048
	ds_read_b128 v[238:241], v0 offset:3072
	global_load_lds_dwordx4 v[202:203], off
	v_lshl_add_u64 v[242:243], s[6:7], 0, v[174:175]
	s_add_i32 m0, s85, 0x2000
	s_nop 0
	global_load_lds_dwordx4 v[242:243], off
	s_barrier
	s_waitcnt lgkmcnt(0)
	s_setprio 1
	v_mfma_f32_16x16x32_bf16 v[36:39], v[226:229], v[148:151], v[36:39]
	v_mfma_f32_16x16x32_bf16 v[40:43], v[234:237], v[148:151], v[40:43]
	v_mfma_f32_16x16x32_bf16 v[44:47], v[226:229], v[156:159], v[44:47]
	v_mfma_f32_16x16x32_bf16 v[48:51], v[234:237], v[156:159], v[48:51]
	v_mfma_f32_16x16x32_bf16 v[52:55], v[226:229], v[186:189], v[52:55]
	v_mfma_f32_16x16x32_bf16 v[56:59], v[234:237], v[186:189], v[56:59]
	v_mfma_f32_16x16x32_bf16 v[60:63], v[226:229], v[194:197], v[60:63]
	v_mfma_f32_16x16x32_bf16 v[64:67], v[234:237], v[194:197], v[64:67]
	v_mfma_f32_16x16x32_bf16 v[36:39], v[230:233], v[152:155], v[36:39]
	v_mfma_f32_16x16x32_bf16 v[40:43], v[238:241], v[152:155], v[40:43]
	v_mfma_f32_16x16x32_bf16 v[44:47], v[230:233], v[160:163], v[44:47]
	v_mfma_f32_16x16x32_bf16 v[48:51], v[238:241], v[160:163], v[48:51]
	v_mfma_f32_16x16x32_bf16 v[52:55], v[230:233], v[190:193], v[52:55]
	v_mfma_f32_16x16x32_bf16 v[56:59], v[238:241], v[190:193], v[56:59]
	v_mfma_f32_16x16x32_bf16 v[60:63], v[230:233], v[198:201], v[60:63]
	v_mfma_f32_16x16x32_bf16 v[64:67], v[238:241], v[198:201], v[64:67]
	s_setprio 0
	s_barrier
	s_mov_b32 m0, s71
	v_lshl_add_u64 v[244:245], s[52:53], 0, v[180:181]
	ds_read_b128 v[148:151], v224 offset:16384
	ds_read_b128 v[152:155], v224 offset:17408
	ds_read_b128 v[156:159], v224 offset:18432
	ds_read_b128 v[160:163], v224 offset:19456
	ds_read_b128 v[186:189], v224 offset:20480
	ds_read_b128 v[190:193], v224 offset:21504
	ds_read_b128 v[194:197], v224 offset:22528
	ds_read_b128 v[198:201], v224 offset:23552
	global_load_lds_dwordx4 v[244:245], off
	v_lshl_add_u64 v[246:247], s[52:53], 0, v[176:177]
	s_mov_b32 m0, s72
	s_nop 0
	global_load_lds_dwordx4 v[246:247], off
	s_barrier
	s_waitcnt lgkmcnt(0)
	s_setprio 1
	v_mfma_f32_16x16x32_bf16 v[68:71], v[132:135], v[148:151], v[68:71]
	v_mfma_f32_16x16x32_bf16 v[72:75], v[140:143], v[148:151], v[72:75]
	v_mfma_f32_16x16x32_bf16 v[76:79], v[132:135], v[156:159], v[76:79]
	v_mfma_f32_16x16x32_bf16 v[80:83], v[140:143], v[156:159], v[80:83]
	v_mfma_f32_16x16x32_bf16 v[84:87], v[132:135], v[186:189], v[84:87]
	v_mfma_f32_16x16x32_bf16 v[88:91], v[140:143], v[186:189], v[88:91]
	v_mfma_f32_16x16x32_bf16 v[92:95], v[132:135], v[194:197], v[92:95]
	v_mfma_f32_16x16x32_bf16 v[96:99], v[140:143], v[194:197], v[96:99]
	v_mfma_f32_16x16x32_bf16 v[68:71], v[136:139], v[152:155], v[68:71]
	v_mfma_f32_16x16x32_bf16 v[72:75], v[144:147], v[152:155], v[72:75]
	v_mfma_f32_16x16x32_bf16 v[76:79], v[136:139], v[160:163], v[76:79]
	v_mfma_f32_16x16x32_bf16 v[80:83], v[144:147], v[160:163], v[80:83]
	v_mfma_f32_16x16x32_bf16 v[84:87], v[136:139], v[190:193], v[84:87]
	v_mfma_f32_16x16x32_bf16 v[88:91], v[144:147], v[190:193], v[88:91]
	v_mfma_f32_16x16x32_bf16 v[92:95], v[136:139], v[198:201], v[92:95]
	v_mfma_f32_16x16x32_bf16 v[96:99], v[144:147], v[198:201], v[96:99]
	s_setprio 0
	s_barrier
; #define PG8_STAGE(bufoff, gbase, voff) do { _Pragma("unroll") for (int _i = 0; _i < 2; ++_i) \
;         __builtin_amdgcn_global_load_lds((const unsigned*)((const char*)(gbase) + (voff)[_i]), (PG8_LAS unsigned*)(lds + (bufoff) + ldsw + _i * 8192), 16, 0, 0); } while (0)
; #define PG8_LDA(dst, b, h) do { _Pragma("unroll") for (int m = 0; m < 4; ++m) _Pragma("unroll") for (int k = 0; k < 2; ++k) dst[m][k] = *(const PG8_LAS bf16x8*)(lds + PG8_SA(b, h) + aoff + m * 2048 + k * 1024); } while (0)
; #define PG8_LDB(dst, b, h) do { _Pragma("unroll") for (int n = 0; n < 2; ++n) _Pragma("unroll") for (int k = 0; k < 2; ++k) dst[n][k] = *(const PG8_LAS bf16x8*)(lds + PG8_SB(b, h) + boff + n * 2048 + k * 1024); } while (0)
; #define PG8_MMA(ai, bj, At, Bt) do { __builtin_amdgcn_s_setprio(1); _Pragma("unroll") for (int m = 0; m < 4; ++m) _Pragma("unroll") for (int n = 0; n < 2; ++n) _Pragma("unroll") for (int k = 0; k < 2; ++k) \
;         acc[ai][bj][m][n] = __builtin_amdgcn_mfma_f32_16x16x32_bf16(Bt[n][k], At[m][k], acc[ai][bj][m][n], 0, 0, 0); __builtin_amdgcn_s_setprio(0); } while (0)
; #define PG8_WAIT_V(n) asm volatile("s_waitcnt vmcnt(" #n ")" ::: "memory")
; #define PG8_WAIT_L(n) asm volatile("s_waitcnt lgkmcnt(" #n ")" ::: "memory")
; #define PG8_BAR __builtin_amdgcn_s_barrier()
; #define PG8_SCHED __builtin_amdgcn_sched_barrier(0)
; template <class Epi, class Sched>
; __device__ __forceinline__ void gemm_phase(PG8_LAS unsigned char* lds, const Gemm g, const Sched& S, const Epi& E) {
;     ...
;             PG8_STAGE(PG8_SB(0, 1), b2 + hstep, voffB);
;             PG8_WAIT_V(6); PG8_BAR; PG8_MMA(1, 1, At, B1); PG8_BAR;
;             PG8_LDB(B0, 1, 0); PG8_SCHED; PG8_LDA(At, 1, 0); PG8_STAGE(PG8_SA(0, 1), a2 + hstep, voffA);
;             PG8_WAIT_L(8); PG8_BAR; PG8_WAIT_L(0); PG8_MMA(0, 0, At, B0); PG8_BAR; PG8_SCHED;
;             PG8_LDB(B1, 1, 1); PG8_STAGE(PG8_SB(1, 0), b3, voffB);
;             PG8_BAR; PG8_WAIT_L(0); PG8_MMA(0, 1, At, B1); PG8_BAR;
;             PG8_LDA(At, 1, 1); PG8_STAGE(PG8_SA(1, 0), a3, voffA);
	s_add_u32 s86, s6, 0x80000
	s_addc_u32 s87, s7, 0
	s_add_i32 s85, s88, s70
	v_lshl_add_u64 v[6:7], s[86:87], 0, v[178:179]
	s_mov_b32 m0, s85
	s_nop 0
	global_load_lds_dwordx4 v[6:7], off
	v_lshl_add_u64 v[6:7], s[86:87], 0, v[174:175]
	s_add_i32 m0, s85, 0x2000
	s_nop 0
	global_load_lds_dwordx4 v[6:7], off
	s_waitcnt vmcnt(6)
	s_barrier
	s_setprio 1
	v_mfma_f32_16x16x32_bf16 v[100:103], v[226:229], v[148:151], v[100:103]
	v_mfma_f32_16x16x32_bf16 v[104:107], v[234:237], v[148:151], v[104:107]
	v_mfma_f32_16x16x32_bf16 v[108:111], v[226:229], v[156:159], v[108:111]
	v_mfma_f32_16x16x32_bf16 v[112:115], v[234:237], v[156:159], v[112:115]
	v_mfma_f32_16x16x32_bf16 v[116:119], v[226:229], v[186:189], v[116:119]
	v_mfma_f32_16x16x32_bf16 v[120:123], v[234:237], v[186:189], v[120:123]
	v_mfma_f32_16x16x32_bf16 v[124:127], v[226:229], v[194:197], v[124:127]
	v_mfma_f32_16x16x32_bf16 v[128:131], v[234:237], v[194:197], v[128:131]
	v_mfma_f32_16x16x32_bf16 v[100:103], v[230:233], v[152:155], v[100:103]
	v_mfma_f32_16x16x32_bf16 v[104:107], v[238:241], v[152:155], v[104:107]
	v_mfma_f32_16x16x32_bf16 v[108:111], v[230:233], v[160:163], v[108:111]
	v_mfma_f32_16x16x32_bf16 v[112:115], v[238:241], v[160:163], v[112:115]
	v_mfma_f32_16x16x32_bf16 v[116:119], v[230:233], v[190:193], v[116:119]
	v_mfma_f32_16x16x32_bf16 v[120:123], v[238:241], v[190:193], v[120:123]
	v_mfma_f32_16x16x32_bf16 v[124:127], v[230:233], v[198:201], v[124:127]
	v_mfma_f32_16x16x32_bf16 v[128:131], v[238:241], v[198:201], v[128:131]
	s_setprio 0
	s_barrier
	s_add_i32 s85, 0, 0x18000
	v_add_u32_e32 v0, s85, v222
	ds_read_b128 v[132:135], v0
	ds_read_b128 v[136:139], v0 offset:1024
	ds_read_b128 v[140:143], v0 offset:2048
	ds_read_b128 v[144:147], v0 offset:3072
	s_add_u32 s52, s52, 0x80000
	s_addc_u32 s53, s53, 0
	s_mov_b32 m0, s73
	v_lshl_add_u64 v[6:7], s[52:53], 0, v[180:181]
	ds_read_b128 v[148:151], v224 offset:32768
	ds_read_b128 v[152:155], v224 offset:33792
	ds_read_b128 v[156:159], v224 offset:34816
	ds_read_b128 v[160:163], v224 offset:35840
	ds_read_b128 v[186:189], v224 offset:36864
	ds_read_b128 v[190:193], v224 offset:37888
	ds_read_b128 v[194:197], v224 offset:38912
	ds_read_b128 v[198:201], v224 offset:39936
	global_load_lds_dwordx4 v[6:7], off
	v_lshl_add_u64 v[6:7], s[52:53], 0, v[176:177]
	s_mov_b32 m0, s74
	s_nop 0
	global_load_lds_dwordx4 v[6:7], off
	s_waitcnt lgkmcnt(8)
	s_barrier
	s_waitcnt lgkmcnt(0)
	s_setprio 1
	v_mfma_f32_16x16x32_bf16 v[2:5], v[132:135], v[148:151], v[2:5]
	v_mfma_f32_16x16x32_bf16 v[8:11], v[140:143], v[148:151], v[8:11]
	v_mfma_f32_16x16x32_bf16 v[12:15], v[132:135], v[156:159], v[12:15]
	v_mfma_f32_16x16x32_bf16 v[16:19], v[140:143], v[156:159], v[16:19]
	v_mfma_f32_16x16x32_bf16 v[20:23], v[132:135], v[186:189], v[20:23]
	v_mfma_f32_16x16x32_bf16 v[24:27], v[140:143], v[186:189], v[24:27]
	v_mfma_f32_16x16x32_bf16 v[28:31], v[132:135], v[194:197], v[28:31]
	v_mfma_f32_16x16x32_bf16 v[32:35], v[140:143], v[194:197], v[32:35]
	v_mfma_f32_16x16x32_bf16 v[4:7], v[136:139], v[152:155], v[2:5]
	v_mfma_f32_16x16x32_bf16 v[8:11], v[144:147], v[152:155], v[8:11]
	v_mfma_f32_16x16x32_bf16 v[12:15], v[136:139], v[160:163], v[12:15]
	v_mfma_f32_16x16x32_bf16 v[16:19], v[144:147], v[160:163], v[16:19]
	v_mfma_f32_16x16x32_bf16 v[20:23], v[136:139], v[190:193], v[20:23]
	v_mfma_f32_16x16x32_bf16 v[24:27], v[144:147], v[190:193], v[24:27]
	v_mfma_f32_16x16x32_bf16 v[28:31], v[136:139], v[198:201], v[28:31]
	v_mfma_f32_16x16x32_bf16 v[32:35], v[144:147], v[198:201], v[32:35]
	s_setprio 0
	s_barrier
	s_add_i32 s52, 0, 0x1c000
	s_add_i32 s53, s85, s70
	v_add_u32_e32 v0, s52, v222
	v_lshl_add_u64 v[2:3], v[202:203], 0, s[8:9]
	s_mov_b32 m0, s53
	ds_read_b128 v[226:229], v0
	ds_read_b128 v[230:233], v0 offset:1024
	ds_read_b128 v[234:237], v0 offset:2048
	ds_read_b128 v[238:241], v0 offset:3072
	global_load_lds_dwordx4 v[2:3], off
	v_lshl_add_u64 v[2:3], v[242:243], 0, s[8:9]
	s_add_i32 m0, s53, 0x2000
	s_nop 0
	global_load_lds_dwordx4 v[2:3], off
	s_barrier
	s_waitcnt lgkmcnt(0)
	s_setprio 1
	v_mfma_f32_16x16x32_bf16 v[36:39], v[226:229], v[148:151], v[36:39]
	v_mfma_f32_16x16x32_bf16 v[40:43], v[234:237], v[148:151], v[40:43]
	v_mfma_f32_16x16x32_bf16 v[44:47], v[226:229], v[156:159], v[44:47]
	v_mfma_f32_16x16x32_bf16 v[48:51], v[234:237], v[156:159], v[48:51]
	v_mfma_f32_16x16x32_bf16 v[52:55], v[226:229], v[186:189], v[52:55]
	v_mfma_f32_16x16x32_bf16 v[56:59], v[234:237], v[186:189], v[56:59]
	v_mfma_f32_16x16x32_bf16 v[60:63], v[226:229], v[194:197], v[60:63]
	v_mfma_f32_16x16x32_bf16 v[64:67], v[234:237], v[194:197], v[64:67]
	v_mfma_f32_16x16x32_bf16 v[36:39], v[230:233], v[152:155], v[36:39]
	v_mfma_f32_16x16x32_bf16 v[40:43], v[238:241], v[152:155], v[40:43]
	v_mfma_f32_16x16x32_bf16 v[44:47], v[230:233], v[160:163], v[44:47]
	v_mfma_f32_16x16x32_bf16 v[48:51], v[238:241], v[160:163], v[48:51]
	v_mfma_f32_16x16x32_bf16 v[52:55], v[230:233], v[190:193], v[52:55]
	v_mfma_f32_16x16x32_bf16 v[56:59], v[238:241], v[190:193], v[56:59]
	v_mfma_f32_16x16x32_bf16 v[60:63], v[230:233], v[198:201], v[60:63]
	v_mfma_f32_16x16x32_bf16 v[64:67], v[238:241], v[198:201], v[64:67]
	s_setprio 0
	s_barrier
	s_mov_b32 m0, s75
	v_lshl_add_u64 v[2:3], v[244:245], 0, s[8:9]
	ds_read_b128 v[148:151], v224 offset:49152
	ds_read_b128 v[152:155], v224 offset:50176
	ds_read_b128 v[156:159], v224 offset:51200
	ds_read_b128 v[160:163], v224 offset:52224
	ds_read_b128 v[186:189], v224 offset:53248
	ds_read_b128 v[190:193], v224 offset:54272
	ds_read_b128 v[194:197], v224 offset:55296
	ds_read_b128 v[198:201], v224 offset:56320
	global_load_lds_dwordx4 v[2:3], off
	v_lshl_add_u64 v[2:3], v[246:247], 0, s[8:9]
	s_mov_b32 m0, s76
	s_nop 0
	global_load_lds_dwordx4 v[2:3], off
	s_barrier
; #define PG8_STAGE(bufoff, gbase, voff) do { _Pragma("unroll") for (int _i = 0; _i < 2; ++_i) \
;         __builtin_amdgcn_global_load_lds((const unsigned*)((const char*)(gbase) + (voff)[_i]), (PG8_LAS unsigned*)(lds + (bufoff) + ldsw + _i * 8192), 16, 0, 0); } while (0)
; #define PG8_WAIT_V(n) asm volatile("s_waitcnt vmcnt(" #n ")" ::: "memory")
; #define PG8_WAIT_L(n) asm volatile("s_waitcnt lgkmcnt(" #n ")" ::: "memory")
; #define PG8_BAR __builtin_amdgcn_s_barrier()
; template <class Epi, class Sched>
; __device__ __forceinline__ void gemm_phase(PG8_LAS unsigned char* lds, const Gemm g, const Sched& S, const Epi& E) {
;     ...
;             PG8_BAR; PG8_WAIT_L(0); PG8_MMA(1, 0, At, B0); PG8_BAR; PG8_SCHED;
;             PG8_STAGE(PG8_SB(1, 1), b3 + hstep, voffB);
;             PG8_WAIT_V(6); PG8_BAR; PG8_MMA(1, 1, At, B1); PG8_BAR;
;     __device__ __forceinline__ void operator()(f32x4 (&acc)[2][2][4][2], const Unit& u, int wr, int wc, int fr, int fq) const {
;         const int row0 = u.pm * 256 + wr * 64 + fr, col0 = u.pn * 256 + wc * 32 + 8 * fq;
;         if (u.seg == 0) return;
;         if (u.seg < 3) {
;             const int br = u.seg - 1;
; #pragma unroll
;             for (int ai = 0; ai < 2; ++ai)
; #pragma unroll
;                 for (int m = 0; m < 4; ++m) { const bf16* zp = Z + (size_t)T * OFF_GATE + (size_t)(row0 + ai * 128 + m * 16) * 3072 + br * 1024 + col0;
; #pragma unroll
;                     for (int bj = 0; bj < 2; ++bj) { const v4u gc = *(const v4u*)(zp + bj * 128), gn = *(const v4u*)(zp + 1024 + bj * 128);
;                         f32x4 r0, r1;
;     ...
;                         r0[0] = RAT(bflo(gn.x), bflo(gc.x)); r0[1] = RAT(bfhi(gn.x), bfhi(gc.x)); r0[2] = RAT(bflo(gn.y), bflo(gc.y)); r0[3] = RAT(bfhi(gn.y), bfhi(gc.y));
;                         r1[0] = RAT(bflo(gn.z), bflo(gc.z)); r1[1] = RAT(bfhi(gn.z), bfhi(gc.z)); r1[2] = RAT(bflo(gn.w), bflo(gc.w)); r1[3] = RAT(bfhi(gn.w), bfhi(gc.w));
;     ...
;                         acc[ai][bj][m][0] *= r0; acc[ai][bj][m][1] *= r1; } }
;             return;
;         }
; #pragma unroll
;         for (int ai = 0; ai < 2; ++ai) {
;             v4u gq[4][2];
; #pragma unroll
;             for (int m = 0; m < 4; ++m)
; #pragma unroll
;                 for (int bj = 0; bj < 2; ++bj) gq[m][bj] = *(const v4u*)(Z + (size_t)T * OFF_GATE + (size_t)(row0 + ai * 128 + m * 16) * 3072 + 2048 + col0 + bj * 128);
	s_waitcnt lgkmcnt(0)
	s_setprio 1
	v_mfma_f32_16x16x32_bf16 v[68:71], v[132:135], v[148:151], v[68:71]
	v_mfma_f32_16x16x32_bf16 v[72:75], v[140:143], v[148:151], v[72:75]
	v_mfma_f32_16x16x32_bf16 v[76:79], v[132:135], v[156:159], v[76:79]
	v_mfma_f32_16x16x32_bf16 v[80:83], v[140:143], v[156:159], v[80:83]
	v_mfma_f32_16x16x32_bf16 v[84:87], v[132:135], v[186:189], v[84:87]
	v_mfma_f32_16x16x32_bf16 v[88:91], v[140:143], v[186:189], v[88:91]
	v_mfma_f32_16x16x32_bf16 v[92:95], v[132:135], v[194:197], v[92:95]
	v_mfma_f32_16x16x32_bf16 v[96:99], v[140:143], v[194:197], v[96:99]
	v_mfma_f32_16x16x32_bf16 v[68:71], v[136:139], v[152:155], v[68:71]
	v_mfma_f32_16x16x32_bf16 v[72:75], v[144:147], v[152:155], v[72:75]
	v_mfma_f32_16x16x32_bf16 v[76:79], v[136:139], v[160:163], v[76:79]
	v_mfma_f32_16x16x32_bf16 v[80:83], v[144:147], v[160:163], v[80:83]
	v_mfma_f32_16x16x32_bf16 v[84:87], v[136:139], v[190:193], v[84:87]
	v_mfma_f32_16x16x32_bf16 v[88:91], v[144:147], v[190:193], v[88:91]
	v_mfma_f32_16x16x32_bf16 v[92:95], v[136:139], v[198:201], v[92:95]
	v_mfma_f32_16x16x32_bf16 v[96:99], v[144:147], v[198:201], v[96:99]
	s_setprio 0
	s_barrier
	s_add_u32 s6, s6, 0x80080
	s_addc_u32 s7, s7, 0
	s_add_i32 s52, s52, s70
	v_lshl_add_u64 v[2:3], s[6:7], 0, v[178:179]
	s_mov_b32 m0, s52
	s_nop 0
	global_load_lds_dwordx4 v[2:3], off
	v_lshl_add_u64 v[2:3], s[6:7], 0, v[174:175]
	s_add_i32 m0, s52, 0x2000
	s_nop 0
	global_load_lds_dwordx4 v[2:3], off
	s_waitcnt vmcnt(6)
	s_barrier
	s_setprio 1
	v_mfma_f32_16x16x32_bf16 v[100:103], v[226:229], v[148:151], v[100:103]
	v_mfma_f32_16x16x32_bf16 v[104:107], v[234:237], v[148:151], v[104:107]
	v_mfma_f32_16x16x32_bf16 v[108:111], v[226:229], v[156:159], v[108:111]
	v_mfma_f32_16x16x32_bf16 v[112:115], v[234:237], v[156:159], v[112:115]
	v_mfma_f32_16x16x32_bf16 v[116:119], v[226:229], v[186:189], v[116:119]
	v_mfma_f32_16x16x32_bf16 v[120:123], v[234:237], v[186:189], v[120:123]
	v_mfma_f32_16x16x32_bf16 v[124:127], v[226:229], v[194:197], v[124:127]
	v_mfma_f32_16x16x32_bf16 v[128:131], v[234:237], v[194:197], v[128:131]
	v_mfma_f32_16x16x32_bf16 v[100:103], v[230:233], v[152:155], v[100:103]
	v_mfma_f32_16x16x32_bf16 v[104:107], v[238:241], v[152:155], v[104:107]
	v_mfma_f32_16x16x32_bf16 v[108:111], v[230:233], v[160:163], v[108:111]
	v_mfma_f32_16x16x32_bf16 v[112:115], v[238:241], v[160:163], v[112:115]
	v_mfma_f32_16x16x32_bf16 v[116:119], v[230:233], v[190:193], v[116:119]
	v_mfma_f32_16x16x32_bf16 v[120:123], v[238:241], v[190:193], v[120:123]
	v_mfma_f32_16x16x32_bf16 v[124:127], v[230:233], v[198:201], v[124:127]
	v_mfma_f32_16x16x32_bf16 v[128:131], v[238:241], v[198:201], v[128:131]
	s_setprio 0
	s_add_i32 s84, s84, 2
	s_add_u32 s50, s50, 0x100
	s_addc_u32 s51, s51, 0
	s_add_u32 s82, s82, 0x100
	s_addc_u32 s83, s83, 0
	s_cmp_gt_u32 s84, 5
	s_barrier
	s_cbranch_scc0 .LBB0_472
	s_cmp_eq_u32 s78, 0
	s_cbranch_scc1 .LBB0_478
	v_lshl_add_u32 v2, s80, 8, v221
	v_lshl_or_b32 v192, s79, 8, v223
	s_mov_b64 s[6:7], -1
	s_cmp_lt_i32 s78, 3
	v_ashrrev_i32_e32 v193, 31, v192
	v_or_b32_e32 v190, 16, v2
	v_or_b32_e32 v188, 32, v2
	v_or_b32_e32 v186, 48, v2
	s_cbranch_scc1 .LBB0_476
	v_mov_b64_e32 v[196:197], s[46:47]
	v_mad_i64_i32 v[132:133], s[6:7], v2, s68, v[196:197]
	v_lshlrev_b64 v[194:195], 1, v[192:193]
	v_lshl_add_u64 v[132:133], v[132:133], 0, v[194:195]
	s_mov_b64 s[50:51], 0x14001000
	v_lshl_add_u64 v[134:135], v[132:133], 0, s[50:51]
	v_add_co_u32_e32 v132, vcc, 0x14001000, v132
	v_ashrrev_i32_e32 v3, 31, v2
	s_nop 0
	v_addc_co_u32_e32 v133, vcc, 0, v133, vcc
	global_load_dwordx4 v[160:163], v[132:133], off
	global_load_dwordx4 v[156:159], v[134:135], off offset:256
	v_mad_i64_i32 v[132:133], s[6:7], v190, s68, v[196:197]
	v_lshl_add_u64 v[132:133], v[132:133], 0, v[194:195]
	v_lshl_add_u64 v[134:135], v[132:133], 0, s[50:51]
	v_add_co_u32_e32 v132, vcc, 0x14001000, v132
	v_lshlrev_b64 v[198:199], 11, v[2:3]
	s_nop 0
	v_addc_co_u32_e32 v133, vcc, 0, v133, vcc
	global_load_dwordx4 v[152:155], v[132:133], off
	global_load_dwordx4 v[148:151], v[134:135], off offset:256
	v_mad_i64_i32 v[132:133], s[6:7], v188, s68, v[196:197]
	v_lshl_add_u64 v[132:133], v[132:133], 0, v[194:195]
	v_lshl_add_u64 v[134:135], v[132:133], 0, s[50:51]
	v_add_co_u32_e32 v132, vcc, 0x14001000, v132
	v_lshl_add_u64 v[198:199], s[56:57], 0, v[198:199]
	s_nop 0
	v_addc_co_u32_e32 v133, vcc, 0, v133, vcc
	global_load_dwordx4 v[144:147], v[132:133], off
	global_load_dwordx4 v[140:143], v[134:135], off offset:256
	v_mad_i64_i32 v[132:133], s[6:7], v186, s68, v[196:197]
	v_lshl_add_u64 v[132:133], v[132:133], 0, v[194:195]
	v_lshl_add_u64 v[134:135], v[132:133], 0, s[50:51]
	v_add_co_u32_e32 v132, vcc, 0x14001000, v132
	v_lshl_add_u64 v[198:199], v[198:199], 0, v[194:195]
	s_nop 0
	v_addc_co_u32_e32 v133, vcc, 0, v133, vcc
	global_load_dwordx4 v[136:139], v[132:133], off
	s_nop 0
	global_load_dwordx4 v[132:135], v[134:135], off offset:256
	v_ashrrev_i32_e32 v191, 31, v190
	v_ashrrev_i32_e32 v189, 31, v188
	v_ashrrev_i32_e32 v187, 31, v186
	v_add_u32_e32 v226, 0x80, v2
	s_mov_b32 s19, 0x14001000
	v_add_u32_e32 v202, 0x90, v2
	v_ashrrev_i32_e32 v227, 31, v226
	v_ashrrev_i32_e32 v203, 31, v202
	s_waitcnt vmcnt(0)
; __device__ __forceinline__ unsigned pk2(float lo, float hi) { v2f v = {lo, hi}; return __builtin_bit_cast(unsigned, __builtin_convertvector(v, v2bf)); }
; __device__ __forceinline__ float bflo(unsigned u) { return __uint_as_float(u << 16); }
; __device__ __forceinline__ float bfhi(unsigned u) { return __uint_as_float(u & 0xffff0000u); }
; #define SG(a_, g_) ((a_) * __builtin_amdgcn_rcpf(einv(g_)))
;     static __device__ __forceinline__ float einv(float g) { return 1.f + __expf(fminf(-g, 30.f)); }
;     __device__ __forceinline__ void operator()(f32x4 (&acc)[2][2][4][2], const Unit& u, int wr, int wc, int fr, int fq) const {
;     ...
;             for (int m = 0; m < 4; ++m) { const int row = row0 + ai * 128 + m * 16;
; #pragma unroll
;                 for (int bj = 0; bj < 2; ++bj) { const int col = col0 + bj * 128;
;                     const v4u gw = gq[m][bj];
;                     const f32x4 a0 = acc[ai][bj][m][0], a1 = acc[ai][bj][m][1];
;     ...
;                     v4u w; w.x = pk2(SG(a0[0], bflo(gw.x)), SG(a0[1], bfhi(gw.x))); w.y = pk2(SG(a0[2], bflo(gw.y)), SG(a0[3], bfhi(gw.y)));
;                     w.z = pk2(SG(a1[0], bflo(gw.z)), SG(a1[1], bfhi(gw.z))); w.w = pk2(SG(a1[2], bflo(gw.w)), SG(a1[3], bfhi(gw.w)));
;     ...
;                     *(v4u*)(MB + (size_t)row * 1024 + col) = w; } }
;         }
	v_lshlrev_b32_e32 v0, 16, v160
	v_max_f32_e64 v0, -v0, -v0
	v_min_f32_e32 v0, 0x41f00000, v0
	v_mul_f32_e32 v0, 0x3fb8aa3b, v0
	v_exp_f32_e32 v0, v0
	s_nop 0
	v_add_f32_e32 v0, 1.0, v0
	v_rcp_f32_e32 v200, v0
	v_and_b32_e32 v0, 0xffff0000, v160
	v_max_f32_e64 v0, -v0, -v0
	v_min_f32_e32 v0, 0x41f00000, v0
	v_mul_f32_e32 v0, 0x3fb8aa3b, v0
	v_exp_f32_e32 v0, v0
	s_nop 0
	v_add_f32_e32 v0, 1.0, v0
	v_rcp_f32_e32 v201, v0
	v_lshlrev_b32_e32 v0, 16, v161
	v_max_f32_e64 v0, -v0, -v0
	v_min_f32_e32 v0, 0x41f00000, v0
	v_mul_f32_e32 v0, 0x3fb8aa3b, v0
	v_exp_f32_e32 v0, v0
	v_pk_mul_f32 v[200:201], v[4:5], v[200:201]
	v_add_f32_e32 v0, 1.0, v0
	v_cvt_pk_bf16_f32 v160, v200, v201
	v_rcp_f32_e32 v200, v0
	v_and_b32_e32 v0, 0xffff0000, v161
	v_max_f32_e64 v0, -v0, -v0
	v_min_f32_e32 v0, 0x41f00000, v0
	v_mul_f32_e32 v0, 0x3fb8aa3b, v0
	v_exp_f32_e32 v0, v0
	s_nop 0
	v_add_f32_e32 v0, 1.0, v0
	v_rcp_f32_e32 v201, v0
	v_lshlrev_b32_e32 v0, 16, v162
	v_max_f32_e64 v0, -v0, -v0
	v_min_f32_e32 v0, 0x41f00000, v0
	v_mul_f32_e32 v0, 0x3fb8aa3b, v0
	v_exp_f32_e32 v0, v0
	v_pk_mul_f32 v[200:201], v[6:7], v[200:201]
	v_add_f32_e32 v0, 1.0, v0
	v_cvt_pk_bf16_f32 v161, v200, v201
	v_rcp_f32_e32 v200, v0
	v_and_b32_e32 v0, 0xffff0000, v162
	v_max_f32_e64 v0, -v0, -v0
	v_min_f32_e32 v0, 0x41f00000, v0
	v_mul_f32_e32 v0, 0x3fb8aa3b, v0
	v_exp_f32_e32 v0, v0
	s_nop 0
	v_add_f32_e32 v0, 1.0, v0
	v_rcp_f32_e32 v201, v0
	v_lshlrev_b32_e32 v0, 16, v163
	v_max_f32_e64 v0, -v0, -v0
	v_min_f32_e32 v0, 0x41f00000, v0
	v_mul_f32_e32 v0, 0x3fb8aa3b, v0
	v_exp_f32_e32 v0, v0
	v_pk_mul_f32 v[200:201], v[8:9], v[200:201]
	v_add_f32_e32 v0, 1.0, v0
	v_cvt_pk_bf16_f32 v162, v200, v201
	v_rcp_f32_e32 v200, v0
	v_and_b32_e32 v0, 0xffff0000, v163
	v_max_f32_e64 v0, -v0, -v0
	v_min_f32_e32 v0, 0x41f00000, v0
	v_mul_f32_e32 v0, 0x3fb8aa3b, v0
	v_exp_f32_e32 v0, v0
	s_nop 0
	v_add_f32_e32 v0, 1.0, v0
	v_rcp_f32_e32 v201, v0
	v_lshlrev_b32_e32 v0, 16, v156
	v_max_f32_e64 v0, -v0, -v0
	v_min_f32_e32 v0, 0x41f00000, v0
	v_mul_f32_e32 v0, 0x3fb8aa3b, v0
	v_exp_f32_e32 v0, v0
	v_pk_mul_f32 v[200:201], v[10:11], v[200:201]
	v_add_f32_e32 v0, 1.0, v0
	v_cvt_pk_bf16_f32 v163, v200, v201
	global_store_dwordx4 v[198:199], v[160:163], off
	v_add_u32_e32 v200, 0xa0, v2
	v_ashrrev_i32_e32 v201, 31, v200
	v_rcp_f32_e32 v160, v0
	v_and_b32_e32 v0, 0xffff0000, v156
	v_max_f32_e64 v0, -v0, -v0
	v_min_f32_e32 v0, 0x41f00000, v0
	v_mul_f32_e32 v0, 0x3fb8aa3b, v0
	v_exp_f32_e32 v0, v0
	s_nop 0
	v_add_f32_e32 v0, 1.0, v0
	v_rcp_f32_e32 v161, v0
	v_lshlrev_b32_e32 v0, 16, v157
	v_max_f32_e64 v0, -v0, -v0
	v_min_f32_e32 v0, 0x41f00000, v0
	v_mul_f32_e32 v0, 0x3fb8aa3b, v0
	v_exp_f32_e32 v0, v0
	v_pk_mul_f32 v[160:161], v[36:37], v[160:161]
	v_add_f32_e32 v0, 1.0, v0
	v_cvt_pk_bf16_f32 v156, v160, v161
	v_rcp_f32_e32 v160, v0
	v_and_b32_e32 v0, 0xffff0000, v157
	v_max_f32_e64 v0, -v0, -v0
	v_min_f32_e32 v0, 0x41f00000, v0
	v_mul_f32_e32 v0, 0x3fb8aa3b, v0
	v_exp_f32_e32 v0, v0
	s_nop 0
	v_add_f32_e32 v0, 1.0, v0
	v_rcp_f32_e32 v161, v0
	v_lshlrev_b32_e32 v0, 16, v158
	v_max_f32_e64 v0, -v0, -v0
	v_min_f32_e32 v0, 0x41f00000, v0
	v_mul_f32_e32 v0, 0x3fb8aa3b, v0
	v_exp_f32_e32 v0, v0
	v_pk_mul_f32 v[160:161], v[38:39], v[160:161]
	v_add_f32_e32 v0, 1.0, v0
	v_cvt_pk_bf16_f32 v157, v160, v161
	v_rcp_f32_e32 v160, v0
	v_and_b32_e32 v0, 0xffff0000, v158
	v_max_f32_e64 v0, -v0, -v0
	v_min_f32_e32 v0, 0x41f00000, v0
	v_mul_f32_e32 v0, 0x3fb8aa3b, v0
	v_exp_f32_e32 v0, v0
	s_nop 0
	v_add_f32_e32 v0, 1.0, v0
	v_rcp_f32_e32 v161, v0
	v_lshlrev_b32_e32 v0, 16, v159
	v_max_f32_e64 v0, -v0, -v0
	v_min_f32_e32 v0, 0x41f00000, v0
	v_mul_f32_e32 v0, 0x3fb8aa3b, v0
	v_exp_f32_e32 v0, v0
	v_pk_mul_f32 v[160:161], v[40:41], v[160:161]
	v_add_f32_e32 v0, 1.0, v0
	v_cvt_pk_bf16_f32 v158, v160, v161
	v_rcp_f32_e32 v160, v0
	v_and_b32_e32 v0, 0xffff0000, v159
	v_max_f32_e64 v0, -v0, -v0
	v_min_f32_e32 v0, 0x41f00000, v0
	v_mul_f32_e32 v0, 0x3fb8aa3b, v0
	v_exp_f32_e32 v0, v0
	s_nop 0
	v_add_f32_e32 v0, 1.0, v0
	v_rcp_f32_e32 v161, v0
	v_lshlrev_b32_e32 v0, 16, v152
	v_max_f32_e64 v0, -v0, -v0
	v_min_f32_e32 v0, 0x41f00000, v0
	v_mul_f32_e32 v0, 0x3fb8aa3b, v0
	v_exp_f32_e32 v0, v0
	v_pk_mul_f32 v[160:161], v[42:43], v[160:161]
	v_add_f32_e32 v0, 1.0, v0
	v_cvt_pk_bf16_f32 v159, v160, v161
	global_store_dwordx4 v[198:199], v[156:159], off offset:256
	v_add_u32_e32 v198, 0xb0, v2
	v_ashrrev_i32_e32 v199, 31, v198
	v_rcp_f32_e32 v158, v0
	v_and_b32_e32 v0, 0xffff0000, v152
	v_max_f32_e64 v0, -v0, -v0
	v_min_f32_e32 v0, 0x41f00000, v0
	v_mul_f32_e32 v0, 0x3fb8aa3b, v0
	v_exp_f32_e32 v0, v0
	v_lshlrev_b64 v[156:157], 11, v[190:191]
	v_lshl_add_u64 v[156:157], s[56:57], 0, v[156:157]
	v_lshl_add_u64 v[156:157], v[156:157], 0, v[194:195]
	v_add_f32_e32 v0, 1.0, v0
	v_rcp_f32_e32 v159, v0
	v_lshlrev_b32_e32 v0, 16, v153
	v_max_f32_e64 v0, -v0, -v0
	v_min_f32_e32 v0, 0x41f00000, v0
	v_mul_f32_e32 v0, 0x3fb8aa3b, v0
	v_exp_f32_e32 v0, v0
	v_pk_mul_f32 v[158:159], v[12:13], v[158:159]
	v_add_f32_e32 v0, 1.0, v0
	v_cvt_pk_bf16_f32 v152, v158, v159
	v_rcp_f32_e32 v158, v0
	v_and_b32_e32 v0, 0xffff0000, v153
	v_max_f32_e64 v0, -v0, -v0
	v_min_f32_e32 v0, 0x41f00000, v0
	v_mul_f32_e32 v0, 0x3fb8aa3b, v0
	v_exp_f32_e32 v0, v0
	s_nop 0
	v_add_f32_e32 v0, 1.0, v0
	v_rcp_f32_e32 v159, v0
	v_lshlrev_b32_e32 v0, 16, v154
	v_max_f32_e64 v0, -v0, -v0
	v_min_f32_e32 v0, 0x41f00000, v0
	v_mul_f32_e32 v0, 0x3fb8aa3b, v0
	v_exp_f32_e32 v0, v0
	v_pk_mul_f32 v[158:159], v[14:15], v[158:159]
	v_add_f32_e32 v0, 1.0, v0
	v_cvt_pk_bf16_f32 v153, v158, v159
	v_rcp_f32_e32 v158, v0
	v_and_b32_e32 v0, 0xffff0000, v154
	v_max_f32_e64 v0, -v0, -v0
; __device__ __forceinline__ unsigned pk2(float lo, float hi) { v2f v = {lo, hi}; return __builtin_bit_cast(unsigned, __builtin_convertvector(v, v2bf)); }
; __device__ __forceinline__ float bflo(unsigned u) { return __uint_as_float(u << 16); }
; __device__ __forceinline__ float bfhi(unsigned u) { return __uint_as_float(u & 0xffff0000u); }
; #define SG(a_, g_) ((a_) * __builtin_amdgcn_rcpf(einv(g_)))
;     __device__ __forceinline__ void operator()(f32x4 (&acc)[2][2][4][2], const Unit& u, int wr, int wc, int fr, int fq) const {
;     ...
; #pragma unroll
;         for (int ai = 0; ai < 2; ++ai) {
;             v4u gq[4][2];
; #pragma unroll
;             for (int m = 0; m < 4; ++m)
; #pragma unroll
;                 for (int bj = 0; bj < 2; ++bj) gq[m][bj] = *(const v4u*)(Z + (size_t)T * OFF_GATE + (size_t)(row0 + ai * 128 + m * 16) * 3072 + 2048 + col0 + bj * 128);
; #pragma unroll
;             for (int m = 0; m < 4; ++m) { const int row = row0 + ai * 128 + m * 16;
; #pragma unroll
;                 for (int bj = 0; bj < 2; ++bj) { const int col = col0 + bj * 128;
;                     const v4u gw = gq[m][bj];
;                     const f32x4 a0 = acc[ai][bj][m][0], a1 = acc[ai][bj][m][1];
;     ...
;                     v4u w; w.x = pk2(SG(a0[0], bflo(gw.x)), SG(a0[1], bfhi(gw.x))); w.y = pk2(SG(a0[2], bflo(gw.y)), SG(a0[3], bfhi(gw.y)));
;                     w.z = pk2(SG(a1[0], bflo(gw.z)), SG(a1[1], bfhi(gw.z))); w.w = pk2(SG(a1[2], bflo(gw.w)), SG(a1[3], bfhi(gw.w)));
;     ...
;                     *(v4u*)(MB + (size_t)row * 1024 + col) = w; } }
;         }
	v_min_f32_e32 v0, 0x41f00000, v0
	v_mul_f32_e32 v0, 0x3fb8aa3b, v0
	v_exp_f32_e32 v0, v0
	s_nop 0
	v_add_f32_e32 v0, 1.0, v0
	v_rcp_f32_e32 v159, v0
	v_lshlrev_b32_e32 v0, 16, v155
	v_max_f32_e64 v0, -v0, -v0
	v_min_f32_e32 v0, 0x41f00000, v0
	v_mul_f32_e32 v0, 0x3fb8aa3b, v0
	v_exp_f32_e32 v0, v0
	v_pk_mul_f32 v[158:159], v[16:17], v[158:159]
	v_add_f32_e32 v0, 1.0, v0
	v_cvt_pk_bf16_f32 v154, v158, v159
	v_rcp_f32_e32 v158, v0
	v_and_b32_e32 v0, 0xffff0000, v155
	v_max_f32_e64 v0, -v0, -v0
	v_min_f32_e32 v0, 0x41f00000, v0
	v_mul_f32_e32 v0, 0x3fb8aa3b, v0
	v_exp_f32_e32 v0, v0
	s_nop 0
	v_add_f32_e32 v0, 1.0, v0
	v_rcp_f32_e32 v159, v0
	v_lshlrev_b32_e32 v0, 16, v148
	v_max_f32_e64 v0, -v0, -v0
	v_min_f32_e32 v0, 0x41f00000, v0
	v_mul_f32_e32 v0, 0x3fb8aa3b, v0
	v_exp_f32_e32 v0, v0
	v_pk_mul_f32 v[158:159], v[18:19], v[158:159]
	v_add_f32_e32 v0, 1.0, v0
	v_cvt_pk_bf16_f32 v155, v158, v159
	global_store_dwordx4 v[156:157], v[152:155], off
	s_nop 1
	v_rcp_f32_e32 v152, v0
	v_and_b32_e32 v0, 0xffff0000, v148
	v_max_f32_e64 v0, -v0, -v0
	v_min_f32_e32 v0, 0x41f00000, v0
	v_mul_f32_e32 v0, 0x3fb8aa3b, v0
	v_exp_f32_e32 v0, v0
	s_nop 0
	v_add_f32_e32 v0, 1.0, v0
	v_rcp_f32_e32 v153, v0
	v_lshlrev_b32_e32 v0, 16, v149
	v_max_f32_e64 v0, -v0, -v0
	v_min_f32_e32 v0, 0x41f00000, v0
	v_mul_f32_e32 v0, 0x3fb8aa3b, v0
	v_exp_f32_e32 v0, v0
	v_pk_mul_f32 v[152:153], v[44:45], v[152:153]
	v_add_f32_e32 v0, 1.0, v0
	v_cvt_pk_bf16_f32 v148, v152, v153
	v_rcp_f32_e32 v152, v0
	v_and_b32_e32 v0, 0xffff0000, v149
	v_max_f32_e64 v0, -v0, -v0
	v_min_f32_e32 v0, 0x41f00000, v0
	v_mul_f32_e32 v0, 0x3fb8aa3b, v0
	v_exp_f32_e32 v0, v0
	s_nop 0
	v_add_f32_e32 v0, 1.0, v0
	v_rcp_f32_e32 v153, v0
	v_lshlrev_b32_e32 v0, 16, v150
	v_max_f32_e64 v0, -v0, -v0
	v_min_f32_e32 v0, 0x41f00000, v0
	v_mul_f32_e32 v0, 0x3fb8aa3b, v0
	v_exp_f32_e32 v0, v0
	v_pk_mul_f32 v[152:153], v[46:47], v[152:153]
	v_add_f32_e32 v0, 1.0, v0
	v_cvt_pk_bf16_f32 v149, v152, v153
	v_rcp_f32_e32 v152, v0
	v_and_b32_e32 v0, 0xffff0000, v150
	v_max_f32_e64 v0, -v0, -v0
	v_min_f32_e32 v0, 0x41f00000, v0
	v_mul_f32_e32 v0, 0x3fb8aa3b, v0
	v_exp_f32_e32 v0, v0
	s_nop 0
	v_add_f32_e32 v0, 1.0, v0
	v_rcp_f32_e32 v153, v0
	v_lshlrev_b32_e32 v0, 16, v151
	v_max_f32_e64 v0, -v0, -v0
	v_min_f32_e32 v0, 0x41f00000, v0
	v_mul_f32_e32 v0, 0x3fb8aa3b, v0
	v_exp_f32_e32 v0, v0
	v_pk_mul_f32 v[152:153], v[48:49], v[152:153]
	v_add_f32_e32 v0, 1.0, v0
	v_cvt_pk_bf16_f32 v150, v152, v153
	v_rcp_f32_e32 v152, v0
	v_and_b32_e32 v0, 0xffff0000, v151
	v_max_f32_e64 v0, -v0, -v0
	v_min_f32_e32 v0, 0x41f00000, v0
	v_mul_f32_e32 v0, 0x3fb8aa3b, v0
	v_exp_f32_e32 v0, v0
	s_nop 0
	v_add_f32_e32 v0, 1.0, v0
	v_rcp_f32_e32 v153, v0
	v_lshlrev_b32_e32 v0, 16, v144
	v_max_f32_e64 v0, -v0, -v0
	v_min_f32_e32 v0, 0x41f00000, v0
	v_mul_f32_e32 v0, 0x3fb8aa3b, v0
	v_exp_f32_e32 v0, v0
	v_pk_mul_f32 v[152:153], v[50:51], v[152:153]
	v_add_f32_e32 v0, 1.0, v0
	v_cvt_pk_bf16_f32 v151, v152, v153
	global_store_dwordx4 v[156:157], v[148:151], off offset:256
	s_nop 1
	v_rcp_f32_e32 v150, v0
	v_and_b32_e32 v0, 0xffff0000, v144
	v_max_f32_e64 v0, -v0, -v0
	v_min_f32_e32 v0, 0x41f00000, v0
	v_mul_f32_e32 v0, 0x3fb8aa3b, v0
	v_exp_f32_e32 v0, v0
	v_lshlrev_b64 v[148:149], 11, v[188:189]
	v_lshl_add_u64 v[148:149], s[56:57], 0, v[148:149]
	v_lshl_add_u64 v[148:149], v[148:149], 0, v[194:195]
	v_add_f32_e32 v0, 1.0, v0
	v_rcp_f32_e32 v151, v0
	v_lshlrev_b32_e32 v0, 16, v145
	v_max_f32_e64 v0, -v0, -v0
	v_min_f32_e32 v0, 0x41f00000, v0
	v_mul_f32_e32 v0, 0x3fb8aa3b, v0
	v_exp_f32_e32 v0, v0
	v_pk_mul_f32 v[150:151], v[20:21], v[150:151]
	v_add_f32_e32 v0, 1.0, v0
	v_cvt_pk_bf16_f32 v144, v150, v151
	v_rcp_f32_e32 v150, v0
	v_and_b32_e32 v0, 0xffff0000, v145
	v_max_f32_e64 v0, -v0, -v0
	v_min_f32_e32 v0, 0x41f00000, v0
	v_mul_f32_e32 v0, 0x3fb8aa3b, v0
	v_exp_f32_e32 v0, v0
	s_nop 0
	v_add_f32_e32 v0, 1.0, v0
	v_rcp_f32_e32 v151, v0
	v_lshlrev_b32_e32 v0, 16, v146
	v_max_f32_e64 v0, -v0, -v0
	v_min_f32_e32 v0, 0x41f00000, v0
	v_mul_f32_e32 v0, 0x3fb8aa3b, v0
	v_exp_f32_e32 v0, v0
	v_pk_mul_f32 v[150:151], v[22:23], v[150:151]
	v_add_f32_e32 v0, 1.0, v0
	v_cvt_pk_bf16_f32 v145, v150, v151
	v_rcp_f32_e32 v150, v0
	v_and_b32_e32 v0, 0xffff0000, v146
	v_max_f32_e64 v0, -v0, -v0
	v_min_f32_e32 v0, 0x41f00000, v0
	v_mul_f32_e32 v0, 0x3fb8aa3b, v0
	v_exp_f32_e32 v0, v0
	s_nop 0
	v_add_f32_e32 v0, 1.0, v0
	v_rcp_f32_e32 v151, v0
	v_lshlrev_b32_e32 v0, 16, v147
	v_max_f32_e64 v0, -v0, -v0
	v_min_f32_e32 v0, 0x41f00000, v0
	v_mul_f32_e32 v0, 0x3fb8aa3b, v0
	v_exp_f32_e32 v0, v0
	v_pk_mul_f32 v[150:151], v[24:25], v[150:151]
	v_add_f32_e32 v0, 1.0, v0
	v_cvt_pk_bf16_f32 v146, v150, v151
	v_rcp_f32_e32 v150, v0
	v_and_b32_e32 v0, 0xffff0000, v147
	v_max_f32_e64 v0, -v0, -v0
	v_min_f32_e32 v0, 0x41f00000, v0
	v_mul_f32_e32 v0, 0x3fb8aa3b, v0
	v_exp_f32_e32 v0, v0
	s_nop 0
	v_add_f32_e32 v0, 1.0, v0
	v_rcp_f32_e32 v151, v0
	v_lshlrev_b32_e32 v0, 16, v140
	v_max_f32_e64 v0, -v0, -v0
	v_min_f32_e32 v0, 0x41f00000, v0
	v_mul_f32_e32 v0, 0x3fb8aa3b, v0
	v_exp_f32_e32 v0, v0
	v_pk_mul_f32 v[150:151], v[26:27], v[150:151]
	v_add_f32_e32 v0, 1.0, v0
	v_cvt_pk_bf16_f32 v147, v150, v151
	global_store_dwordx4 v[148:149], v[144:147], off
	s_nop 1
	v_rcp_f32_e32 v144, v0
	v_and_b32_e32 v0, 0xffff0000, v140
	v_max_f32_e64 v0, -v0, -v0
	v_min_f32_e32 v0, 0x41f00000, v0
	v_mul_f32_e32 v0, 0x3fb8aa3b, v0
	v_exp_f32_e32 v0, v0
	s_nop 0
	v_add_f32_e32 v0, 1.0, v0
	v_rcp_f32_e32 v145, v0
	v_lshlrev_b32_e32 v0, 16, v141
	v_max_f32_e64 v0, -v0, -v0
	v_min_f32_e32 v0, 0x41f00000, v0
	v_mul_f32_e32 v0, 0x3fb8aa3b, v0
	v_exp_f32_e32 v0, v0
	v_pk_mul_f32 v[144:145], v[52:53], v[144:145]
; __device__ __forceinline__ unsigned pk2(float lo, float hi) { v2f v = {lo, hi}; return __builtin_bit_cast(unsigned, __builtin_convertvector(v, v2bf)); }
; __device__ __forceinline__ float bflo(unsigned u) { return __uint_as_float(u << 16); }
; __device__ __forceinline__ float bfhi(unsigned u) { return __uint_as_float(u & 0xffff0000u); }
; #define SG(a_, g_) ((a_) * __builtin_amdgcn_rcpf(einv(g_)))
;     __device__ __forceinline__ void operator()(f32x4 (&acc)[2][2][4][2], const Unit& u, int wr, int wc, int fr, int fq) const {
;     ...
;         for (int ai = 0; ai < 2; ++ai) {
;             v4u gq[4][2];
; #pragma unroll
;             for (int m = 0; m < 4; ++m)
; #pragma unroll
;                 for (int bj = 0; bj < 2; ++bj) gq[m][bj] = *(const v4u*)(Z + (size_t)T * OFF_GATE + (size_t)(row0 + ai * 128 + m * 16) * 3072 + 2048 + col0 + bj * 128);
; #pragma unroll
;             for (int m = 0; m < 4; ++m) { const int row = row0 + ai * 128 + m * 16;
; #pragma unroll
;                 for (int bj = 0; bj < 2; ++bj) { const int col = col0 + bj * 128;
;                     const v4u gw = gq[m][bj];
;                     const f32x4 a0 = acc[ai][bj][m][0], a1 = acc[ai][bj][m][1];
;     ...
;                     v4u w; w.x = pk2(SG(a0[0], bflo(gw.x)), SG(a0[1], bfhi(gw.x))); w.y = pk2(SG(a0[2], bflo(gw.y)), SG(a0[3], bfhi(gw.y)));
;                     w.z = pk2(SG(a1[0], bflo(gw.z)), SG(a1[1], bfhi(gw.z))); w.w = pk2(SG(a1[2], bflo(gw.w)), SG(a1[3], bfhi(gw.w)));
;     ...
;                     *(v4u*)(MB + (size_t)row * 1024 + col) = w; } }
	v_add_f32_e32 v0, 1.0, v0
	v_cvt_pk_bf16_f32 v140, v144, v145
	v_rcp_f32_e32 v144, v0
	v_and_b32_e32 v0, 0xffff0000, v141
	v_max_f32_e64 v0, -v0, -v0
	v_min_f32_e32 v0, 0x41f00000, v0
	v_mul_f32_e32 v0, 0x3fb8aa3b, v0
	v_exp_f32_e32 v0, v0
	s_nop 0
	v_add_f32_e32 v0, 1.0, v0
	v_rcp_f32_e32 v145, v0
	v_lshlrev_b32_e32 v0, 16, v142
	v_max_f32_e64 v0, -v0, -v0
	v_min_f32_e32 v0, 0x41f00000, v0
	v_mul_f32_e32 v0, 0x3fb8aa3b, v0
	v_exp_f32_e32 v0, v0
	v_pk_mul_f32 v[144:145], v[54:55], v[144:145]
	v_add_f32_e32 v0, 1.0, v0
	v_cvt_pk_bf16_f32 v141, v144, v145
	v_rcp_f32_e32 v144, v0
	v_and_b32_e32 v0, 0xffff0000, v142
	v_max_f32_e64 v0, -v0, -v0
	v_min_f32_e32 v0, 0x41f00000, v0
	v_mul_f32_e32 v0, 0x3fb8aa3b, v0
	v_exp_f32_e32 v0, v0
	s_nop 0
	v_add_f32_e32 v0, 1.0, v0
	v_rcp_f32_e32 v145, v0
	v_lshlrev_b32_e32 v0, 16, v143
	v_max_f32_e64 v0, -v0, -v0
	v_min_f32_e32 v0, 0x41f00000, v0
	v_mul_f32_e32 v0, 0x3fb8aa3b, v0
	v_exp_f32_e32 v0, v0
	v_pk_mul_f32 v[144:145], v[56:57], v[144:145]
	v_add_f32_e32 v0, 1.0, v0
	v_cvt_pk_bf16_f32 v142, v144, v145
	v_rcp_f32_e32 v144, v0
	v_and_b32_e32 v0, 0xffff0000, v143
	v_max_f32_e64 v0, -v0, -v0
	v_min_f32_e32 v0, 0x41f00000, v0
	v_mul_f32_e32 v0, 0x3fb8aa3b, v0
	v_exp_f32_e32 v0, v0
	s_nop 0
	v_add_f32_e32 v0, 1.0, v0
	v_rcp_f32_e32 v145, v0
	v_lshlrev_b32_e32 v0, 16, v136
	v_max_f32_e64 v0, -v0, -v0
	v_min_f32_e32 v0, 0x41f00000, v0
	v_mul_f32_e32 v0, 0x3fb8aa3b, v0
	v_exp_f32_e32 v0, v0
	v_pk_mul_f32 v[144:145], v[58:59], v[144:145]
	v_add_f32_e32 v0, 1.0, v0
	v_cvt_pk_bf16_f32 v143, v144, v145
	global_store_dwordx4 v[148:149], v[140:143], off offset:256
	s_nop 1
	v_rcp_f32_e32 v142, v0
	v_and_b32_e32 v0, 0xffff0000, v136
	v_max_f32_e64 v0, -v0, -v0
	v_min_f32_e32 v0, 0x41f00000, v0
	v_mul_f32_e32 v0, 0x3fb8aa3b, v0
	v_exp_f32_e32 v0, v0
	v_lshlrev_b64 v[140:141], 11, v[186:187]
	v_lshl_add_u64 v[140:141], s[56:57], 0, v[140:141]
	v_lshl_add_u64 v[140:141], v[140:141], 0, v[194:195]
	v_add_f32_e32 v0, 1.0, v0
	v_rcp_f32_e32 v143, v0
	v_lshlrev_b32_e32 v0, 16, v137
	v_max_f32_e64 v0, -v0, -v0
	v_min_f32_e32 v0, 0x41f00000, v0
	v_mul_f32_e32 v0, 0x3fb8aa3b, v0
	v_exp_f32_e32 v0, v0
	v_pk_mul_f32 v[142:143], v[28:29], v[142:143]
	v_add_f32_e32 v0, 1.0, v0
	v_cvt_pk_bf16_f32 v136, v142, v143
	v_rcp_f32_e32 v142, v0
	v_and_b32_e32 v0, 0xffff0000, v137
	v_max_f32_e64 v0, -v0, -v0
	v_min_f32_e32 v0, 0x41f00000, v0
	v_mul_f32_e32 v0, 0x3fb8aa3b, v0
	v_exp_f32_e32 v0, v0
	s_nop 0
	v_add_f32_e32 v0, 1.0, v0
	v_rcp_f32_e32 v143, v0
	v_lshlrev_b32_e32 v0, 16, v138
	v_max_f32_e64 v0, -v0, -v0
	v_min_f32_e32 v0, 0x41f00000, v0
	v_mul_f32_e32 v0, 0x3fb8aa3b, v0
	v_exp_f32_e32 v0, v0
	v_pk_mul_f32 v[142:143], v[30:31], v[142:143]
	v_add_f32_e32 v0, 1.0, v0
	v_cvt_pk_bf16_f32 v137, v142, v143
	v_rcp_f32_e32 v142, v0
	v_and_b32_e32 v0, 0xffff0000, v138
	v_max_f32_e64 v0, -v0, -v0
	v_min_f32_e32 v0, 0x41f00000, v0
	v_mul_f32_e32 v0, 0x3fb8aa3b, v0
	v_exp_f32_e32 v0, v0
	s_nop 0
	v_add_f32_e32 v0, 1.0, v0
	v_rcp_f32_e32 v143, v0
	v_lshlrev_b32_e32 v0, 16, v139
	v_max_f32_e64 v0, -v0, -v0
	v_min_f32_e32 v0, 0x41f00000, v0
	v_mul_f32_e32 v0, 0x3fb8aa3b, v0
	v_exp_f32_e32 v0, v0
	v_pk_mul_f32 v[142:143], v[32:33], v[142:143]
	v_add_f32_e32 v0, 1.0, v0
	v_cvt_pk_bf16_f32 v138, v142, v143
	v_rcp_f32_e32 v142, v0
	v_and_b32_e32 v0, 0xffff0000, v139
	v_max_f32_e64 v0, -v0, -v0
	v_min_f32_e32 v0, 0x41f00000, v0
	v_mul_f32_e32 v0, 0x3fb8aa3b, v0
	v_exp_f32_e32 v0, v0
	s_nop 0
	v_add_f32_e32 v0, 1.0, v0
	v_rcp_f32_e32 v143, v0
	v_lshlrev_b32_e32 v0, 16, v132
	v_max_f32_e64 v0, -v0, -v0
	v_min_f32_e32 v0, 0x41f00000, v0
	v_mul_f32_e32 v0, 0x3fb8aa3b, v0
	v_exp_f32_e32 v0, v0
	v_pk_mul_f32 v[142:143], v[34:35], v[142:143]
	v_add_f32_e32 v0, 1.0, v0
	v_cvt_pk_bf16_f32 v139, v142, v143
	global_store_dwordx4 v[140:141], v[136:139], off
	s_nop 1
	v_rcp_f32_e32 v136, v0
	v_and_b32_e32 v0, 0xffff0000, v132
	v_max_f32_e64 v0, -v0, -v0
	v_min_f32_e32 v0, 0x41f00000, v0
	v_mul_f32_e32 v0, 0x3fb8aa3b, v0
	v_exp_f32_e32 v0, v0
	s_nop 0
	v_add_f32_e32 v0, 1.0, v0
	v_rcp_f32_e32 v137, v0
	v_lshlrev_b32_e32 v0, 16, v133
	v_max_f32_e64 v0, -v0, -v0
	v_min_f32_e32 v0, 0x41f00000, v0
	v_mul_f32_e32 v0, 0x3fb8aa3b, v0
	v_exp_f32_e32 v0, v0
	v_pk_mul_f32 v[136:137], v[60:61], v[136:137]
	v_add_f32_e32 v0, 1.0, v0
	v_cvt_pk_bf16_f32 v132, v136, v137
	v_rcp_f32_e32 v136, v0
	v_and_b32_e32 v0, 0xffff0000, v133
	v_max_f32_e64 v0, -v0, -v0
	v_min_f32_e32 v0, 0x41f00000, v0
	v_mul_f32_e32 v0, 0x3fb8aa3b, v0
	v_exp_f32_e32 v0, v0
	s_nop 0
	v_add_f32_e32 v0, 1.0, v0
	v_rcp_f32_e32 v137, v0
	v_lshlrev_b32_e32 v0, 16, v134
	v_max_f32_e64 v0, -v0, -v0
	v_min_f32_e32 v0, 0x41f00000, v0
	v_mul_f32_e32 v0, 0x3fb8aa3b, v0
	v_exp_f32_e32 v0, v0
	v_pk_mul_f32 v[136:137], v[62:63], v[136:137]
	v_add_f32_e32 v0, 1.0, v0
	v_cvt_pk_bf16_f32 v133, v136, v137
	v_rcp_f32_e32 v136, v0
	v_and_b32_e32 v0, 0xffff0000, v134
	v_max_f32_e64 v0, -v0, -v0
	v_min_f32_e32 v0, 0x41f00000, v0
	v_mul_f32_e32 v0, 0x3fb8aa3b, v0
	v_exp_f32_e32 v0, v0
	s_nop 0
	v_add_f32_e32 v0, 1.0, v0
	v_rcp_f32_e32 v137, v0
	v_lshlrev_b32_e32 v0, 16, v135
	v_max_f32_e64 v0, -v0, -v0
	v_min_f32_e32 v0, 0x41f00000, v0
	v_mul_f32_e32 v0, 0x3fb8aa3b, v0
	v_exp_f32_e32 v0, v0
	v_pk_mul_f32 v[136:137], v[64:65], v[136:137]
	v_add_f32_e32 v0, 1.0, v0
	v_cvt_pk_bf16_f32 v134, v136, v137
	v_rcp_f32_e32 v136, v0
	v_and_b32_e32 v0, 0xffff0000, v135
	v_max_f32_e64 v0, -v0, -v0
	v_min_f32_e32 v0, 0x41f00000, v0
	v_mul_f32_e32 v0, 0x3fb8aa3b, v0
	v_exp_f32_e32 v0, v0
	s_nop 0
	v_add_f32_e32 v0, 1.0, v0
	v_rcp_f32_e32 v137, v0
	s_nop 0
	v_pk_mul_f32 v[136:137], v[66:67], v[136:137]
	s_nop 0
	v_cvt_pk_bf16_f32 v135, v136, v137
	global_store_dwordx4 v[140:141], v[132:135], off offset:256
	s_nop 1
	v_mad_i64_i32 v[132:133], s[6:7], v226, s68, v[196:197]
	v_lshl_add_u64 v[132:133], v[132:133], 0, v[194:195]
	v_lshl_add_u64 v[134:135], v[132:133], 0, s[50:51]
	v_add_co_u32_e32 v132, vcc, s19, v132
	s_nop 1
	v_addc_co_u32_e32 v133, vcc, 0, v133, vcc
	global_load_dwordx4 v[160:163], v[132:133], off
	global_load_dwordx4 v[156:159], v[134:135], off offset:256
	v_mad_i64_i32 v[132:133], s[6:7], v202, s68, v[196:197]
	v_lshl_add_u64 v[132:133], v[132:133], 0, v[194:195]
	v_lshl_add_u64 v[134:135], v[132:133], 0, s[50:51]
	v_add_co_u32_e32 v132, vcc, s19, v132
	s_waitcnt vmcnt(0)
; __device__ __forceinline__ unsigned pk2(float lo, float hi) { v2f v = {lo, hi}; return __builtin_bit_cast(unsigned, __builtin_convertvector(v, v2bf)); }
; __device__ __forceinline__ float bflo(unsigned u) { return __uint_as_float(u << 16); }
; __device__ __forceinline__ float bfhi(unsigned u) { return __uint_as_float(u & 0xffff0000u); }
; #define SG(a_, g_) ((a_) * __builtin_amdgcn_rcpf(einv(g_)))
;     __device__ __forceinline__ void operator()(f32x4 (&acc)[2][2][4][2], const Unit& u, int wr, int wc, int fr, int fq) const {
;     ...
;         for (int ai = 0; ai < 2; ++ai) {
;             v4u gq[4][2];
; #pragma unroll
;             for (int m = 0; m < 4; ++m)
; #pragma unroll
;                 for (int bj = 0; bj < 2; ++bj) gq[m][bj] = *(const v4u*)(Z + (size_t)T * OFF_GATE + (size_t)(row0 + ai * 128 + m * 16) * 3072 + 2048 + col0 + bj * 128);
; #pragma unroll
;             for (int m = 0; m < 4; ++m) { const int row = row0 + ai * 128 + m * 16;
; #pragma unroll
;                 for (int bj = 0; bj < 2; ++bj) { const int col = col0 + bj * 128;
;                     const v4u gw = gq[m][bj];
;                     const f32x4 a0 = acc[ai][bj][m][0], a1 = acc[ai][bj][m][1];
;     ...
;                     v4u w; w.x = pk2(SG(a0[0], bflo(gw.x)), SG(a0[1], bfhi(gw.x))); w.y = pk2(SG(a0[2], bflo(gw.y)), SG(a0[3], bfhi(gw.y)));
;                     w.z = pk2(SG(a1[0], bflo(gw.z)), SG(a1[1], bfhi(gw.z))); w.w = pk2(SG(a1[2], bflo(gw.w)), SG(a1[3], bfhi(gw.w)));
;     ...
;                     *(v4u*)(MB + (size_t)row * 1024 + col) = w; } }
	v_lshlrev_b32_e32 v0, 16, v160
	v_max_f32_e64 v0, -v0, -v0
	v_min_f32_e32 v0, 0x41f00000, v0
	v_mul_f32_e32 v0, 0x3fb8aa3b, v0
	v_addc_co_u32_e32 v133, vcc, 0, v133, vcc
	v_exp_f32_e32 v0, v0
	global_load_dwordx4 v[152:155], v[132:133], off
	global_load_dwordx4 v[148:151], v[134:135], off offset:256
	v_mad_i64_i32 v[132:133], s[6:7], v200, s68, v[196:197]
	v_lshl_add_u64 v[132:133], v[132:133], 0, v[194:195]
	v_lshl_add_u64 v[134:135], v[132:133], 0, s[50:51]
	v_add_co_u32_e32 v132, vcc, s19, v132
	v_add_f32_e32 v0, 1.0, v0
	s_nop 0
	v_addc_co_u32_e32 v133, vcc, 0, v133, vcc
	global_load_dwordx4 v[144:147], v[132:133], off
	global_load_dwordx4 v[140:143], v[134:135], off offset:256
	v_mad_i64_i32 v[132:133], s[6:7], v198, s68, v[196:197]
	v_lshlrev_b64 v[196:197], 11, v[226:227]
	v_rcp_f32_e32 v226, v0
	v_and_b32_e32 v0, 0xffff0000, v160
	v_max_f32_e64 v0, -v0, -v0
	v_min_f32_e32 v0, 0x41f00000, v0
	v_mul_f32_e32 v0, 0x3fb8aa3b, v0
	v_exp_f32_e32 v0, v0
	v_lshl_add_u64 v[132:133], v[132:133], 0, v[194:195]
	v_lshl_add_u64 v[134:135], v[132:133], 0, s[50:51]
	v_add_co_u32_e32 v132, vcc, s19, v132
	v_add_f32_e32 v0, 1.0, v0
	v_rcp_f32_e32 v227, v0
	v_lshlrev_b32_e32 v0, 16, v161
	v_max_f32_e64 v0, -v0, -v0
	v_min_f32_e32 v0, 0x41f00000, v0
	v_mul_f32_e32 v0, 0x3fb8aa3b, v0
	v_exp_f32_e32 v0, v0
	v_pk_mul_f32 v[226:227], v[68:69], v[226:227]
	v_lshl_add_u64 v[196:197], s[56:57], 0, v[196:197]
	v_cvt_pk_bf16_f32 v160, v226, v227
	v_add_f32_e32 v0, 1.0, v0
	v_rcp_f32_e32 v226, v0
	v_and_b32_e32 v0, 0xffff0000, v161
	v_max_f32_e64 v0, -v0, -v0
	v_min_f32_e32 v0, 0x41f00000, v0
	v_mul_f32_e32 v0, 0x3fb8aa3b, v0
	v_exp_f32_e32 v0, v0
	v_addc_co_u32_e32 v133, vcc, 0, v133, vcc
	v_lshl_add_u64 v[196:197], v[196:197], 0, v[194:195]
	v_add_f32_e32 v0, 1.0, v0
	v_rcp_f32_e32 v227, v0
	v_lshlrev_b32_e32 v0, 16, v162
	v_max_f32_e64 v0, -v0, -v0
	v_min_f32_e32 v0, 0x41f00000, v0
	v_mul_f32_e32 v0, 0x3fb8aa3b, v0
	v_exp_f32_e32 v0, v0
	v_pk_mul_f32 v[226:227], v[70:71], v[226:227]
	global_load_dwordx4 v[136:139], v[132:133], off
	s_nop 0
	global_load_dwordx4 v[132:135], v[134:135], off offset:256
	v_cvt_pk_bf16_f32 v161, v226, v227
	v_add_f32_e32 v0, 1.0, v0
	v_rcp_f32_e32 v226, v0
	v_and_b32_e32 v0, 0xffff0000, v162
	v_max_f32_e64 v0, -v0, -v0
	v_min_f32_e32 v0, 0x41f00000, v0
	v_mul_f32_e32 v0, 0x3fb8aa3b, v0
	v_exp_f32_e32 v0, v0
	s_mov_b64 s[6:7], 0
	v_add_f32_e32 v0, 1.0, v0
	v_rcp_f32_e32 v227, v0
	v_lshlrev_b32_e32 v0, 16, v163
	v_max_f32_e64 v0, -v0, -v0
	v_min_f32_e32 v0, 0x41f00000, v0
	v_mul_f32_e32 v0, 0x3fb8aa3b, v0
	v_exp_f32_e32 v0, v0
	v_pk_mul_f32 v[226:227], v[72:73], v[226:227]
	v_add_f32_e32 v0, 1.0, v0
	v_cvt_pk_bf16_f32 v162, v226, v227
	v_rcp_f32_e32 v226, v0
	v_and_b32_e32 v0, 0xffff0000, v163
	v_max_f32_e64 v0, -v0, -v0
	v_min_f32_e32 v0, 0x41f00000, v0
	v_mul_f32_e32 v0, 0x3fb8aa3b, v0
	v_exp_f32_e32 v0, v0
	s_nop 0
	v_add_f32_e32 v0, 1.0, v0
	v_rcp_f32_e32 v227, v0
	v_lshlrev_b32_e32 v0, 16, v156
	v_max_f32_e64 v0, -v0, -v0
	v_min_f32_e32 v0, 0x41f00000, v0
	v_mul_f32_e32 v0, 0x3fb8aa3b, v0
	v_exp_f32_e32 v0, v0
	v_pk_mul_f32 v[226:227], v[74:75], v[226:227]
	v_add_f32_e32 v0, 1.0, v0
	v_cvt_pk_bf16_f32 v163, v226, v227
	global_store_dwordx4 v[196:197], v[160:163], off
	s_nop 1
	v_rcp_f32_e32 v160, v0
	v_and_b32_e32 v0, 0xffff0000, v156
	v_max_f32_e64 v0, -v0, -v0
	v_min_f32_e32 v0, 0x41f00000, v0
	v_mul_f32_e32 v0, 0x3fb8aa3b, v0
	v_exp_f32_e32 v0, v0
	s_nop 0
	v_add_f32_e32 v0, 1.0, v0
	v_rcp_f32_e32 v161, v0
	v_lshlrev_b32_e32 v0, 16, v157
	v_max_f32_e64 v0, -v0, -v0
	v_min_f32_e32 v0, 0x41f00000, v0
	v_mul_f32_e32 v0, 0x3fb8aa3b, v0
	v_exp_f32_e32 v0, v0
	v_pk_mul_f32 v[160:161], v[100:101], v[160:161]
	v_add_f32_e32 v0, 1.0, v0
	v_cvt_pk_bf16_f32 v156, v160, v161
	v_rcp_f32_e32 v160, v0
	v_and_b32_e32 v0, 0xffff0000, v157
	v_max_f32_e64 v0, -v0, -v0
	v_min_f32_e32 v0, 0x41f00000, v0
	v_mul_f32_e32 v0, 0x3fb8aa3b, v0
	v_exp_f32_e32 v0, v0
	s_nop 0
	v_add_f32_e32 v0, 1.0, v0
	v_rcp_f32_e32 v161, v0
	v_lshlrev_b32_e32 v0, 16, v158
	v_max_f32_e64 v0, -v0, -v0
	v_min_f32_e32 v0, 0x41f00000, v0
	v_mul_f32_e32 v0, 0x3fb8aa3b, v0
	v_exp_f32_e32 v0, v0
	v_pk_mul_f32 v[160:161], v[102:103], v[160:161]
	v_add_f32_e32 v0, 1.0, v0
	v_cvt_pk_bf16_f32 v157, v160, v161
	v_rcp_f32_e32 v160, v0
	v_and_b32_e32 v0, 0xffff0000, v158
	v_max_f32_e64 v0, -v0, -v0
	v_min_f32_e32 v0, 0x41f00000, v0
	v_mul_f32_e32 v0, 0x3fb8aa3b, v0
	v_exp_f32_e32 v0, v0
	s_nop 0
	v_add_f32_e32 v0, 1.0, v0
	v_rcp_f32_e32 v161, v0
	v_lshlrev_b32_e32 v0, 16, v159
	v_max_f32_e64 v0, -v0, -v0
	v_min_f32_e32 v0, 0x41f00000, v0
	v_mul_f32_e32 v0, 0x3fb8aa3b, v0
	v_exp_f32_e32 v0, v0
	v_pk_mul_f32 v[160:161], v[104:105], v[160:161]
	v_add_f32_e32 v0, 1.0, v0
	v_cvt_pk_bf16_f32 v158, v160, v161
	v_rcp_f32_e32 v160, v0
	v_and_b32_e32 v0, 0xffff0000, v159
	v_max_f32_e64 v0, -v0, -v0
	v_min_f32_e32 v0, 0x41f00000, v0
	v_mul_f32_e32 v0, 0x3fb8aa3b, v0
	v_exp_f32_e32 v0, v0
	s_nop 0
	v_add_f32_e32 v0, 1.0, v0
	v_rcp_f32_e32 v161, v0
	s_waitcnt vmcnt(0)
; __device__ __forceinline__ unsigned pk2(float lo, float hi) { v2f v = {lo, hi}; return __builtin_bit_cast(unsigned, __builtin_convertvector(v, v2bf)); }
; __device__ __forceinline__ float bflo(unsigned u) { return __uint_as_float(u << 16); }
; __device__ __forceinline__ float bfhi(unsigned u) { return __uint_as_float(u & 0xffff0000u); }
; #define SG(a_, g_) ((a_) * __builtin_amdgcn_rcpf(einv(g_)))
;     __device__ __forceinline__ void operator()(f32x4 (&acc)[2][2][4][2], const Unit& u, int wr, int wc, int fr, int fq) const {
;     ...
;             for (int m = 0; m < 4; ++m) { const int row = row0 + ai * 128 + m * 16;
; #pragma unroll
;                 for (int bj = 0; bj < 2; ++bj) { const int col = col0 + bj * 128;
;                     const v4u gw = gq[m][bj];
;                     const f32x4 a0 = acc[ai][bj][m][0], a1 = acc[ai][bj][m][1];
;     ...
;                     v4u w; w.x = pk2(SG(a0[0], bflo(gw.x)), SG(a0[1], bfhi(gw.x))); w.y = pk2(SG(a0[2], bflo(gw.y)), SG(a0[3], bfhi(gw.y)));
;                     w.z = pk2(SG(a1[0], bflo(gw.z)), SG(a1[1], bfhi(gw.z))); w.w = pk2(SG(a1[2], bflo(gw.w)), SG(a1[3], bfhi(gw.w)));
;     ...
;                     *(v4u*)(MB + (size_t)row * 1024 + col) = w; } }
	v_lshlrev_b32_e32 v0, 16, v152
	v_max_f32_e64 v0, -v0, -v0
	v_min_f32_e32 v0, 0x41f00000, v0
	v_mul_f32_e32 v0, 0x3fb8aa3b, v0
	v_exp_f32_e32 v0, v0
	v_pk_mul_f32 v[160:161], v[106:107], v[160:161]
	v_add_f32_e32 v0, 1.0, v0
	v_cvt_pk_bf16_f32 v159, v160, v161
	global_store_dwordx4 v[196:197], v[156:159], off offset:256
	s_nop 1
	v_rcp_f32_e32 v158, v0
	v_and_b32_e32 v0, 0xffff0000, v152
	v_max_f32_e64 v0, -v0, -v0
	v_min_f32_e32 v0, 0x41f00000, v0
	v_mul_f32_e32 v0, 0x3fb8aa3b, v0
	v_exp_f32_e32 v0, v0
	v_lshlrev_b64 v[156:157], 11, v[202:203]
	v_lshl_add_u64 v[156:157], s[56:57], 0, v[156:157]
	v_lshl_add_u64 v[156:157], v[156:157], 0, v[194:195]
	v_add_f32_e32 v0, 1.0, v0
	v_rcp_f32_e32 v159, v0
	v_lshlrev_b32_e32 v0, 16, v153
	v_max_f32_e64 v0, -v0, -v0
	v_min_f32_e32 v0, 0x41f00000, v0
	v_mul_f32_e32 v0, 0x3fb8aa3b, v0
	v_exp_f32_e32 v0, v0
	v_pk_mul_f32 v[158:159], v[76:77], v[158:159]
	v_add_f32_e32 v0, 1.0, v0
	v_cvt_pk_bf16_f32 v152, v158, v159
	v_rcp_f32_e32 v158, v0
	v_and_b32_e32 v0, 0xffff0000, v153
	v_max_f32_e64 v0, -v0, -v0
	v_min_f32_e32 v0, 0x41f00000, v0
	v_mul_f32_e32 v0, 0x3fb8aa3b, v0
	v_exp_f32_e32 v0, v0
	s_nop 0
	v_add_f32_e32 v0, 1.0, v0
	v_rcp_f32_e32 v159, v0
	v_lshlrev_b32_e32 v0, 16, v154
	v_max_f32_e64 v0, -v0, -v0
	v_min_f32_e32 v0, 0x41f00000, v0
	v_mul_f32_e32 v0, 0x3fb8aa3b, v0
	v_exp_f32_e32 v0, v0
	v_pk_mul_f32 v[158:159], v[78:79], v[158:159]
	v_add_f32_e32 v0, 1.0, v0
	v_cvt_pk_bf16_f32 v153, v158, v159
	v_rcp_f32_e32 v158, v0
	v_and_b32_e32 v0, 0xffff0000, v154
	v_max_f32_e64 v0, -v0, -v0
	v_min_f32_e32 v0, 0x41f00000, v0
	v_mul_f32_e32 v0, 0x3fb8aa3b, v0
	v_exp_f32_e32 v0, v0
	s_nop 0
	v_add_f32_e32 v0, 1.0, v0
	v_rcp_f32_e32 v159, v0
	v_lshlrev_b32_e32 v0, 16, v155
	v_max_f32_e64 v0, -v0, -v0
	v_min_f32_e32 v0, 0x41f00000, v0
	v_mul_f32_e32 v0, 0x3fb8aa3b, v0
	v_exp_f32_e32 v0, v0
	v_pk_mul_f32 v[158:159], v[80:81], v[158:159]
	v_add_f32_e32 v0, 1.0, v0
	v_cvt_pk_bf16_f32 v154, v158, v159
	v_rcp_f32_e32 v158, v0
	v_and_b32_e32 v0, 0xffff0000, v155
	v_max_f32_e64 v0, -v0, -v0
	v_min_f32_e32 v0, 0x41f00000, v0
	v_mul_f32_e32 v0, 0x3fb8aa3b, v0
	v_exp_f32_e32 v0, v0
	s_nop 0
	v_add_f32_e32 v0, 1.0, v0
	v_rcp_f32_e32 v159, v0
	v_lshlrev_b32_e32 v0, 16, v148
	v_max_f32_e64 v0, -v0, -v0
	v_min_f32_e32 v0, 0x41f00000, v0
	v_mul_f32_e32 v0, 0x3fb8aa3b, v0
	v_exp_f32_e32 v0, v0
	v_pk_mul_f32 v[158:159], v[82:83], v[158:159]
	v_add_f32_e32 v0, 1.0, v0
	v_cvt_pk_bf16_f32 v155, v158, v159
	global_store_dwordx4 v[156:157], v[152:155], off
	s_nop 1
	v_rcp_f32_e32 v152, v0
	v_and_b32_e32 v0, 0xffff0000, v148
	v_max_f32_e64 v0, -v0, -v0
	v_min_f32_e32 v0, 0x41f00000, v0
	v_mul_f32_e32 v0, 0x3fb8aa3b, v0
	v_exp_f32_e32 v0, v0
	s_nop 0
	v_add_f32_e32 v0, 1.0, v0
	v_rcp_f32_e32 v153, v0
	v_lshlrev_b32_e32 v0, 16, v149
	v_max_f32_e64 v0, -v0, -v0
	v_min_f32_e32 v0, 0x41f00000, v0
	v_mul_f32_e32 v0, 0x3fb8aa3b, v0
	v_exp_f32_e32 v0, v0
	v_pk_mul_f32 v[152:153], v[108:109], v[152:153]
	v_add_f32_e32 v0, 1.0, v0
	v_cvt_pk_bf16_f32 v148, v152, v153
	v_rcp_f32_e32 v152, v0
	v_and_b32_e32 v0, 0xffff0000, v149
	v_max_f32_e64 v0, -v0, -v0
	v_min_f32_e32 v0, 0x41f00000, v0
	v_mul_f32_e32 v0, 0x3fb8aa3b, v0
	v_exp_f32_e32 v0, v0
	s_nop 0
	v_add_f32_e32 v0, 1.0, v0
	v_rcp_f32_e32 v153, v0
	v_lshlrev_b32_e32 v0, 16, v150
	v_max_f32_e64 v0, -v0, -v0
	v_min_f32_e32 v0, 0x41f00000, v0
	v_mul_f32_e32 v0, 0x3fb8aa3b, v0
	v_exp_f32_e32 v0, v0
	v_pk_mul_f32 v[152:153], v[110:111], v[152:153]
	v_add_f32_e32 v0, 1.0, v0
	v_cvt_pk_bf16_f32 v149, v152, v153
	v_rcp_f32_e32 v152, v0
	v_and_b32_e32 v0, 0xffff0000, v150
	v_max_f32_e64 v0, -v0, -v0
	v_min_f32_e32 v0, 0x41f00000, v0
	v_mul_f32_e32 v0, 0x3fb8aa3b, v0
	v_exp_f32_e32 v0, v0
	s_nop 0
	v_add_f32_e32 v0, 1.0, v0
	v_rcp_f32_e32 v153, v0
	v_lshlrev_b32_e32 v0, 16, v151
	v_max_f32_e64 v0, -v0, -v0
	v_min_f32_e32 v0, 0x41f00000, v0
	v_mul_f32_e32 v0, 0x3fb8aa3b, v0
	v_exp_f32_e32 v0, v0
	v_pk_mul_f32 v[152:153], v[112:113], v[152:153]
	v_add_f32_e32 v0, 1.0, v0
	v_cvt_pk_bf16_f32 v150, v152, v153
	v_rcp_f32_e32 v152, v0
	v_and_b32_e32 v0, 0xffff0000, v151
	v_max_f32_e64 v0, -v0, -v0
	v_min_f32_e32 v0, 0x41f00000, v0
	v_mul_f32_e32 v0, 0x3fb8aa3b, v0
	v_exp_f32_e32 v0, v0
	s_nop 0
	v_add_f32_e32 v0, 1.0, v0
	v_rcp_f32_e32 v153, v0
	v_lshlrev_b32_e32 v0, 16, v144
	v_max_f32_e64 v0, -v0, -v0
	v_min_f32_e32 v0, 0x41f00000, v0
	v_mul_f32_e32 v0, 0x3fb8aa3b, v0
	v_exp_f32_e32 v0, v0
	v_pk_mul_f32 v[152:153], v[114:115], v[152:153]
	v_add_f32_e32 v0, 1.0, v0
	v_cvt_pk_bf16_f32 v151, v152, v153
	global_store_dwordx4 v[156:157], v[148:151], off offset:256
	s_nop 1
	v_rcp_f32_e32 v150, v0
	v_and_b32_e32 v0, 0xffff0000, v144
	v_max_f32_e64 v0, -v0, -v0
	v_min_f32_e32 v0, 0x41f00000, v0
	v_mul_f32_e32 v0, 0x3fb8aa3b, v0
	v_exp_f32_e32 v0, v0
	v_lshlrev_b64 v[148:149], 11, v[200:201]
	v_lshl_add_u64 v[148:149], s[56:57], 0, v[148:149]
	v_lshl_add_u64 v[148:149], v[148:149], 0, v[194:195]
	v_add_f32_e32 v0, 1.0, v0
	v_rcp_f32_e32 v151, v0
	v_lshlrev_b32_e32 v0, 16, v145
	v_max_f32_e64 v0, -v0, -v0
	v_min_f32_e32 v0, 0x41f00000, v0
	v_mul_f32_e32 v0, 0x3fb8aa3b, v0
	v_exp_f32_e32 v0, v0
	v_pk_mul_f32 v[150:151], v[84:85], v[150:151]
	v_add_f32_e32 v0, 1.0, v0
	v_cvt_pk_bf16_f32 v144, v150, v151
	v_rcp_f32_e32 v150, v0
	v_and_b32_e32 v0, 0xffff0000, v145
	v_max_f32_e64 v0, -v0, -v0
	v_min_f32_e32 v0, 0x41f00000, v0
	v_mul_f32_e32 v0, 0x3fb8aa3b, v0
	v_exp_f32_e32 v0, v0
	s_nop 0
	v_add_f32_e32 v0, 1.0, v0
	v_rcp_f32_e32 v151, v0
	v_lshlrev_b32_e32 v0, 16, v146
	v_max_f32_e64 v0, -v0, -v0
	v_min_f32_e32 v0, 0x41f00000, v0
	v_mul_f32_e32 v0, 0x3fb8aa3b, v0
	v_exp_f32_e32 v0, v0
; __device__ __forceinline__ unsigned pk2(float lo, float hi) { v2f v = {lo, hi}; return __builtin_bit_cast(unsigned, __builtin_convertvector(v, v2bf)); }
; __device__ __forceinline__ float bflo(unsigned u) { return __uint_as_float(u << 16); }
; __device__ __forceinline__ float bfhi(unsigned u) { return __uint_as_float(u & 0xffff0000u); }
; #define SG(a_, g_) ((a_) * __builtin_amdgcn_rcpf(einv(g_)))
;     __device__ __forceinline__ void operator()(f32x4 (&acc)[2][2][4][2], const Unit& u, int wr, int wc, int fr, int fq) const {
;     ...
;             for (int m = 0; m < 4; ++m) { const int row = row0 + ai * 128 + m * 16;
; #pragma unroll
;                 for (int bj = 0; bj < 2; ++bj) { const int col = col0 + bj * 128;
;                     const v4u gw = gq[m][bj];
;                     const f32x4 a0 = acc[ai][bj][m][0], a1 = acc[ai][bj][m][1];
;     ...
;                     v4u w; w.x = pk2(SG(a0[0], bflo(gw.x)), SG(a0[1], bfhi(gw.x))); w.y = pk2(SG(a0[2], bflo(gw.y)), SG(a0[3], bfhi(gw.y)));
;                     w.z = pk2(SG(a1[0], bflo(gw.z)), SG(a1[1], bfhi(gw.z))); w.w = pk2(SG(a1[2], bflo(gw.w)), SG(a1[3], bfhi(gw.w)));
;     ...
;                     *(v4u*)(MB + (size_t)row * 1024 + col) = w; } }
	v_pk_mul_f32 v[150:151], v[86:87], v[150:151]
	v_add_f32_e32 v0, 1.0, v0
	v_cvt_pk_bf16_f32 v145, v150, v151
	v_rcp_f32_e32 v150, v0
	v_and_b32_e32 v0, 0xffff0000, v146
	v_max_f32_e64 v0, -v0, -v0
	v_min_f32_e32 v0, 0x41f00000, v0
	v_mul_f32_e32 v0, 0x3fb8aa3b, v0
	v_exp_f32_e32 v0, v0
	s_nop 0
	v_add_f32_e32 v0, 1.0, v0
	v_rcp_f32_e32 v151, v0
	v_lshlrev_b32_e32 v0, 16, v147
	v_max_f32_e64 v0, -v0, -v0
	v_min_f32_e32 v0, 0x41f00000, v0
	v_mul_f32_e32 v0, 0x3fb8aa3b, v0
	v_exp_f32_e32 v0, v0
	v_pk_mul_f32 v[150:151], v[88:89], v[150:151]
	v_add_f32_e32 v0, 1.0, v0
	v_cvt_pk_bf16_f32 v146, v150, v151
	v_rcp_f32_e32 v150, v0
	v_and_b32_e32 v0, 0xffff0000, v147
	v_max_f32_e64 v0, -v0, -v0
	v_min_f32_e32 v0, 0x41f00000, v0
	v_mul_f32_e32 v0, 0x3fb8aa3b, v0
	v_exp_f32_e32 v0, v0
	s_nop 0
	v_add_f32_e32 v0, 1.0, v0
	v_rcp_f32_e32 v151, v0
	v_lshlrev_b32_e32 v0, 16, v140
	v_max_f32_e64 v0, -v0, -v0
	v_min_f32_e32 v0, 0x41f00000, v0
	v_mul_f32_e32 v0, 0x3fb8aa3b, v0
	v_exp_f32_e32 v0, v0
	v_pk_mul_f32 v[150:151], v[90:91], v[150:151]
	v_add_f32_e32 v0, 1.0, v0
	v_cvt_pk_bf16_f32 v147, v150, v151
	global_store_dwordx4 v[148:149], v[144:147], off
	s_nop 1
	v_rcp_f32_e32 v144, v0
	v_and_b32_e32 v0, 0xffff0000, v140
	v_max_f32_e64 v0, -v0, -v0
	v_min_f32_e32 v0, 0x41f00000, v0
	v_mul_f32_e32 v0, 0x3fb8aa3b, v0
	v_exp_f32_e32 v0, v0
	s_nop 0
	v_add_f32_e32 v0, 1.0, v0
	v_rcp_f32_e32 v145, v0
	v_lshlrev_b32_e32 v0, 16, v141
	v_max_f32_e64 v0, -v0, -v0
	v_min_f32_e32 v0, 0x41f00000, v0
	v_mul_f32_e32 v0, 0x3fb8aa3b, v0
	v_exp_f32_e32 v0, v0
	v_pk_mul_f32 v[144:145], v[116:117], v[144:145]
	v_add_f32_e32 v0, 1.0, v0
	v_cvt_pk_bf16_f32 v140, v144, v145
	v_rcp_f32_e32 v144, v0
	v_and_b32_e32 v0, 0xffff0000, v141
	v_max_f32_e64 v0, -v0, -v0
	v_min_f32_e32 v0, 0x41f00000, v0
	v_mul_f32_e32 v0, 0x3fb8aa3b, v0
	v_exp_f32_e32 v0, v0
	s_nop 0
	v_add_f32_e32 v0, 1.0, v0
	v_rcp_f32_e32 v145, v0
	v_lshlrev_b32_e32 v0, 16, v142
	v_max_f32_e64 v0, -v0, -v0
	v_min_f32_e32 v0, 0x41f00000, v0
	v_mul_f32_e32 v0, 0x3fb8aa3b, v0
	v_exp_f32_e32 v0, v0
	v_pk_mul_f32 v[144:145], v[118:119], v[144:145]
	v_add_f32_e32 v0, 1.0, v0
	v_cvt_pk_bf16_f32 v141, v144, v145
	v_rcp_f32_e32 v144, v0
	v_and_b32_e32 v0, 0xffff0000, v142
	v_max_f32_e64 v0, -v0, -v0
	v_min_f32_e32 v0, 0x41f00000, v0
	v_mul_f32_e32 v0, 0x3fb8aa3b, v0
	v_exp_f32_e32 v0, v0
	s_nop 0
	v_add_f32_e32 v0, 1.0, v0
	v_rcp_f32_e32 v145, v0
	v_lshlrev_b32_e32 v0, 16, v143
	v_max_f32_e64 v0, -v0, -v0
	v_min_f32_e32 v0, 0x41f00000, v0
	v_mul_f32_e32 v0, 0x3fb8aa3b, v0
	v_exp_f32_e32 v0, v0
	v_pk_mul_f32 v[144:145], v[120:121], v[144:145]
	v_add_f32_e32 v0, 1.0, v0
	v_cvt_pk_bf16_f32 v142, v144, v145
	v_rcp_f32_e32 v144, v0
	v_and_b32_e32 v0, 0xffff0000, v143
	v_max_f32_e64 v0, -v0, -v0
	v_min_f32_e32 v0, 0x41f00000, v0
	v_mul_f32_e32 v0, 0x3fb8aa3b, v0
	v_exp_f32_e32 v0, v0
	s_nop 0
	v_add_f32_e32 v0, 1.0, v0
	v_rcp_f32_e32 v145, v0
	v_lshlrev_b32_e32 v0, 16, v136
	v_max_f32_e64 v0, -v0, -v0
	v_min_f32_e32 v0, 0x41f00000, v0
	v_mul_f32_e32 v0, 0x3fb8aa3b, v0
	v_exp_f32_e32 v0, v0
	v_pk_mul_f32 v[144:145], v[122:123], v[144:145]
	v_add_f32_e32 v0, 1.0, v0
	v_cvt_pk_bf16_f32 v143, v144, v145
	global_store_dwordx4 v[148:149], v[140:143], off offset:256
	s_nop 1
	v_rcp_f32_e32 v142, v0
	v_and_b32_e32 v0, 0xffff0000, v136
	v_max_f32_e64 v0, -v0, -v0
	v_min_f32_e32 v0, 0x41f00000, v0
	v_mul_f32_e32 v0, 0x3fb8aa3b, v0
	v_exp_f32_e32 v0, v0
	v_lshlrev_b64 v[140:141], 11, v[198:199]
	v_lshl_add_u64 v[140:141], s[56:57], 0, v[140:141]
	v_lshl_add_u64 v[140:141], v[140:141], 0, v[194:195]
	v_add_f32_e32 v0, 1.0, v0
	v_rcp_f32_e32 v143, v0
	v_lshlrev_b32_e32 v0, 16, v137
	v_max_f32_e64 v0, -v0, -v0
; __device__ __forceinline__ unsigned pk2(float lo, float hi) { v2f v = {lo, hi}; return __builtin_bit_cast(unsigned, __builtin_convertvector(v, v2bf)); }
; __device__ __forceinline__ float bflo(unsigned u) { return __uint_as_float(u << 16); }
; __device__ __forceinline__ float bfhi(unsigned u) { return __uint_as_float(u & 0xffff0000u); }
; #define SG(a_, g_) ((a_) * __builtin_amdgcn_rcpf(einv(g_)))
;     __device__ __forceinline__ void operator()(f32x4 (&acc)[2][2][4][2], const Unit& u, int wr, int wc, int fr, int fq) const {
;     ...
;             for (int m = 0; m < 4; ++m) { const int row = row0 + ai * 128 + m * 16;
; #pragma unroll
;                 for (int bj = 0; bj < 2; ++bj) { const int col = col0 + bj * 128;
;                     const v4u gw = gq[m][bj];
;                     const f32x4 a0 = acc[ai][bj][m][0], a1 = acc[ai][bj][m][1];
;     ...
;                     v4u w; w.x = pk2(SG(a0[0], bflo(gw.x)), SG(a0[1], bfhi(gw.x))); w.y = pk2(SG(a0[2], bflo(gw.y)), SG(a0[3], bfhi(gw.y)));
;                     w.z = pk2(SG(a1[0], bflo(gw.z)), SG(a1[1], bfhi(gw.z))); w.w = pk2(SG(a1[2], bflo(gw.w)), SG(a1[3], bfhi(gw.w)));
;     ...
;                     *(v4u*)(MB + (size_t)row * 1024 + col) = w; } }
	v_min_f32_e32 v0, 0x41f00000, v0
	v_mul_f32_e32 v0, 0x3fb8aa3b, v0
	v_exp_f32_e32 v0, v0
	v_pk_mul_f32 v[142:143], v[92:93], v[142:143]
	v_add_f32_e32 v0, 1.0, v0
	v_cvt_pk_bf16_f32 v136, v142, v143
	v_rcp_f32_e32 v142, v0
	v_and_b32_e32 v0, 0xffff0000, v137
	v_max_f32_e64 v0, -v0, -v0
	v_min_f32_e32 v0, 0x41f00000, v0
	v_mul_f32_e32 v0, 0x3fb8aa3b, v0
	v_exp_f32_e32 v0, v0
	s_nop 0
	v_add_f32_e32 v0, 1.0, v0
	v_rcp_f32_e32 v143, v0
	v_lshlrev_b32_e32 v0, 16, v138
	v_max_f32_e64 v0, -v0, -v0
	v_min_f32_e32 v0, 0x41f00000, v0
	v_mul_f32_e32 v0, 0x3fb8aa3b, v0
	v_exp_f32_e32 v0, v0
	v_pk_mul_f32 v[142:143], v[94:95], v[142:143]
	v_add_f32_e32 v0, 1.0, v0
	v_cvt_pk_bf16_f32 v137, v142, v143
	v_rcp_f32_e32 v142, v0
	v_and_b32_e32 v0, 0xffff0000, v138
	v_max_f32_e64 v0, -v0, -v0
	v_min_f32_e32 v0, 0x41f00000, v0
	v_mul_f32_e32 v0, 0x3fb8aa3b, v0
	v_exp_f32_e32 v0, v0
	s_nop 0
	v_add_f32_e32 v0, 1.0, v0
	v_rcp_f32_e32 v143, v0
	v_lshlrev_b32_e32 v0, 16, v139
	v_max_f32_e64 v0, -v0, -v0
	v_min_f32_e32 v0, 0x41f00000, v0
	v_mul_f32_e32 v0, 0x3fb8aa3b, v0
	v_exp_f32_e32 v0, v0
	v_pk_mul_f32 v[142:143], v[96:97], v[142:143]
	v_add_f32_e32 v0, 1.0, v0
	v_cvt_pk_bf16_f32 v138, v142, v143
	v_rcp_f32_e32 v142, v0
	v_and_b32_e32 v0, 0xffff0000, v139
	v_max_f32_e64 v0, -v0, -v0
	v_min_f32_e32 v0, 0x41f00000, v0
	v_mul_f32_e32 v0, 0x3fb8aa3b, v0
	v_exp_f32_e32 v0, v0
	s_nop 0
	v_add_f32_e32 v0, 1.0, v0
	v_rcp_f32_e32 v143, v0
	v_lshlrev_b32_e32 v0, 16, v132
	v_max_f32_e64 v0, -v0, -v0
	v_min_f32_e32 v0, 0x41f00000, v0
	v_mul_f32_e32 v0, 0x3fb8aa3b, v0
	v_exp_f32_e32 v0, v0
	v_pk_mul_f32 v[142:143], v[98:99], v[142:143]
	v_add_f32_e32 v0, 1.0, v0
	v_cvt_pk_bf16_f32 v139, v142, v143
	global_store_dwordx4 v[140:141], v[136:139], off
	s_nop 1
	v_rcp_f32_e32 v136, v0
	v_and_b32_e32 v0, 0xffff0000, v132
	v_max_f32_e64 v0, -v0, -v0
	v_min_f32_e32 v0, 0x41f00000, v0
	v_mul_f32_e32 v0, 0x3fb8aa3b, v0
	v_exp_f32_e32 v0, v0
	s_nop 0
	v_add_f32_e32 v0, 1.0, v0
	v_rcp_f32_e32 v137, v0
	v_lshlrev_b32_e32 v0, 16, v133
	v_max_f32_e64 v0, -v0, -v0
	v_min_f32_e32 v0, 0x41f00000, v0
	v_mul_f32_e32 v0, 0x3fb8aa3b, v0
	v_exp_f32_e32 v0, v0
	v_pk_mul_f32 v[136:137], v[124:125], v[136:137]
	v_add_f32_e32 v0, 1.0, v0
	v_cvt_pk_bf16_f32 v132, v136, v137
	v_rcp_f32_e32 v136, v0
	v_and_b32_e32 v0, 0xffff0000, v133
	v_max_f32_e64 v0, -v0, -v0
	v_min_f32_e32 v0, 0x41f00000, v0
	v_mul_f32_e32 v0, 0x3fb8aa3b, v0
	v_exp_f32_e32 v0, v0
	s_nop 0
	v_add_f32_e32 v0, 1.0, v0
	v_rcp_f32_e32 v137, v0
	v_lshlrev_b32_e32 v0, 16, v134
	v_max_f32_e64 v0, -v0, -v0
	v_min_f32_e32 v0, 0x41f00000, v0
	v_mul_f32_e32 v0, 0x3fb8aa3b, v0
	v_exp_f32_e32 v0, v0
	v_pk_mul_f32 v[136:137], v[126:127], v[136:137]
	v_add_f32_e32 v0, 1.0, v0
	v_cvt_pk_bf16_f32 v133, v136, v137
	v_rcp_f32_e32 v136, v0
	v_and_b32_e32 v0, 0xffff0000, v134
	v_max_f32_e64 v0, -v0, -v0
	v_min_f32_e32 v0, 0x41f00000, v0
	v_mul_f32_e32 v0, 0x3fb8aa3b, v0
	v_exp_f32_e32 v0, v0
	s_nop 0
	v_add_f32_e32 v0, 1.0, v0
	v_rcp_f32_e32 v137, v0
	v_lshlrev_b32_e32 v0, 16, v135
	v_max_f32_e64 v0, -v0, -v0
	v_min_f32_e32 v0, 0x41f00000, v0
	v_mul_f32_e32 v0, 0x3fb8aa3b, v0
	v_exp_f32_e32 v0, v0
	v_pk_mul_f32 v[136:137], v[128:129], v[136:137]
	v_add_f32_e32 v0, 1.0, v0
	v_cvt_pk_bf16_f32 v134, v136, v137
	v_rcp_f32_e32 v136, v0
	v_and_b32_e32 v0, 0xffff0000, v135
	v_max_f32_e64 v0, -v0, -v0
	v_min_f32_e32 v0, 0x41f00000, v0
	v_mul_f32_e32 v0, 0x3fb8aa3b, v0
	v_exp_f32_e32 v0, v0
	s_nop 0
	v_add_f32_e32 v0, 1.0, v0
	v_rcp_f32_e32 v137, v0
	s_nop 0
	v_pk_mul_f32 v[136:137], v[130:131], v[136:137]
	s_nop 0
	v_cvt_pk_bf16_f32 v135, v136, v137
	global_store_dwordx4 v[140:141], v[132:135], off offset:256

; #define PG8_STAGE(bufoff, gbase, voff) do { _Pragma("unroll") for (int _i = 0; _i < 2; ++_i) \
;         __builtin_amdgcn_global_load_lds((const unsigned*)((const char*)(gbase) + (voff)[_i]), (PG8_LAS unsigned*)(lds + (bufoff) + ldsw + _i * 8192), 16, 0, 0); } while (0)
; #define PG8_LDA(dst, b, h) do { _Pragma("unroll") for (int m = 0; m < 4; ++m) _Pragma("unroll") for (int k = 0; k < 2; ++k) dst[m][k] = *(const PG8_LAS bf16x8*)(lds + PG8_SA(b, h) + aoff + m * 2048 + k * 1024); } while (0)
; #define PG8_LDB(dst, b, h) do { _Pragma("unroll") for (int n = 0; n < 2; ++n) _Pragma("unroll") for (int k = 0; k < 2; ++k) dst[n][k] = *(const PG8_LAS bf16x8*)(lds + PG8_SB(b, h) + boff + n * 2048 + k * 1024); } while (0)
; #define PG8_MMA(ai, bj, At, Bt) do { __builtin_amdgcn_s_setprio(1); _Pragma("unroll") for (int m = 0; m < 4; ++m) _Pragma("unroll") for (int n = 0; n < 2; ++n) _Pragma("unroll") for (int k = 0; k < 2; ++k) \
;         acc[ai][bj][m][n] = __builtin_amdgcn_mfma_f32_16x16x32_bf16(Bt[n][k], At[m][k], acc[ai][bj][m][n], 0, 0, 0); __builtin_amdgcn_s_setprio(0); } while (0)
; #define PG8_WAIT_L(n) asm volatile("s_waitcnt lgkmcnt(" #n ")" ::: "memory")
; #define PG8_BAR __builtin_amdgcn_s_barrier()
; #define PG8_SCHED __builtin_amdgcn_sched_barrier(0)
; template <class Epi, class Sched>
; __device__ __forceinline__ void gemm_phase(PG8_LAS unsigned char* lds, const Gemm g, const Sched& S, const Epi& E) {
;     ...
;         for (int t = 0; t < nt; t += 2) {
;             const bool last = (t == nt - 2);
;             const char* a1 = cA + (size_t)(t + 1) * kstep;
;             const char* a2 = last ? nA : cA + (size_t)(t + 2) * kstep; const char* b2 = last ? nB : cB + (size_t)(t + 2) * kstep;
;             const char* a3 = a2 + kstep; const char* b3 = b2 + kstep;
;             if (last && has_next) S.a_ready(nxt);
;             PG8_LDB(B0, 0, 0); PG8_SCHED; PG8_LDA(At, 0, 0); PG8_STAGE(PG8_SA(1, 1), a1 + hstep, voffA);
;             PG8_WAIT_L(8); PG8_BAR; PG8_WAIT_L(0); PG8_MMA(0, 0, At, B0); PG8_BAR; PG8_SCHED;
;             PG8_LDB(B1, 0, 1); PG8_STAGE(PG8_SB(0, 0), b2, voffB);
;             PG8_BAR; PG8_WAIT_L(0); PG8_MMA(0, 1, At, B1); PG8_BAR;
;             PG8_LDA(At, 0, 1); PG8_STAGE(PG8_SA(0, 0), a2, voffA);
;             PG8_BAR; PG8_WAIT_L(0); PG8_MMA(1, 0, At, B0); PG8_BAR; PG8_SCHED;
.LBB0_548:
	s_add_u32 s10, vcc_lo, 0xfffc0080
	s_addc_u32 s11, vcc_hi, -1
	s_add_i32 s84, 0, 0x10000
	v_add_u32_e32 v156, s84, v141
	ds_read_b128 v[144:147], v156
	ds_read_b128 v[148:151], v156 offset:1024
	ds_read_b128 v[152:155], v156 offset:2048
	ds_read_b128 v[156:159], v156 offset:3072
	s_cmp_eq_u32 s83, 12
	s_cselect_b32 s51, s21, s11
	s_cselect_b32 s50, s79, s10
	s_cselect_b32 s11, s19, s82
	s_cselect_b32 s10, s80, s81
	v_lshl_add_u64 v[202:203], vcc, 0, v[136:137]
	s_add_i32 m0, s70, 0xc000
	ds_read_b128 v[160:163], v143
	ds_read_b128 v[174:177], v143 offset:1024
	ds_read_b128 v[178:181], v143 offset:2048
	ds_read_b128 v[182:185], v143 offset:3072
	ds_read_b128 v[186:189], v143 offset:4096
	ds_read_b128 v[190:193], v143 offset:5120
	ds_read_b128 v[194:197], v143 offset:6144
	ds_read_b128 v[198:201], v143 offset:7168
	global_load_lds_dwordx4 v[202:203], off
	v_lshl_add_u64 v[202:203], vcc, 0, v[138:139]
	s_add_i32 m0, s70, 0xe000
	s_nop 0
	global_load_lds_dwordx4 v[202:203], off
	s_waitcnt lgkmcnt(8)
	s_barrier
	s_waitcnt lgkmcnt(0)
	s_setprio 1
	v_mfma_f32_16x16x32_bf16 v[6:9], v[144:147], v[160:163], v[6:9]
	v_mfma_f32_16x16x32_bf16 v[2:5], v[152:155], v[160:163], v[2:5]
	v_mfma_f32_16x16x32_bf16 v[22:25], v[144:147], v[178:181], v[22:25]
	v_mfma_f32_16x16x32_bf16 v[18:21], v[152:155], v[178:181], v[18:21]
	v_mfma_f32_16x16x32_bf16 v[38:41], v[144:147], v[186:189], v[38:41]
	v_mfma_f32_16x16x32_bf16 v[34:37], v[152:155], v[186:189], v[34:37]
	v_mfma_f32_16x16x32_bf16 v[54:57], v[144:147], v[194:197], v[54:57]
	v_mfma_f32_16x16x32_bf16 v[50:53], v[152:155], v[194:197], v[50:53]
	v_mfma_f32_16x16x32_bf16 v[6:9], v[148:151], v[174:177], v[6:9]
	v_mfma_f32_16x16x32_bf16 v[2:5], v[156:159], v[174:177], v[2:5]
	v_mfma_f32_16x16x32_bf16 v[22:25], v[148:151], v[182:185], v[22:25]
	v_mfma_f32_16x16x32_bf16 v[18:21], v[156:159], v[182:185], v[18:21]
	v_mfma_f32_16x16x32_bf16 v[38:41], v[148:151], v[190:193], v[38:41]
	v_mfma_f32_16x16x32_bf16 v[34:37], v[156:159], v[190:193], v[34:37]
	v_mfma_f32_16x16x32_bf16 v[54:57], v[148:151], v[198:201], v[54:57]
	v_mfma_f32_16x16x32_bf16 v[50:53], v[156:159], v[198:201], v[50:53]
	s_setprio 0
	s_barrier
	s_add_i32 s86, 0, 0x14000
	v_add_u32_e32 v202, s86, v141
	s_add_i32 s84, s84, s53
	ds_read_b128 v[222:225], v202
	ds_read_b128 v[226:229], v202 offset:1024
	ds_read_b128 v[230:233], v202 offset:2048
	ds_read_b128 v[234:237], v202 offset:3072
	v_lshl_add_u64 v[202:203], s[10:11], 0, v[0:1]
	s_mov_b32 m0, s84
	v_lshl_add_u64 v[238:239], s[10:11], 0, v[130:131]
	global_load_lds_dwordx4 v[202:203], off
	s_add_i32 m0, s84, 0x2000
	s_nop 0
	global_load_lds_dwordx4 v[238:239], off
	s_barrier
	s_waitcnt lgkmcnt(0)
	s_setprio 1
	v_mfma_f32_16x16x32_bf16 v[14:17], v[222:225], v[160:163], v[14:17]
	v_mfma_f32_16x16x32_bf16 v[10:13], v[230:233], v[160:163], v[10:13]
	v_mfma_f32_16x16x32_bf16 v[30:33], v[222:225], v[178:181], v[30:33]
	v_mfma_f32_16x16x32_bf16 v[26:29], v[230:233], v[178:181], v[26:29]
	v_mfma_f32_16x16x32_bf16 v[46:49], v[222:225], v[186:189], v[46:49]
	v_mfma_f32_16x16x32_bf16 v[42:45], v[230:233], v[186:189], v[42:45]
	v_mfma_f32_16x16x32_bf16 v[62:65], v[222:225], v[194:197], v[62:65]
	v_mfma_f32_16x16x32_bf16 v[58:61], v[230:233], v[194:197], v[58:61]
	v_mfma_f32_16x16x32_bf16 v[14:17], v[226:229], v[174:177], v[14:17]
	v_mfma_f32_16x16x32_bf16 v[10:13], v[234:237], v[174:177], v[10:13]
	v_mfma_f32_16x16x32_bf16 v[30:33], v[226:229], v[182:185], v[30:33]
	v_mfma_f32_16x16x32_bf16 v[26:29], v[234:237], v[182:185], v[26:29]
	v_mfma_f32_16x16x32_bf16 v[46:49], v[226:229], v[190:193], v[46:49]
	v_mfma_f32_16x16x32_bf16 v[42:45], v[234:237], v[190:193], v[42:45]
	v_mfma_f32_16x16x32_bf16 v[62:65], v[226:229], v[198:201], v[62:65]
	v_mfma_f32_16x16x32_bf16 v[58:61], v[234:237], v[198:201], v[58:61]
	s_setprio 0
	s_barrier
	s_mov_b32 m0, s70
	v_lshl_add_u64 v[240:241], s[50:51], 0, v[134:135]
	ds_read_b128 v[160:163], v143 offset:16384
	ds_read_b128 v[174:177], v143 offset:17408
	ds_read_b128 v[178:181], v143 offset:18432
	ds_read_b128 v[182:185], v143 offset:19456
	ds_read_b128 v[186:189], v143 offset:20480
	ds_read_b128 v[190:193], v143 offset:21504
	ds_read_b128 v[194:197], v143 offset:22528
	ds_read_b128 v[198:201], v143 offset:23552
	global_load_lds_dwordx4 v[240:241], off
	v_lshl_add_u64 v[242:243], s[50:51], 0, v[132:133]
	s_mov_b32 m0, s71
	s_nop 0
	global_load_lds_dwordx4 v[242:243], off
	s_barrier
	s_waitcnt lgkmcnt(0)
	s_setprio 1
	v_mfma_f32_16x16x32_bf16 v[66:69], v[144:147], v[160:163], v[66:69]
	v_mfma_f32_16x16x32_bf16 v[70:73], v[152:155], v[160:163], v[70:73]
	v_mfma_f32_16x16x32_bf16 v[82:85], v[144:147], v[178:181], v[82:85]
	v_mfma_f32_16x16x32_bf16 v[86:89], v[152:155], v[178:181], v[86:89]
	v_mfma_f32_16x16x32_bf16 v[98:101], v[144:147], v[186:189], v[98:101]
	v_mfma_f32_16x16x32_bf16 v[102:105], v[152:155], v[186:189], v[102:105]
	v_mfma_f32_16x16x32_bf16 v[114:117], v[144:147], v[194:197], v[114:117]
	v_mfma_f32_16x16x32_bf16 v[118:121], v[152:155], v[194:197], v[118:121]
	v_mfma_f32_16x16x32_bf16 v[66:69], v[148:151], v[174:177], v[66:69]
	v_mfma_f32_16x16x32_bf16 v[70:73], v[156:159], v[174:177], v[70:73]
	v_mfma_f32_16x16x32_bf16 v[82:85], v[148:151], v[182:185], v[82:85]
	v_mfma_f32_16x16x32_bf16 v[86:89], v[156:159], v[182:185], v[86:89]
	v_mfma_f32_16x16x32_bf16 v[98:101], v[148:151], v[190:193], v[98:101]
	v_mfma_f32_16x16x32_bf16 v[102:105], v[156:159], v[190:193], v[102:105]
	v_mfma_f32_16x16x32_bf16 v[114:117], v[148:151], v[198:201], v[114:117]
	v_mfma_f32_16x16x32_bf16 v[118:121], v[156:159], v[198:201], v[118:121]
	s_setprio 0
	s_barrier
; #define PG8_STAGE(bufoff, gbase, voff) do { _Pragma("unroll") for (int _i = 0; _i < 2; ++_i) \
;         __builtin_amdgcn_global_load_lds((const unsigned*)((const char*)(gbase) + (voff)[_i]), (PG8_LAS unsigned*)(lds + (bufoff) + ldsw + _i * 8192), 16, 0, 0); } while (0)
; #define PG8_LDA(dst, b, h) do { _Pragma("unroll") for (int m = 0; m < 4; ++m) _Pragma("unroll") for (int k = 0; k < 2; ++k) dst[m][k] = *(const PG8_LAS bf16x8*)(lds + PG8_SA(b, h) + aoff + m * 2048 + k * 1024); } while (0)
; #define PG8_LDB(dst, b, h) do { _Pragma("unroll") for (int n = 0; n < 2; ++n) _Pragma("unroll") for (int k = 0; k < 2; ++k) dst[n][k] = *(const PG8_LAS bf16x8*)(lds + PG8_SB(b, h) + boff + n * 2048 + k * 1024); } while (0)
; #define PG8_MMA(ai, bj, At, Bt) do { __builtin_amdgcn_s_setprio(1); _Pragma("unroll") for (int m = 0; m < 4; ++m) _Pragma("unroll") for (int n = 0; n < 2; ++n) _Pragma("unroll") for (int k = 0; k < 2; ++k) \
;         acc[ai][bj][m][n] = __builtin_amdgcn_mfma_f32_16x16x32_bf16(Bt[n][k], At[m][k], acc[ai][bj][m][n], 0, 0, 0); __builtin_amdgcn_s_setprio(0); } while (0)
; #define PG8_WAIT_V(n) asm volatile("s_waitcnt vmcnt(" #n ")" ::: "memory")
; #define PG8_WAIT_L(n) asm volatile("s_waitcnt lgkmcnt(" #n ")" ::: "memory")
; #define PG8_BAR __builtin_amdgcn_s_barrier()
; #define PG8_SCHED __builtin_amdgcn_sched_barrier(0)
; template <class Epi, class Sched>
; __device__ __forceinline__ void gemm_phase(PG8_LAS unsigned char* lds, const Gemm g, const Sched& S, const Epi& E) {
;     ...
;             PG8_STAGE(PG8_SB(0, 1), b2 + hstep, voffB);
;             PG8_WAIT_V(6); PG8_BAR; PG8_MMA(1, 1, At, B1); PG8_BAR;
;             PG8_LDB(B0, 1, 0); PG8_SCHED; PG8_LDA(At, 1, 0); PG8_STAGE(PG8_SA(0, 1), a2 + hstep, voffA);
;             PG8_WAIT_L(8); PG8_BAR; PG8_WAIT_L(0); PG8_MMA(0, 0, At, B0); PG8_BAR; PG8_SCHED;
;             PG8_LDB(B1, 1, 1); PG8_STAGE(PG8_SB(1, 0), b3, voffB);
;             PG8_BAR; PG8_WAIT_L(0); PG8_MMA(0, 1, At, B1); PG8_BAR;
	s_add_u32 s84, s10, 0x40000
	s_addc_u32 s85, s11, 0
	s_add_i32 s86, s86, s53
	v_lshl_add_u64 v[144:145], s[84:85], 0, v[0:1]
	s_mov_b32 m0, s86
	s_nop 0
	global_load_lds_dwordx4 v[144:145], off
	v_lshl_add_u64 v[144:145], s[84:85], 0, v[130:131]
	s_add_i32 m0, s86, 0x2000
	s_nop 0
	global_load_lds_dwordx4 v[144:145], off
	s_waitcnt vmcnt(6)
	s_barrier
	s_setprio 1
	v_mfma_f32_16x16x32_bf16 v[78:81], v[222:225], v[160:163], v[78:81]
	v_mfma_f32_16x16x32_bf16 v[74:77], v[230:233], v[160:163], v[74:77]
	v_mfma_f32_16x16x32_bf16 v[94:97], v[222:225], v[178:181], v[94:97]
	v_mfma_f32_16x16x32_bf16 v[90:93], v[230:233], v[178:181], v[90:93]
	v_mfma_f32_16x16x32_bf16 v[110:113], v[222:225], v[186:189], v[110:113]
	v_mfma_f32_16x16x32_bf16 v[106:109], v[230:233], v[186:189], v[106:109]
	v_mfma_f32_16x16x32_bf16 v[126:129], v[222:225], v[194:197], v[126:129]
	v_mfma_f32_16x16x32_bf16 v[122:125], v[230:233], v[194:197], v[122:125]
	v_mfma_f32_16x16x32_bf16 v[78:81], v[226:229], v[174:177], v[78:81]
	v_mfma_f32_16x16x32_bf16 v[74:77], v[234:237], v[174:177], v[74:77]
	v_mfma_f32_16x16x32_bf16 v[94:97], v[226:229], v[182:185], v[94:97]
	v_mfma_f32_16x16x32_bf16 v[90:93], v[234:237], v[182:185], v[90:93]
	v_mfma_f32_16x16x32_bf16 v[110:113], v[226:229], v[190:193], v[110:113]
	v_mfma_f32_16x16x32_bf16 v[106:109], v[234:237], v[190:193], v[106:109]
	v_mfma_f32_16x16x32_bf16 v[126:129], v[226:229], v[198:201], v[126:129]
	v_mfma_f32_16x16x32_bf16 v[122:125], v[234:237], v[198:201], v[122:125]
	s_setprio 0
	s_barrier
	s_add_i32 s84, 0, 0x18000
	v_add_u32_e32 v156, s84, v141
	ds_read_b128 v[144:147], v156
	ds_read_b128 v[148:151], v156 offset:1024
	ds_read_b128 v[152:155], v156 offset:2048
	ds_read_b128 v[156:159], v156 offset:3072
	s_add_u32 s50, s50, 0x40000
	s_addc_u32 s51, s51, 0
	s_mov_b32 m0, s72
	v_lshl_add_u64 v[222:223], s[50:51], 0, v[134:135]
	ds_read_b128 v[160:163], v143 offset:32768
	ds_read_b128 v[174:177], v143 offset:33792
	ds_read_b128 v[178:181], v143 offset:34816
	ds_read_b128 v[182:185], v143 offset:35840
	ds_read_b128 v[186:189], v143 offset:36864
	ds_read_b128 v[190:193], v143 offset:37888
	ds_read_b128 v[194:197], v143 offset:38912
	ds_read_b128 v[198:201], v143 offset:39936
	global_load_lds_dwordx4 v[222:223], off
	v_lshl_add_u64 v[222:223], s[50:51], 0, v[132:133]
	s_mov_b32 m0, s73
	s_nop 0
	global_load_lds_dwordx4 v[222:223], off
	s_waitcnt lgkmcnt(8)
	s_barrier
	s_waitcnt lgkmcnt(0)
	s_setprio 1
	v_mfma_f32_16x16x32_bf16 v[6:9], v[144:147], v[160:163], v[6:9]
	v_mfma_f32_16x16x32_bf16 v[2:5], v[152:155], v[160:163], v[2:5]
	v_mfma_f32_16x16x32_bf16 v[22:25], v[144:147], v[178:181], v[22:25]
	v_mfma_f32_16x16x32_bf16 v[18:21], v[152:155], v[178:181], v[18:21]
	v_mfma_f32_16x16x32_bf16 v[38:41], v[144:147], v[186:189], v[38:41]
	v_mfma_f32_16x16x32_bf16 v[34:37], v[152:155], v[186:189], v[34:37]
	v_mfma_f32_16x16x32_bf16 v[54:57], v[144:147], v[194:197], v[54:57]
	v_mfma_f32_16x16x32_bf16 v[50:53], v[152:155], v[194:197], v[50:53]
	v_mfma_f32_16x16x32_bf16 v[6:9], v[148:151], v[174:177], v[6:9]
	v_mfma_f32_16x16x32_bf16 v[2:5], v[156:159], v[174:177], v[2:5]
	v_mfma_f32_16x16x32_bf16 v[22:25], v[148:151], v[182:185], v[22:25]
	v_mfma_f32_16x16x32_bf16 v[18:21], v[156:159], v[182:185], v[18:21]
	v_mfma_f32_16x16x32_bf16 v[38:41], v[148:151], v[190:193], v[38:41]
	v_mfma_f32_16x16x32_bf16 v[34:37], v[156:159], v[190:193], v[34:37]
	v_mfma_f32_16x16x32_bf16 v[54:57], v[148:151], v[198:201], v[54:57]
	v_mfma_f32_16x16x32_bf16 v[50:53], v[156:159], v[198:201], v[50:53]
	s_setprio 0
	s_barrier
	s_add_i32 s50, 0, 0x1c000
	s_add_i32 s51, s84, s53
	v_add_u32_e32 v221, s50, v141
	v_lshl_add_u64 v[202:203], v[202:203], 0, s[8:9]
	s_mov_b32 m0, s51
	ds_read_b128 v[222:225], v221
	ds_read_b128 v[226:229], v221 offset:1024
	ds_read_b128 v[230:233], v221 offset:2048
	ds_read_b128 v[234:237], v221 offset:3072
	global_load_lds_dwordx4 v[202:203], off
	v_lshl_add_u64 v[202:203], v[238:239], 0, s[8:9]
	s_add_i32 m0, s51, 0x2000
	s_nop 0
	global_load_lds_dwordx4 v[202:203], off
	s_barrier
	s_waitcnt lgkmcnt(0)
	s_setprio 1
	v_mfma_f32_16x16x32_bf16 v[14:17], v[222:225], v[160:163], v[14:17]
	v_mfma_f32_16x16x32_bf16 v[10:13], v[230:233], v[160:163], v[10:13]
	v_mfma_f32_16x16x32_bf16 v[30:33], v[222:225], v[178:181], v[30:33]
	v_mfma_f32_16x16x32_bf16 v[26:29], v[230:233], v[178:181], v[26:29]
	v_mfma_f32_16x16x32_bf16 v[46:49], v[222:225], v[186:189], v[46:49]
	v_mfma_f32_16x16x32_bf16 v[42:45], v[230:233], v[186:189], v[42:45]
	v_mfma_f32_16x16x32_bf16 v[62:65], v[222:225], v[194:197], v[62:65]
	v_mfma_f32_16x16x32_bf16 v[58:61], v[230:233], v[194:197], v[58:61]
	v_mfma_f32_16x16x32_bf16 v[14:17], v[226:229], v[174:177], v[14:17]
	v_mfma_f32_16x16x32_bf16 v[10:13], v[234:237], v[174:177], v[10:13]
	v_mfma_f32_16x16x32_bf16 v[30:33], v[226:229], v[182:185], v[30:33]
	v_mfma_f32_16x16x32_bf16 v[26:29], v[234:237], v[182:185], v[26:29]
	v_mfma_f32_16x16x32_bf16 v[46:49], v[226:229], v[190:193], v[46:49]
	v_mfma_f32_16x16x32_bf16 v[42:45], v[234:237], v[190:193], v[42:45]
	v_mfma_f32_16x16x32_bf16 v[62:65], v[226:229], v[198:201], v[62:65]
	v_mfma_f32_16x16x32_bf16 v[58:61], v[234:237], v[198:201], v[58:61]
	s_setprio 0
	s_barrier
	s_mov_b32 m0, s74
	v_lshl_add_u64 v[202:203], v[240:241], 0, s[8:9]
	ds_read_b128 v[160:163], v143 offset:49152
	ds_read_b128 v[174:177], v143 offset:50176
	ds_read_b128 v[178:181], v143 offset:51200
	ds_read_b128 v[182:185], v143 offset:52224
	ds_read_b128 v[186:189], v143 offset:53248
	ds_read_b128 v[190:193], v143 offset:54272
	ds_read_b128 v[194:197], v143 offset:55296
	ds_read_b128 v[198:201], v143 offset:56320
	global_load_lds_dwordx4 v[202:203], off
	v_lshl_add_u64 v[202:203], v[242:243], 0, s[8:9]
	s_mov_b32 m0, s75
	s_nop 0
	global_load_lds_dwordx4 v[202:203], off
	s_barrier
; #define PG8_STAGE(bufoff, gbase, voff) do { _Pragma("unroll") for (int _i = 0; _i < 2; ++_i) \
;         __builtin_amdgcn_global_load_lds((const unsigned*)((const char*)(gbase) + (voff)[_i]), (PG8_LAS unsigned*)(lds + (bufoff) + ldsw + _i * 8192), 16, 0, 0); } while (0)
; #define PG8_LDA(dst, b, h) do { _Pragma("unroll") for (int m = 0; m < 4; ++m) _Pragma("unroll") for (int k = 0; k < 2; ++k) dst[m][k] = *(const PG8_LAS bf16x8*)(lds + PG8_SA(b, h) + aoff + m * 2048 + k * 1024); } while (0)
; #define PG8_MMA(ai, bj, At, Bt) do { __builtin_amdgcn_s_setprio(1); _Pragma("unroll") for (int m = 0; m < 4; ++m) _Pragma("unroll") for (int n = 0; n < 2; ++n) _Pragma("unroll") for (int k = 0; k < 2; ++k) \
;         acc[ai][bj][m][n] = __builtin_amdgcn_mfma_f32_16x16x32_bf16(Bt[n][k], At[m][k], acc[ai][bj][m][n], 0, 0, 0); __builtin_amdgcn_s_setprio(0); } while (0)
; #define PG8_WAIT_V(n) asm volatile("s_waitcnt vmcnt(" #n ")" ::: "memory")
; #define PG8_WAIT_L(n) asm volatile("s_waitcnt lgkmcnt(" #n ")" ::: "memory")
; #define PG8_BAR __builtin_amdgcn_s_barrier()
; #define PG8_SCHED __builtin_amdgcn_sched_barrier(0)
; template <class Epi, class Sched>
; __device__ __forceinline__ void gemm_phase(PG8_LAS unsigned char* lds, const Gemm g, const Sched& S, const Epi& E) {
;     ...
;             PG8_LDA(At, 1, 1); PG8_STAGE(PG8_SA(1, 0), a3, voffA);
;             PG8_BAR; PG8_WAIT_L(0); PG8_MMA(1, 0, At, B0); PG8_BAR; PG8_SCHED;
;             PG8_STAGE(PG8_SB(1, 1), b3 + hstep, voffB);
;             PG8_WAIT_V(6); PG8_BAR; PG8_MMA(1, 1, At, B1); PG8_BAR;
;     __device__ __forceinline__ void operator()(const f32x4 (&acc)[2][2][4][2], const Unit& u, int wr, int wc, int fr, int fq) const {
;         const int row0 = u.pm * 256 + wr * 64 + fr, col0 = u.pn * 256 + wc * 32 + 8 * fq;
; #pragma unroll
;         for (int ai = 0; ai < 2; ++ai)
; #pragma unroll
;             for (int m = 0; m < 4; ++m) { const size_t ro = (size_t)(row0 + ai * 128 + m * 16) * 1024 + col0;
; #pragma unroll
;                 for (int bj = 0; bj < 2; ++bj) { *(f32x4*)(XO + ro + bj * 128) = acc[ai][bj][m][0]; *(f32x4*)(XO + ro + bj * 128 + 4) = acc[ai][bj][m][1]; } }
;     }
	s_waitcnt lgkmcnt(0)
	s_setprio 1
	v_mfma_f32_16x16x32_bf16 v[66:69], v[144:147], v[160:163], v[66:69]
	v_mfma_f32_16x16x32_bf16 v[70:73], v[152:155], v[160:163], v[70:73]
	v_mfma_f32_16x16x32_bf16 v[82:85], v[144:147], v[178:181], v[82:85]
	v_mfma_f32_16x16x32_bf16 v[86:89], v[152:155], v[178:181], v[86:89]
	v_mfma_f32_16x16x32_bf16 v[98:101], v[144:147], v[186:189], v[98:101]
	v_mfma_f32_16x16x32_bf16 v[102:105], v[152:155], v[186:189], v[102:105]
	v_mfma_f32_16x16x32_bf16 v[114:117], v[144:147], v[194:197], v[114:117]
	v_mfma_f32_16x16x32_bf16 v[118:121], v[152:155], v[194:197], v[118:121]
	v_mfma_f32_16x16x32_bf16 v[66:69], v[148:151], v[174:177], v[66:69]
	v_mfma_f32_16x16x32_bf16 v[70:73], v[156:159], v[174:177], v[70:73]
	v_mfma_f32_16x16x32_bf16 v[82:85], v[148:151], v[182:185], v[82:85]
	v_mfma_f32_16x16x32_bf16 v[86:89], v[156:159], v[182:185], v[86:89]
	v_mfma_f32_16x16x32_bf16 v[98:101], v[148:151], v[190:193], v[98:101]
	v_mfma_f32_16x16x32_bf16 v[102:105], v[156:159], v[190:193], v[102:105]
	v_mfma_f32_16x16x32_bf16 v[114:117], v[148:151], v[198:201], v[114:117]
	v_mfma_f32_16x16x32_bf16 v[118:121], v[156:159], v[198:201], v[118:121]
	s_setprio 0
	s_barrier
	s_add_u32 s10, s10, 0x40080
	s_addc_u32 s11, s11, 0
	s_add_i32 s50, s50, s53
	v_lshl_add_u64 v[144:145], s[10:11], 0, v[0:1]
	s_mov_b32 m0, s50
	s_nop 0
	global_load_lds_dwordx4 v[144:145], off
	v_lshl_add_u64 v[144:145], s[10:11], 0, v[130:131]
	s_add_i32 m0, s50, 0x2000
	s_nop 0
	global_load_lds_dwordx4 v[144:145], off
	s_waitcnt vmcnt(6)
	s_barrier
	s_setprio 1
	v_mfma_f32_16x16x32_bf16 v[78:81], v[222:225], v[160:163], v[78:81]
	v_mfma_f32_16x16x32_bf16 v[74:77], v[230:233], v[160:163], v[74:77]
	v_mfma_f32_16x16x32_bf16 v[94:97], v[222:225], v[178:181], v[94:97]
	v_mfma_f32_16x16x32_bf16 v[90:93], v[230:233], v[178:181], v[90:93]
	v_mfma_f32_16x16x32_bf16 v[110:113], v[222:225], v[186:189], v[110:113]
	v_mfma_f32_16x16x32_bf16 v[106:109], v[230:233], v[186:189], v[106:109]
	v_mfma_f32_16x16x32_bf16 v[126:129], v[222:225], v[194:197], v[126:129]
	v_mfma_f32_16x16x32_bf16 v[122:125], v[230:233], v[194:197], v[122:125]
	v_mfma_f32_16x16x32_bf16 v[78:81], v[226:229], v[174:177], v[78:81]
	v_mfma_f32_16x16x32_bf16 v[74:77], v[234:237], v[174:177], v[74:77]
	v_mfma_f32_16x16x32_bf16 v[94:97], v[226:229], v[182:185], v[94:97]
	v_mfma_f32_16x16x32_bf16 v[90:93], v[234:237], v[182:185], v[90:93]
	v_mfma_f32_16x16x32_bf16 v[110:113], v[226:229], v[190:193], v[110:113]
	v_mfma_f32_16x16x32_bf16 v[106:109], v[234:237], v[190:193], v[106:109]
	v_mfma_f32_16x16x32_bf16 v[126:129], v[226:229], v[198:201], v[126:129]
	v_mfma_f32_16x16x32_bf16 v[122:125], v[234:237], v[198:201], v[122:125]
	s_setprio 0
	s_add_i32 s83, s83, 2
	s_add_u32 vcc_lo, vcc_lo, 0x100
	s_addc_u32 vcc_hi, vcc_hi, 0
	s_add_u32 s81, s81, 0x100
	s_addc_u32 s82, s82, 0
	s_cmp_gt_u32 s83, 13
	s_barrier
	s_cbranch_scc0 .LBB0_548
	v_lshl_add_u32 v144, s78, 8, v140
	v_lshl_or_b32 v146, s77, 8, v142
	v_ashrrev_i32_e32 v145, 31, v144
	v_ashrrev_i32_e32 v147, 31, v146
	v_lshlrev_b64 v[148:149], 12, v[144:145]
	v_lshl_add_u64 v[148:149], s[62:63], 0, v[148:149]
	v_lshlrev_b64 v[146:147], 2, v[146:147]
	v_lshl_add_u64 v[148:149], v[148:149], 0, v[146:147]
	global_store_dwordx4 v[148:149], v[6:9], off
	global_store_dwordx4 v[148:149], v[2:5], off offset:16
	global_store_dwordx4 v[148:149], v[14:17], off offset:512
	global_store_dwordx4 v[148:149], v[10:13], off offset:528
	v_or_b32_e32 v2, 16, v144
	v_ashrrev_i32_e32 v3, 31, v2
	v_lshlrev_b64 v[2:3], 12, v[2:3]
	v_lshl_add_u64 v[2:3], s[62:63], 0, v[2:3]
	v_lshl_add_u64 v[2:3], v[2:3], 0, v[146:147]
	global_store_dwordx4 v[2:3], v[22:25], off
	global_store_dwordx4 v[2:3], v[18:21], off offset:16
	global_store_dwordx4 v[2:3], v[30:33], off offset:512
	global_store_dwordx4 v[2:3], v[26:29], off offset:528
	v_or_b32_e32 v2, 32, v144
	v_ashrrev_i32_e32 v3, 31, v2
	v_lshlrev_b64 v[2:3], 12, v[2:3]
	v_lshl_add_u64 v[2:3], s[62:63], 0, v[2:3]
	v_lshl_add_u64 v[2:3], v[2:3], 0, v[146:147]
	global_store_dwordx4 v[2:3], v[38:41], off
	global_store_dwordx4 v[2:3], v[34:37], off offset:16
	global_store_dwordx4 v[2:3], v[46:49], off offset:512
	global_store_dwordx4 v[2:3], v[42:45], off offset:528
	v_or_b32_e32 v2, 48, v144
	v_ashrrev_i32_e32 v3, 31, v2
	v_lshlrev_b64 v[2:3], 12, v[2:3]
	v_lshl_add_u64 v[2:3], s[62:63], 0, v[2:3]
	v_lshl_add_u64 v[2:3], v[2:3], 0, v[146:147]
	v_add_co_u32_e32 v4, vcc, s54, v148
	global_store_dwordx4 v[2:3], v[54:57], off
	global_store_dwordx4 v[2:3], v[50:53], off offset:16
	global_store_dwordx4 v[2:3], v[62:65], off offset:512
	global_store_dwordx4 v[2:3], v[58:61], off offset:528
	v_lshl_add_u64 v[2:3], v[148:149], 0, s[42:43]
	v_addc_co_u32_e32 v5, vcc, 0, v149, vcc
	s_mov_b64 s[10:11], 0x90000
	global_store_dwordx4 v[4:5], v[66:69], off
	global_store_dwordx4 v[2:3], v[70:73], off offset:16
	global_store_dwordx4 v[2:3], v[78:81], off offset:512
	global_store_dwordx4 v[2:3], v[74:77], off offset:528
	v_lshl_add_u64 v[2:3], v[148:149], 0, s[10:11]
	s_mov_b32 s10, 0x90000
	v_add_co_u32_e32 v4, vcc, s10, v148
	s_mov_b64 s[10:11], 0xa0000
	s_nop 0
	v_addc_co_u32_e32 v5, vcc, 0, v149, vcc
	global_store_dwordx4 v[4:5], v[82:85], off
	global_store_dwordx4 v[2:3], v[86:89], off offset:16
	global_store_dwordx4 v[2:3], v[94:97], off offset:512
	global_store_dwordx4 v[2:3], v[90:93], off offset:528
	v_lshl_add_u64 v[2:3], v[148:149], 0, s[10:11]
	s_mov_b32 s10, 0xa0000
	v_add_co_u32_e32 v4, vcc, s10, v148
	s_mov_b64 s[10:11], 0xb0000
	s_nop 0
	v_addc_co_u32_e32 v5, vcc, 0, v149, vcc
	global_store_dwordx4 v[4:5], v[98:101], off
	global_store_dwordx4 v[2:3], v[102:105], off offset:16
	global_store_dwordx4 v[2:3], v[110:113], off offset:512
	global_store_dwordx4 v[2:3], v[106:109], off offset:528
	v_add_co_u32_e32 v4, vcc, 0xb0000, v148
	v_lshl_add_u64 v[2:3], v[148:149], 0, s[10:11]
	s_nop 0
	v_addc_co_u32_e32 v5, vcc, 0, v149, vcc
	s_andn2_b64 vcc, exec, s[36:37]
	s_mov_b64 s[10:11], -1
	global_store_dwordx4 v[4:5], v[114:117], off
	global_store_dwordx4 v[2:3], v[118:121], off offset:16
	global_store_dwordx4 v[2:3], v[126:129], off offset:512
	global_store_dwordx4 v[2:3], v[122:125], off offset:528
	s_cbranch_vccnz .LBB0_540
;     __device__ __forceinline__ void init(f32x4 (&acc)[2][2][4][2], const Unit& u, int wr, int wc, int fr, int fq) const {
;         const int row0 = u.pm * 256 + wr * 64 + fr, col0 = u.pn * 256 + wc * 32 + 8 * fq;
; #pragma unroll
;         for (int ai = 0; ai < 2; ++ai)
; #pragma unroll
;             for (int m = 0; m < 4; ++m) { const size_t ro = (size_t)(row0 + ai * 128 + m * 16) * 1024 + col0;
; #pragma unroll
;                 for (int bj = 0; bj < 2; ++bj) { acc[ai][bj][m][0] = *(const f32x4*)(XI + ro + bj * 128); acc[ai][bj][m][1] = *(const f32x4*)(XI + ro + bj * 128 + 4); } }
;     }
	v_lshl_add_u32 v50, s20, 8, v140
	v_lshl_or_b32 v2, s18, 8, v142
	v_ashrrev_i32_e32 v51, 31, v50
	v_ashrrev_i32_e32 v3, 31, v2
	v_lshlrev_b64 v[4:5], 12, v[50:51]
	v_lshl_add_u64 v[4:5], s[6:7], 0, v[4:5]
	v_lshlrev_b64 v[52:53], 2, v[2:3]
	v_lshl_add_u64 v[114:115], v[4:5], 0, v[52:53]
	v_add_co_u32_e32 v66, vcc, s54, v114
	s_mov_b64 s[10:11], 0x90000
	s_nop 0
	v_addc_co_u32_e32 v67, vcc, 0, v115, vcc
	v_lshl_add_u64 v[94:95], v[114:115], 0, s[10:11]
	s_mov_b32 s10, 0x90000
	v_add_co_u32_e32 v82, vcc, s10, v114
	s_mov_b64 s[10:11], 0xa0000
	v_or_b32_e32 v18, 16, v50
	v_or_b32_e32 v34, 32, v50
	v_or_b32_e32 v50, 48, v50
	v_addc_co_u32_e32 v83, vcc, 0, v115, vcc
	v_lshl_add_u64 v[110:111], v[114:115], 0, s[10:11]
	s_mov_b32 s10, 0xa0000
	v_ashrrev_i32_e32 v19, 31, v18
	v_ashrrev_i32_e32 v35, 31, v34
	v_ashrrev_i32_e32 v51, 31, v50
	v_add_co_u32_e32 v98, vcc, s10, v114
	s_mov_b64 s[10:11], 0xb0000
	v_lshlrev_b64 v[18:19], 12, v[18:19]
	v_lshlrev_b64 v[34:35], 12, v[34:35]
	v_lshlrev_b64 v[50:51], 12, v[50:51]
	v_addc_co_u32_e32 v99, vcc, 0, v115, vcc
	v_lshl_add_u64 v[126:127], v[114:115], 0, s[10:11]
	s_mov_b32 s10, 0xb0000
	global_load_dwordx4 v[2:5], v[114:115], off offset:16
	global_load_dwordx4 v[6:9], v[114:115], off
	global_load_dwordx4 v[10:13], v[114:115], off offset:528
	global_load_dwordx4 v[14:17], v[114:115], off offset:512
	v_lshl_add_u64 v[18:19], s[6:7], 0, v[18:19]
	v_lshl_add_u64 v[34:35], s[6:7], 0, v[34:35]
	v_lshl_add_u64 v[50:51], s[6:7], 0, v[50:51]
	v_lshl_add_u64 v[78:79], v[114:115], 0, s[42:43]
	v_add_co_u32_e32 v114, vcc, s10, v114
	v_lshl_add_u64 v[30:31], v[18:19], 0, v[52:53]
	v_lshl_add_u64 v[46:47], v[34:35], 0, v[52:53]
	v_lshl_add_u64 v[62:63], v[50:51], 0, v[52:53]
	v_addc_co_u32_e32 v115, vcc, 0, v115, vcc
	global_load_dwordx4 v[18:21], v[30:31], off offset:16
	global_load_dwordx4 v[22:25], v[30:31], off
	global_load_dwordx4 v[26:29], v[30:31], off offset:528
	s_nop 0
	global_load_dwordx4 v[30:33], v[30:31], off offset:512
	s_nop 0
	global_load_dwordx4 v[34:37], v[46:47], off offset:16
	global_load_dwordx4 v[38:41], v[46:47], off
	global_load_dwordx4 v[42:45], v[46:47], off offset:528
	s_nop 0
	global_load_dwordx4 v[46:49], v[46:47], off offset:512
	s_nop 0
	global_load_dwordx4 v[50:53], v[62:63], off offset:16
	global_load_dwordx4 v[54:57], v[62:63], off
	global_load_dwordx4 v[58:61], v[62:63], off offset:528
	s_nop 0
	global_load_dwordx4 v[62:65], v[62:63], off offset:512
	s_nop 0
	global_load_dwordx4 v[66:69], v[66:67], off
	s_nop 0
	global_load_dwordx4 v[74:77], v[78:79], off offset:528
	global_load_dwordx4 v[70:73], v[78:79], off offset:16
	s_nop 0
	global_load_dwordx4 v[78:81], v[78:79], off offset:512
	s_nop 0
	global_load_dwordx4 v[82:85], v[82:83], off
	s_nop 0
	global_load_dwordx4 v[90:93], v[94:95], off offset:528
	global_load_dwordx4 v[86:89], v[94:95], off offset:16
	s_nop 0
	global_load_dwordx4 v[94:97], v[94:95], off offset:512
	s_nop 0
	global_load_dwordx4 v[98:101], v[98:99], off
	s_nop 0
	global_load_dwordx4 v[106:109], v[110:111], off offset:528
	global_load_dwordx4 v[102:105], v[110:111], off offset:16
	s_nop 0
	global_load_dwordx4 v[110:113], v[110:111], off offset:512
	s_nop 0
	global_load_dwordx4 v[114:117], v[114:115], off
	s_nop 0
	global_load_dwordx4 v[122:125], v[126:127], off offset:528
	global_load_dwordx4 v[118:121], v[126:127], off offset:16
	s_nop 0
	global_load_dwordx4 v[126:129], v[126:127], off offset:512
	s_mov_b64 s[10:11], 0
	s_branch .LBB0_540
